# MFMA accumulate chains with the K-half order alternating between consecutive chains so the chain boundary shares one input operand
# speedup vs baseline: 1.0217x; 1.0085x over previous
; #define PG8_STAGE(bufoff, gbase, voff) do { _Pragma("unroll") for (int _i = 0; _i < 2; ++_i) \
;         __builtin_amdgcn_global_load_lds((const unsigned*)((const char*)(gbase) + (voff)[_i]), (LAS unsigned*)(lds + (bufoff) + ldsw + _i * 8192), 16, 0, 0); } while (0)
; #define PG8_LDA(dst, b, h) do { _Pragma("unroll") for (int m = 0; m < 4; ++m) _Pragma("unroll") for (int k = 0; k < 2; ++k) dst[m][k] = *(const LAS bf16x8*)(lds + PG8_SA(b, h) + aoff + m * 2048 + k * 1024); } while (0)
; #define PG8_LDB(dst, b, h) do { _Pragma("unroll") for (int n = 0; n < 2; ++n) _Pragma("unroll") for (int k = 0; k < 2; ++k) dst[n][k] = *(const LAS bf16x8*)(lds + PG8_SB(b, h) + boff + n * 2048 + k * 1024); } while (0)
; #define PG8_MMA(ai, bj, At, Bt) do { __builtin_amdgcn_s_setprio(1); _Pragma("unroll") for (int m = 0; m < 4; ++m) _Pragma("unroll") for (int n = 0; n < 2; ++n) _Pragma("unroll") for (int k = 0; k < 2; ++k) \
;         acc[ai][bj][m][n] = __builtin_amdgcn_mfma_f32_16x16x32_bf16(Bt[n][k], At[m][k], acc[ai][bj][m][n], 0, 0, 0); __builtin_amdgcn_s_setprio(0); } while (0)
; #define PG8_WAIT_V(n) asm volatile("s_waitcnt vmcnt(" #n ")" ::: "memory")
; #define PG8_WAIT_L(n) asm volatile("s_waitcnt lgkmcnt(" #n ")" ::: "memory")
; #define PG8_BAR __builtin_amdgcn_s_barrier()
; #define PG8_SCHED __builtin_amdgcn_sched_barrier(0)
; template <class Epi>
; __device__ __forceinline__ void gemm_phase(LAS unsigned char* lds, const Gemm g, const StaticOrder& S, const Epi& E) {
;     ...
;             const char* a2 = last ? nA : cA + (size_t)(t + 2) * kstep; const char* b2 = last ? nB : cB + (size_t)(t + 2) * kstep;
;             const char* a3 = a2 + kstep; const char* b3 = b2 + kstep;
;             PG8_LDB(B0, 0, 0); PG8_LDB(B1, 0, 1); PG8_SCHED; PG8_LDA(At, 0, 0); PG8_STAGE(PG8_SA(1, 1), a1 + hstepA, voffA);
;             PG8_WAIT_V(8); PG8_WAIT_L(0); PG8_BAR; PG8_MMA(0, 0, At, B0); PG8_MMA(0, 1, At, B1); PG8_BAR; PG8_SCHED;
;             PG8_LDA(At, 0, 1); PG8_STAGE(PG8_SB(0, 0), b2, voffB); PG8_STAGE(PG8_SB(0, 1), b2 + hstepB, voffB); PG8_STAGE(PG8_SA(0, 0), a2, voffA);
;             PG8_WAIT_V(8); PG8_WAIT_L(0); PG8_BAR; PG8_MMA(1, 0, At, B0); PG8_MMA(1, 1, At, B1); PG8_BAR; PG8_SCHED;
.LBB0_245:
	ds_read_b128 v[152:155], v148
	ds_read_b128 v[156:159], v148 offset:1024
	ds_read_b128 v[160:163], v148 offset:2048
	ds_read_b128 v[164:167], v148 offset:3072
	ds_read_b128 v[168:171], v149
	ds_read_b128 v[172:175], v149 offset:1024
	ds_read_b128 v[176:179], v149 offset:2048
	ds_read_b128 v[180:183], v149 offset:3072
	s_add_i32 s64, s26, 2
	s_add_u32 s27, s24, 0xfff80080
	s_addc_u32 s30, s25, -1
	s_cmp_eq_u32 s54, s26
	s_cselect_b32 s26, s61, s62
	s_cselect_b32 s31, s15, s30
	s_cselect_b32 s30, s17, s27
	s_cselect_b32 s27, s60, s63
	v_lshl_add_u64 v[220:221], s[24:25], 0, v[138:139]
	s_add_i32 m0, s44, 0xc000
	ds_read_b128 v[184:187], v150
	ds_read_b128 v[188:191], v150 offset:1024
	ds_read_b128 v[192:195], v150 offset:2048
	ds_read_b128 v[196:199], v150 offset:3072
	ds_read_b128 v[200:203], v150 offset:4096
	ds_read_b128 v[208:211], v150 offset:5120
	ds_read_b128 v[212:215], v150 offset:6144
	ds_read_b128 v[216:219], v150 offset:7168
	global_load_lds_dwordx4 v[220:221], off
	v_lshl_add_u64 v[220:221], s[24:25], 0, v[140:141]
	s_add_i32 m0, s44, 0xe000
	s_nop 0
	global_load_lds_dwordx4 v[220:221], off
	s_waitcnt vmcnt(8)
	s_waitcnt lgkmcnt(0)
	s_barrier
	s_setprio 1
	s_waitcnt lgkmcnt(0)
	v_mfma_f32_16x16x32_bf16 v[120:123], v[152:155], v[184:187], v[120:123]
	v_mfma_f32_16x16x32_bf16 v[120:123], v[156:159], v[188:191], v[120:123]
	v_mfma_f32_16x16x32_bf16 v[116:119], v[164:167], v[188:191], v[116:119]
	v_mfma_f32_16x16x32_bf16 v[116:119], v[160:163], v[184:187], v[116:119]
	v_mfma_f32_16x16x32_bf16 v[124:127], v[168:171], v[184:187], v[124:127]
	v_mfma_f32_16x16x32_bf16 v[124:127], v[172:175], v[188:191], v[124:127]
	v_mfma_f32_16x16x32_bf16 v[112:115], v[180:183], v[188:191], v[112:115]
	v_mfma_f32_16x16x32_bf16 v[112:115], v[176:179], v[184:187], v[112:115]
	v_mfma_f32_16x16x32_bf16 v[96:99], v[176:179], v[192:195], v[96:99]
	v_mfma_f32_16x16x32_bf16 v[96:99], v[180:183], v[196:199], v[96:99]
	v_mfma_f32_16x16x32_bf16 v[104:107], v[172:175], v[196:199], v[104:107]
	v_mfma_f32_16x16x32_bf16 v[104:107], v[168:171], v[192:195], v[104:107]
	v_mfma_f32_16x16x32_bf16 v[100:103], v[160:163], v[192:195], v[100:103]
	v_mfma_f32_16x16x32_bf16 v[100:103], v[164:167], v[196:199], v[100:103]
	v_mfma_f32_16x16x32_bf16 v[108:111], v[156:159], v[196:199], v[108:111]
	v_mfma_f32_16x16x32_bf16 v[108:111], v[152:155], v[192:195], v[108:111]
	s_setprio 0
	s_setprio 1
	v_mfma_f32_16x16x32_bf16 v[92:95], v[152:155], v[200:203], v[92:95]
	v_mfma_f32_16x16x32_bf16 v[92:95], v[156:159], v[208:211], v[92:95]
	v_mfma_f32_16x16x32_bf16 v[84:87], v[164:167], v[208:211], v[84:87]
	v_mfma_f32_16x16x32_bf16 v[84:87], v[160:163], v[200:203], v[84:87]
	v_mfma_f32_16x16x32_bf16 v[88:91], v[168:171], v[200:203], v[88:91]
	v_mfma_f32_16x16x32_bf16 v[88:91], v[172:175], v[208:211], v[88:91]
	v_mfma_f32_16x16x32_bf16 v[80:83], v[180:183], v[208:211], v[80:83]
	v_mfma_f32_16x16x32_bf16 v[80:83], v[176:179], v[200:203], v[80:83]
	v_mfma_f32_16x16x32_bf16 v[64:67], v[176:179], v[212:215], v[64:67]
	v_mfma_f32_16x16x32_bf16 v[64:67], v[180:183], v[216:219], v[64:67]
	v_mfma_f32_16x16x32_bf16 v[72:75], v[172:175], v[216:219], v[72:75]
	v_mfma_f32_16x16x32_bf16 v[72:75], v[168:171], v[212:215], v[72:75]
	v_mfma_f32_16x16x32_bf16 v[68:71], v[160:163], v[212:215], v[68:71]
	v_mfma_f32_16x16x32_bf16 v[68:71], v[164:167], v[216:219], v[68:71]
	v_mfma_f32_16x16x32_bf16 v[76:79], v[156:159], v[216:219], v[76:79]
	v_mfma_f32_16x16x32_bf16 v[76:79], v[152:155], v[212:215], v[76:79]
	s_setprio 0
	s_barrier
	s_add_i32 s65, s57, s33
	v_lshl_add_u64 v[220:221], s[26:27], 0, v[132:133]
	s_mov_b32 m0, s65
	ds_read_b128 v[184:187], v150 offset:16384
	ds_read_b128 v[188:191], v150 offset:17408
	ds_read_b128 v[192:195], v150 offset:18432
	ds_read_b128 v[196:199], v150 offset:19456
	ds_read_b128 v[200:203], v150 offset:20480
	ds_read_b128 v[208:211], v150 offset:21504
	ds_read_b128 v[212:215], v150 offset:22528
	ds_read_b128 v[216:219], v150 offset:23552
	global_load_lds_dwordx4 v[220:221], off
	s_add_i32 m0, s65, 0x2000
	s_add_u32 s66, s26, 0x80000
	v_lshl_add_u64 v[222:223], s[26:27], 0, v[128:129]
	s_addc_u32 s67, s27, 0
	s_add_i32 s65, s58, s33
	global_load_lds_dwordx4 v[222:223], off
	v_lshl_add_u64 v[224:225], s[66:67], 0, v[132:133]
	s_mov_b32 m0, s65
	v_lshl_add_u64 v[226:227], s[30:31], 0, v[130:131]
	global_load_lds_dwordx4 v[224:225], off
	v_lshl_add_u64 v[224:225], s[66:67], 0, v[128:129]
	s_add_i32 m0, s65, 0x2000
	s_nop 0
	global_load_lds_dwordx4 v[224:225], off
	v_lshl_add_u64 v[224:225], s[30:31], 0, v[134:135]
	s_mov_b32 m0, s44
	s_nop 0
	global_load_lds_dwordx4 v[224:225], off
	s_mov_b32 m0, s45
	s_nop 0
	global_load_lds_dwordx4 v[226:227], off
	s_waitcnt vmcnt(8)
	s_waitcnt lgkmcnt(0)
	s_barrier
; #define PG8_STAGE(bufoff, gbase, voff) do { _Pragma("unroll") for (int _i = 0; _i < 2; ++_i) \
;         __builtin_amdgcn_global_load_lds((const unsigned*)((const char*)(gbase) + (voff)[_i]), (LAS unsigned*)(lds + (bufoff) + ldsw + _i * 8192), 16, 0, 0); } while (0)
; #define PG8_LDA(dst, b, h) do { _Pragma("unroll") for (int m = 0; m < 4; ++m) _Pragma("unroll") for (int k = 0; k < 2; ++k) dst[m][k] = *(const LAS bf16x8*)(lds + PG8_SA(b, h) + aoff + m * 2048 + k * 1024); } while (0)
; #define PG8_LDB(dst, b, h) do { _Pragma("unroll") for (int n = 0; n < 2; ++n) _Pragma("unroll") for (int k = 0; k < 2; ++k) dst[n][k] = *(const LAS bf16x8*)(lds + PG8_SB(b, h) + boff + n * 2048 + k * 1024); } while (0)
; #define PG8_MMA(ai, bj, At, Bt) do { __builtin_amdgcn_s_setprio(1); _Pragma("unroll") for (int m = 0; m < 4; ++m) _Pragma("unroll") for (int n = 0; n < 2; ++n) _Pragma("unroll") for (int k = 0; k < 2; ++k) \
;         acc[ai][bj][m][n] = __builtin_amdgcn_mfma_f32_16x16x32_bf16(Bt[n][k], At[m][k], acc[ai][bj][m][n], 0, 0, 0); __builtin_amdgcn_s_setprio(0); } while (0)
; #define PG8_WAIT_V(n) asm volatile("s_waitcnt vmcnt(" #n ")" ::: "memory")
; #define PG8_WAIT_L(n) asm volatile("s_waitcnt lgkmcnt(" #n ")" ::: "memory")
; #define PG8_BAR __builtin_amdgcn_s_barrier()
; #define PG8_SCHED __builtin_amdgcn_sched_barrier(0)
; template <class Epi>
; __device__ __forceinline__ void gemm_phase(LAS unsigned char* lds, const Gemm g, const StaticOrder& S, const Epi& E) {
;     ...
;             PG8_WAIT_V(8); PG8_WAIT_L(0); PG8_BAR; PG8_MMA(1, 0, At, B0); PG8_MMA(1, 1, At, B1); PG8_BAR; PG8_SCHED;
;             PG8_LDB(B0, 1, 0); PG8_LDB(B1, 1, 1); PG8_SCHED; PG8_LDA(At, 1, 0); PG8_STAGE(PG8_SA(0, 1), a2 + hstepA, voffA);
;             PG8_WAIT_V(8); PG8_WAIT_L(0); PG8_BAR; PG8_MMA(0, 0, At, B0); PG8_MMA(0, 1, At, B1); PG8_BAR; PG8_SCHED;
	s_setprio 1
	s_waitcnt lgkmcnt(0)
	v_mfma_f32_16x16x32_bf16 v[60:63], v[152:155], v[184:187], v[60:63]
	v_mfma_f32_16x16x32_bf16 v[60:63], v[156:159], v[188:191], v[60:63]
	v_mfma_f32_16x16x32_bf16 v[52:55], v[164:167], v[188:191], v[52:55]
	v_mfma_f32_16x16x32_bf16 v[52:55], v[160:163], v[184:187], v[52:55]
	v_mfma_f32_16x16x32_bf16 v[56:59], v[168:171], v[184:187], v[56:59]
	v_mfma_f32_16x16x32_bf16 v[56:59], v[172:175], v[188:191], v[56:59]
	v_mfma_f32_16x16x32_bf16 v[48:51], v[180:183], v[188:191], v[48:51]
	v_mfma_f32_16x16x32_bf16 v[48:51], v[176:179], v[184:187], v[48:51]
	v_mfma_f32_16x16x32_bf16 v[32:35], v[176:179], v[192:195], v[32:35]
	v_mfma_f32_16x16x32_bf16 v[32:35], v[180:183], v[196:199], v[32:35]
	v_mfma_f32_16x16x32_bf16 v[40:43], v[172:175], v[196:199], v[40:43]
	v_mfma_f32_16x16x32_bf16 v[40:43], v[168:171], v[192:195], v[40:43]
	v_mfma_f32_16x16x32_bf16 v[36:39], v[160:163], v[192:195], v[36:39]
	v_mfma_f32_16x16x32_bf16 v[36:39], v[164:167], v[196:199], v[36:39]
	v_mfma_f32_16x16x32_bf16 v[44:47], v[156:159], v[196:199], v[44:47]
	v_mfma_f32_16x16x32_bf16 v[44:47], v[152:155], v[192:195], v[44:47]
	s_setprio 0
	s_setprio 1
	v_mfma_f32_16x16x32_bf16 v[28:31], v[152:155], v[200:203], v[28:31]
	v_mfma_f32_16x16x32_bf16 v[28:31], v[156:159], v[208:211], v[28:31]
	v_mfma_f32_16x16x32_bf16 v[20:23], v[164:167], v[208:211], v[20:23]
	v_mfma_f32_16x16x32_bf16 v[20:23], v[160:163], v[200:203], v[20:23]
	v_mfma_f32_16x16x32_bf16 v[24:27], v[168:171], v[200:203], v[24:27]
	v_mfma_f32_16x16x32_bf16 v[24:27], v[172:175], v[208:211], v[24:27]
	v_mfma_f32_16x16x32_bf16 v[16:19], v[180:183], v[208:211], v[16:19]
	v_mfma_f32_16x16x32_bf16 v[16:19], v[176:179], v[200:203], v[16:19]
	v_mfma_f32_16x16x32_bf16 v[0:3], v[176:179], v[212:215], v[0:3]
	v_mfma_f32_16x16x32_bf16 v[0:3], v[180:183], v[216:219], v[0:3]
	v_mfma_f32_16x16x32_bf16 v[8:11], v[172:175], v[216:219], v[8:11]
	v_mfma_f32_16x16x32_bf16 v[8:11], v[168:171], v[212:215], v[8:11]
	v_mfma_f32_16x16x32_bf16 v[4:7], v[160:163], v[212:215], v[4:7]
	v_mfma_f32_16x16x32_bf16 v[4:7], v[164:167], v[216:219], v[4:7]
	v_mfma_f32_16x16x32_bf16 v[12:15], v[156:159], v[216:219], v[12:15]
	v_mfma_f32_16x16x32_bf16 v[12:15], v[152:155], v[212:215], v[12:15]
	s_setprio 0
	s_barrier
	s_add_i32 s65, 0, 0x18000
	v_add_u32_e32 v151, s65, v146
	s_add_i32 s66, 0, 0x1c000
	ds_read_b128 v[152:155], v151
	ds_read_b128 v[156:159], v151 offset:1024
	ds_read_b128 v[160:163], v151 offset:2048
	ds_read_b128 v[164:167], v151 offset:3072
	v_add_u32_e32 v151, s66, v146
	ds_read_b128 v[168:171], v151
	ds_read_b128 v[172:175], v151 offset:1024
	ds_read_b128 v[176:179], v151 offset:2048
	ds_read_b128 v[180:183], v151 offset:3072
	s_add_u32 s30, s30, 0x80000
	s_addc_u32 s31, s31, 0
	s_mov_b32 m0, s46
	v_lshl_add_u64 v[230:231], s[30:31], 0, v[134:135]
	ds_read_b128 v[184:187], v150 offset:32768
	ds_read_b128 v[188:191], v150 offset:33792
	ds_read_b128 v[192:195], v150 offset:34816
	ds_read_b128 v[196:199], v150 offset:35840
	ds_read_b128 v[200:203], v150 offset:36864
	ds_read_b128 v[208:211], v150 offset:37888
	ds_read_b128 v[212:215], v150 offset:38912
	ds_read_b128 v[216:219], v150 offset:39936
	global_load_lds_dwordx4 v[230:231], off
	v_lshl_add_u64 v[230:231], s[30:31], 0, v[130:131]
	s_mov_b32 m0, s47
	s_nop 0
	global_load_lds_dwordx4 v[230:231], off
	s_waitcnt vmcnt(8)
	s_waitcnt lgkmcnt(0)
	s_barrier
	s_setprio 1
	s_waitcnt lgkmcnt(0)
	v_mfma_f32_16x16x32_bf16 v[120:123], v[152:155], v[184:187], v[120:123]
	v_mfma_f32_16x16x32_bf16 v[120:123], v[156:159], v[188:191], v[120:123]
	v_mfma_f32_16x16x32_bf16 v[116:119], v[164:167], v[188:191], v[116:119]
	v_mfma_f32_16x16x32_bf16 v[116:119], v[160:163], v[184:187], v[116:119]
	v_mfma_f32_16x16x32_bf16 v[124:127], v[168:171], v[184:187], v[124:127]
	v_mfma_f32_16x16x32_bf16 v[124:127], v[172:175], v[188:191], v[124:127]
	v_mfma_f32_16x16x32_bf16 v[112:115], v[180:183], v[188:191], v[112:115]
	v_mfma_f32_16x16x32_bf16 v[112:115], v[176:179], v[184:187], v[112:115]
	v_mfma_f32_16x16x32_bf16 v[96:99], v[176:179], v[192:195], v[96:99]
	v_mfma_f32_16x16x32_bf16 v[96:99], v[180:183], v[196:199], v[96:99]
	v_mfma_f32_16x16x32_bf16 v[104:107], v[172:175], v[196:199], v[104:107]
	v_mfma_f32_16x16x32_bf16 v[104:107], v[168:171], v[192:195], v[104:107]
	v_mfma_f32_16x16x32_bf16 v[100:103], v[160:163], v[192:195], v[100:103]
	v_mfma_f32_16x16x32_bf16 v[100:103], v[164:167], v[196:199], v[100:103]
	v_mfma_f32_16x16x32_bf16 v[108:111], v[156:159], v[196:199], v[108:111]
	v_mfma_f32_16x16x32_bf16 v[108:111], v[152:155], v[192:195], v[108:111]
	s_setprio 0
	s_setprio 1
	v_mfma_f32_16x16x32_bf16 v[92:95], v[152:155], v[200:203], v[92:95]
	v_mfma_f32_16x16x32_bf16 v[92:95], v[156:159], v[208:211], v[92:95]
	v_mfma_f32_16x16x32_bf16 v[84:87], v[164:167], v[208:211], v[84:87]
	v_mfma_f32_16x16x32_bf16 v[84:87], v[160:163], v[200:203], v[84:87]
	v_mfma_f32_16x16x32_bf16 v[88:91], v[168:171], v[200:203], v[88:91]
	v_mfma_f32_16x16x32_bf16 v[88:91], v[172:175], v[208:211], v[88:91]
	v_mfma_f32_16x16x32_bf16 v[80:83], v[180:183], v[208:211], v[80:83]
	v_mfma_f32_16x16x32_bf16 v[80:83], v[176:179], v[200:203], v[80:83]
	v_mfma_f32_16x16x32_bf16 v[64:67], v[176:179], v[212:215], v[64:67]
	v_mfma_f32_16x16x32_bf16 v[64:67], v[180:183], v[216:219], v[64:67]
	v_mfma_f32_16x16x32_bf16 v[72:75], v[172:175], v[216:219], v[72:75]
	v_mfma_f32_16x16x32_bf16 v[72:75], v[168:171], v[212:215], v[72:75]
	v_mfma_f32_16x16x32_bf16 v[68:71], v[160:163], v[212:215], v[68:71]
	v_mfma_f32_16x16x32_bf16 v[68:71], v[164:167], v[216:219], v[68:71]
	v_mfma_f32_16x16x32_bf16 v[76:79], v[156:159], v[216:219], v[76:79]
	v_mfma_f32_16x16x32_bf16 v[76:79], v[152:155], v[212:215], v[76:79]
	s_setprio 0
	s_barrier
; #define PG8_STAGE(bufoff, gbase, voff) do { _Pragma("unroll") for (int _i = 0; _i < 2; ++_i) \
;         __builtin_amdgcn_global_load_lds((const unsigned*)((const char*)(gbase) + (voff)[_i]), (LAS unsigned*)(lds + (bufoff) + ldsw + _i * 8192), 16, 0, 0); } while (0)
; #define PG8_LDA(dst, b, h) do { _Pragma("unroll") for (int m = 0; m < 4; ++m) _Pragma("unroll") for (int k = 0; k < 2; ++k) dst[m][k] = *(const LAS bf16x8*)(lds + PG8_SA(b, h) + aoff + m * 2048 + k * 1024); } while (0)
; #define PG8_MMA(ai, bj, At, Bt) do { __builtin_amdgcn_s_setprio(1); _Pragma("unroll") for (int m = 0; m < 4; ++m) _Pragma("unroll") for (int n = 0; n < 2; ++n) _Pragma("unroll") for (int k = 0; k < 2; ++k) \
;         acc[ai][bj][m][n] = __builtin_amdgcn_mfma_f32_16x16x32_bf16(Bt[n][k], At[m][k], acc[ai][bj][m][n], 0, 0, 0); __builtin_amdgcn_s_setprio(0); } while (0)
; #define PG8_WAIT_V(n) asm volatile("s_waitcnt vmcnt(" #n ")" ::: "memory")
; #define PG8_WAIT_L(n) asm volatile("s_waitcnt lgkmcnt(" #n ")" ::: "memory")
; #define PG8_BAR __builtin_amdgcn_s_barrier()
; #define PG8_SCHED __builtin_amdgcn_sched_barrier(0)
; template <class Epi>
; __device__ __forceinline__ void gemm_phase(LAS unsigned char* lds, const Gemm g, const StaticOrder& S, const Epi& E) {
;     ...
;             PG8_LDA(At, 1, 1); PG8_STAGE(PG8_SB(1, 0), b3, voffB); PG8_STAGE(PG8_SB(1, 1), b3 + hstepB, voffB); PG8_STAGE(PG8_SA(1, 0), a3, voffA);
;             PG8_WAIT_V(8); PG8_WAIT_L(0); PG8_BAR; PG8_MMA(1, 0, At, B0); PG8_MMA(1, 1, At, B1); PG8_BAR; PG8_SCHED;
	s_add_i32 s30, s65, s33
	v_lshl_add_u64 v[220:221], v[220:221], 0, s[8:9]
	s_mov_b32 m0, s30
	ds_read_b128 v[184:187], v150 offset:49152
	ds_read_b128 v[188:191], v150 offset:50176
	ds_read_b128 v[192:195], v150 offset:51200
	ds_read_b128 v[196:199], v150 offset:52224
	ds_read_b128 v[200:203], v150 offset:53248
	ds_read_b128 v[208:211], v150 offset:54272
	ds_read_b128 v[212:215], v150 offset:55296
	ds_read_b128 v[216:219], v150 offset:56320
	global_load_lds_dwordx4 v[220:221], off
	s_add_i32 m0, s30, 0x2000
	s_add_u32 s26, s26, 0x80080
	v_lshl_add_u64 v[220:221], v[222:223], 0, s[8:9]
	s_addc_u32 s27, s27, 0
	s_add_i32 s30, s66, s33
	global_load_lds_dwordx4 v[220:221], off
	v_lshl_add_u64 v[220:221], s[26:27], 0, v[132:133]
	s_mov_b32 m0, s30
	s_nop 0
	global_load_lds_dwordx4 v[220:221], off
	v_lshl_add_u64 v[220:221], s[26:27], 0, v[128:129]
	s_add_i32 m0, s30, 0x2000
	s_nop 0
	global_load_lds_dwordx4 v[220:221], off
	v_lshl_add_u64 v[220:221], v[224:225], 0, s[8:9]
	s_mov_b32 m0, s52
	s_nop 0
	global_load_lds_dwordx4 v[220:221], off
	v_lshl_add_u64 v[220:221], v[226:227], 0, s[8:9]
	s_mov_b32 m0, s53
	s_nop 0
	global_load_lds_dwordx4 v[220:221], off
	s_waitcnt vmcnt(8)
	s_waitcnt lgkmcnt(0)
	s_barrier
	s_setprio 1
	s_waitcnt lgkmcnt(0)
	v_mfma_f32_16x16x32_bf16 v[60:63], v[152:155], v[184:187], v[60:63]
	v_mfma_f32_16x16x32_bf16 v[60:63], v[156:159], v[188:191], v[60:63]
	v_mfma_f32_16x16x32_bf16 v[52:55], v[164:167], v[188:191], v[52:55]
	v_mfma_f32_16x16x32_bf16 v[52:55], v[160:163], v[184:187], v[52:55]
	v_mfma_f32_16x16x32_bf16 v[56:59], v[168:171], v[184:187], v[56:59]
	v_mfma_f32_16x16x32_bf16 v[56:59], v[172:175], v[188:191], v[56:59]
	v_mfma_f32_16x16x32_bf16 v[48:51], v[180:183], v[188:191], v[48:51]
	v_mfma_f32_16x16x32_bf16 v[48:51], v[176:179], v[184:187], v[48:51]
	v_mfma_f32_16x16x32_bf16 v[32:35], v[176:179], v[192:195], v[32:35]
	v_mfma_f32_16x16x32_bf16 v[32:35], v[180:183], v[196:199], v[32:35]
	v_mfma_f32_16x16x32_bf16 v[40:43], v[172:175], v[196:199], v[40:43]
	v_mfma_f32_16x16x32_bf16 v[40:43], v[168:171], v[192:195], v[40:43]
	v_mfma_f32_16x16x32_bf16 v[36:39], v[160:163], v[192:195], v[36:39]
	v_mfma_f32_16x16x32_bf16 v[36:39], v[164:167], v[196:199], v[36:39]
	v_mfma_f32_16x16x32_bf16 v[44:47], v[156:159], v[196:199], v[44:47]
	v_mfma_f32_16x16x32_bf16 v[44:47], v[152:155], v[192:195], v[44:47]
	s_setprio 0
	s_setprio 1
	v_mfma_f32_16x16x32_bf16 v[28:31], v[152:155], v[200:203], v[28:31]
	v_mfma_f32_16x16x32_bf16 v[28:31], v[156:159], v[208:211], v[28:31]
	v_mfma_f32_16x16x32_bf16 v[20:23], v[164:167], v[208:211], v[20:23]
	v_mfma_f32_16x16x32_bf16 v[20:23], v[160:163], v[200:203], v[20:23]
	v_mfma_f32_16x16x32_bf16 v[24:27], v[168:171], v[200:203], v[24:27]
	v_mfma_f32_16x16x32_bf16 v[24:27], v[172:175], v[208:211], v[24:27]
	v_mfma_f32_16x16x32_bf16 v[16:19], v[180:183], v[208:211], v[16:19]
	v_mfma_f32_16x16x32_bf16 v[16:19], v[176:179], v[200:203], v[16:19]
	v_mfma_f32_16x16x32_bf16 v[0:3], v[176:179], v[212:215], v[0:3]
	v_mfma_f32_16x16x32_bf16 v[0:3], v[180:183], v[216:219], v[0:3]
	v_mfma_f32_16x16x32_bf16 v[8:11], v[172:175], v[216:219], v[8:11]
	v_mfma_f32_16x16x32_bf16 v[8:11], v[168:171], v[212:215], v[8:11]
	v_mfma_f32_16x16x32_bf16 v[4:7], v[160:163], v[212:215], v[4:7]
	v_mfma_f32_16x16x32_bf16 v[4:7], v[164:167], v[216:219], v[4:7]
	v_mfma_f32_16x16x32_bf16 v[12:15], v[156:159], v[216:219], v[12:15]
	v_mfma_f32_16x16x32_bf16 v[12:15], v[152:155], v[212:215], v[12:15]
	s_setprio 0
	s_barrier
	s_add_u32 s24, s24, 0x100
	s_addc_u32 s25, s25, 0
	s_add_u32 s62, s62, 0x100
	s_addc_u32 s63, s63, 0
	s_cmp_ge_i32 s64, s49
	s_mov_b32 s26, s64
	s_cbranch_scc0 .LBB0_245

; #define PG8_STAGE(bufoff, gbase, voff) do { _Pragma("unroll") for (int _i = 0; _i < 2; ++_i) \
;         __builtin_amdgcn_global_load_lds((const unsigned*)((const char*)(gbase) + (voff)[_i]), (LAS unsigned*)(lds + (bufoff) + ldsw + _i * 8192), 16, 0, 0); } while (0)
; #define PG8_LDA(dst, b, h) do { _Pragma("unroll") for (int m = 0; m < 4; ++m) _Pragma("unroll") for (int k = 0; k < 2; ++k) dst[m][k] = *(const LAS bf16x8*)(lds + PG8_SA(b, h) + aoff + m * 2048 + k * 1024); } while (0)
; #define PG8_LDB(dst, b, h) do { _Pragma("unroll") for (int n = 0; n < 2; ++n) _Pragma("unroll") for (int k = 0; k < 2; ++k) dst[n][k] = *(const LAS bf16x8*)(lds + PG8_SB(b, h) + boff + n * 2048 + k * 1024); } while (0)
; #define PG8_MMA(ai, bj, At, Bt) do { __builtin_amdgcn_s_setprio(1); _Pragma("unroll") for (int m = 0; m < 4; ++m) _Pragma("unroll") for (int n = 0; n < 2; ++n) _Pragma("unroll") for (int k = 0; k < 2; ++k) \
;         acc[ai][bj][m][n] = __builtin_amdgcn_mfma_f32_16x16x32_bf16(Bt[n][k], At[m][k], acc[ai][bj][m][n], 0, 0, 0); __builtin_amdgcn_s_setprio(0); } while (0)
; #define PG8_WAIT_V(n) asm volatile("s_waitcnt vmcnt(" #n ")" ::: "memory")
; #define PG8_WAIT_L(n) asm volatile("s_waitcnt lgkmcnt(" #n ")" ::: "memory")
; #define PG8_BAR __builtin_amdgcn_s_barrier()
; #define PG8_SCHED __builtin_amdgcn_sched_barrier(0)
; template <class Epi>
; __device__ __forceinline__ void gemm_phase(LAS unsigned char* lds, const Gemm g, const StaticOrder& S, const Epi& E) {
;     ...
;         for (int t = 0; t < nt; t += 2) {
;             const bool last = (t == nt - 2);
;             const char* a1 = cA + (size_t)(t + 1) * kstep;
;             const char* a2 = last ? nA : cA + (size_t)(t + 2) * kstep; const char* b2 = last ? nB : cB + (size_t)(t + 2) * kstep;
;             const char* a3 = a2 + kstep; const char* b3 = b2 + kstep;
;             PG8_LDB(B0, 0, 0); PG8_LDB(B1, 0, 1); PG8_SCHED; PG8_LDA(At, 0, 0); PG8_STAGE(PG8_SA(1, 1), a1 + hstepA, voffA);
;             PG8_WAIT_V(8); PG8_WAIT_L(0); PG8_BAR; PG8_MMA(0, 0, At, B0); PG8_MMA(0, 1, At, B1); PG8_BAR; PG8_SCHED;
;             PG8_LDA(At, 0, 1); PG8_STAGE(PG8_SB(0, 0), b2, voffB); PG8_STAGE(PG8_SB(0, 1), b2 + hstepB, voffB); PG8_STAGE(PG8_SA(0, 0), a2, voffA);
;             PG8_WAIT_V(8); PG8_WAIT_L(0); PG8_BAR; PG8_MMA(1, 0, At, B0); PG8_MMA(1, 1, At, B1); PG8_BAR; PG8_SCHED;
.LBB0_445:
	ds_read_b128 v[148:151], v218
	ds_read_b128 v[152:155], v218 offset:1024
	ds_read_b128 v[156:159], v218 offset:2048
	ds_read_b128 v[160:163], v218 offset:3072
	ds_read_b128 v[164:167], v219
	ds_read_b128 v[168:171], v219 offset:1024
	ds_read_b128 v[172:175], v219 offset:2048
	ds_read_b128 v[176:179], v219 offset:3072
	s_add_i32 s65, s34, 2
	s_add_u32 s30, s4, 0x100
	s_addc_u32 s31, s5, 0
	s_cmp_eq_u32 s49, s34
	s_cselect_b32 s34, s26, s1
	s_cselect_b32 s37, s11, s31
	s_cselect_b32 s36, s10, s30
	s_cselect_b32 s35, s27, s64
	v_lshl_add_u64 v[216:217], s[4:5], 0, v[140:141]
	s_add_i32 m0, s41, 0xc000
	ds_read_b128 v[180:183], v220
	ds_read_b128 v[184:187], v220 offset:1024
	ds_read_b128 v[188:191], v220 offset:2048
	ds_read_b128 v[192:195], v220 offset:3072
	ds_read_b128 v[196:199], v220 offset:4096
	ds_read_b128 v[200:203], v220 offset:5120
	ds_read_b128 v[208:211], v220 offset:6144
	ds_read_b128 v[212:215], v220 offset:7168
	global_load_lds_dwordx4 v[216:217], off
	v_lshl_add_u64 v[216:217], s[4:5], 0, v[142:143]
	s_add_i32 m0, s41, 0xe000
	s_nop 0
	global_load_lds_dwordx4 v[216:217], off
	s_waitcnt vmcnt(8)
	s_waitcnt lgkmcnt(0)
	s_barrier
	s_setprio 1
	s_waitcnt lgkmcnt(0)
	v_mfma_f32_16x16x32_bf16 v[124:127], v[148:151], v[180:183], v[124:127]
	v_mfma_f32_16x16x32_bf16 v[124:127], v[152:155], v[184:187], v[124:127]
	v_mfma_f32_16x16x32_bf16 v[120:123], v[160:163], v[184:187], v[120:123]
	v_mfma_f32_16x16x32_bf16 v[120:123], v[156:159], v[180:183], v[120:123]
	v_mfma_f32_16x16x32_bf16 v[108:111], v[164:167], v[180:183], v[108:111]
	v_mfma_f32_16x16x32_bf16 v[108:111], v[168:171], v[184:187], v[108:111]
	v_mfma_f32_16x16x32_bf16 v[100:103], v[176:179], v[184:187], v[100:103]
	v_mfma_f32_16x16x32_bf16 v[100:103], v[172:175], v[180:183], v[100:103]
	v_mfma_f32_16x16x32_bf16 v[84:87], v[172:175], v[188:191], v[84:87]
	v_mfma_f32_16x16x32_bf16 v[84:87], v[176:179], v[192:195], v[84:87]
	v_mfma_f32_16x16x32_bf16 v[92:95], v[168:171], v[192:195], v[92:95]
	v_mfma_f32_16x16x32_bf16 v[92:95], v[164:167], v[188:191], v[92:95]
	v_mfma_f32_16x16x32_bf16 v[112:115], v[156:159], v[188:191], v[112:115]
	v_mfma_f32_16x16x32_bf16 v[112:115], v[160:163], v[192:195], v[112:115]
	v_mfma_f32_16x16x32_bf16 v[116:119], v[152:155], v[192:195], v[116:119]
	v_mfma_f32_16x16x32_bf16 v[116:119], v[148:151], v[188:191], v[116:119]
	s_setprio 0
	s_setprio 1
	v_mfma_f32_16x16x32_bf16 v[104:107], v[148:151], v[196:199], v[104:107]
	v_mfma_f32_16x16x32_bf16 v[104:107], v[152:155], v[200:203], v[104:107]
	v_mfma_f32_16x16x32_bf16 v[96:99], v[160:163], v[200:203], v[96:99]
	v_mfma_f32_16x16x32_bf16 v[96:99], v[156:159], v[196:199], v[96:99]
	v_mfma_f32_16x16x32_bf16 v[76:79], v[164:167], v[196:199], v[76:79]
	v_mfma_f32_16x16x32_bf16 v[76:79], v[168:171], v[200:203], v[76:79]
	v_mfma_f32_16x16x32_bf16 v[72:75], v[176:179], v[200:203], v[72:75]
	v_mfma_f32_16x16x32_bf16 v[72:75], v[172:175], v[196:199], v[72:75]
	v_mfma_f32_16x16x32_bf16 v[64:67], v[172:175], v[208:211], v[64:67]
	v_mfma_f32_16x16x32_bf16 v[64:67], v[176:179], v[212:215], v[64:67]
	v_mfma_f32_16x16x32_bf16 v[68:71], v[168:171], v[212:215], v[68:71]
	v_mfma_f32_16x16x32_bf16 v[68:71], v[164:167], v[208:211], v[68:71]
	v_mfma_f32_16x16x32_bf16 v[80:83], v[156:159], v[208:211], v[80:83]
	v_mfma_f32_16x16x32_bf16 v[80:83], v[160:163], v[212:215], v[80:83]
	v_mfma_f32_16x16x32_bf16 v[88:91], v[152:155], v[212:215], v[88:91]
	v_mfma_f32_16x16x32_bf16 v[88:91], v[148:151], v[208:211], v[88:91]
	s_setprio 0
	s_barrier
	s_add_i32 s4, s54, s40
	v_lshl_add_u64 v[216:217], s[34:35], 0, v[130:131]
	s_mov_b32 m0, s4
	ds_read_b128 v[180:183], v220 offset:16384
	ds_read_b128 v[184:187], v220 offset:17408
	ds_read_b128 v[188:191], v220 offset:18432
	ds_read_b128 v[192:195], v220 offset:19456
	ds_read_b128 v[196:199], v220 offset:20480
	ds_read_b128 v[200:203], v220 offset:21504
	ds_read_b128 v[208:211], v220 offset:22528
	ds_read_b128 v[212:215], v220 offset:23552
	global_load_lds_dwordx4 v[216:217], off
	s_add_i32 m0, s4, 0x2000
	s_add_u32 s4, s34, 0x158000
	v_lshl_add_u64 v[222:223], s[34:35], 0, v[134:135]
	s_addc_u32 s5, s35, 0
	s_add_i32 s66, s55, s40
	global_load_lds_dwordx4 v[222:223], off
	v_lshl_add_u64 v[224:225], s[4:5], 0, v[130:131]
	s_mov_b32 m0, s66
	v_lshl_add_u64 v[226:227], s[36:37], 0, v[132:133]
	global_load_lds_dwordx4 v[224:225], off
	v_lshl_add_u64 v[224:225], s[4:5], 0, v[134:135]
	s_add_i32 m0, s66, 0x2000
	s_nop 0
	global_load_lds_dwordx4 v[224:225], off
	v_lshl_add_u64 v[224:225], s[36:37], 0, v[128:129]
	s_mov_b32 m0, s41
	s_nop 0
	global_load_lds_dwordx4 v[224:225], off
	s_mov_b32 m0, s42
	s_nop 0
	global_load_lds_dwordx4 v[226:227], off
	s_waitcnt vmcnt(8)
	s_waitcnt lgkmcnt(0)
	s_barrier
; #define PG8_STAGE(bufoff, gbase, voff) do { _Pragma("unroll") for (int _i = 0; _i < 2; ++_i) \
;         __builtin_amdgcn_global_load_lds((const unsigned*)((const char*)(gbase) + (voff)[_i]), (LAS unsigned*)(lds + (bufoff) + ldsw + _i * 8192), 16, 0, 0); } while (0)
; #define PG8_LDA(dst, b, h) do { _Pragma("unroll") for (int m = 0; m < 4; ++m) _Pragma("unroll") for (int k = 0; k < 2; ++k) dst[m][k] = *(const LAS bf16x8*)(lds + PG8_SA(b, h) + aoff + m * 2048 + k * 1024); } while (0)
; #define PG8_LDB(dst, b, h) do { _Pragma("unroll") for (int n = 0; n < 2; ++n) _Pragma("unroll") for (int k = 0; k < 2; ++k) dst[n][k] = *(const LAS bf16x8*)(lds + PG8_SB(b, h) + boff + n * 2048 + k * 1024); } while (0)
; #define PG8_MMA(ai, bj, At, Bt) do { __builtin_amdgcn_s_setprio(1); _Pragma("unroll") for (int m = 0; m < 4; ++m) _Pragma("unroll") for (int n = 0; n < 2; ++n) _Pragma("unroll") for (int k = 0; k < 2; ++k) \
;         acc[ai][bj][m][n] = __builtin_amdgcn_mfma_f32_16x16x32_bf16(Bt[n][k], At[m][k], acc[ai][bj][m][n], 0, 0, 0); __builtin_amdgcn_s_setprio(0); } while (0)
; #define PG8_WAIT_V(n) asm volatile("s_waitcnt vmcnt(" #n ")" ::: "memory")
; #define PG8_WAIT_L(n) asm volatile("s_waitcnt lgkmcnt(" #n ")" ::: "memory")
; #define PG8_BAR __builtin_amdgcn_s_barrier()
; #define PG8_SCHED __builtin_amdgcn_sched_barrier(0)
; template <class Epi>
; __device__ __forceinline__ void gemm_phase(LAS unsigned char* lds, const Gemm g, const StaticOrder& S, const Epi& E) {
;     ...
;             PG8_WAIT_V(8); PG8_WAIT_L(0); PG8_BAR; PG8_MMA(1, 0, At, B0); PG8_MMA(1, 1, At, B1); PG8_BAR; PG8_SCHED;
;             PG8_LDB(B0, 1, 0); PG8_LDB(B1, 1, 1); PG8_SCHED; PG8_LDA(At, 1, 0); PG8_STAGE(PG8_SA(0, 1), a2 + hstepA, voffA);
;             PG8_WAIT_V(8); PG8_WAIT_L(0); PG8_BAR; PG8_MMA(0, 0, At, B0); PG8_MMA(0, 1, At, B1); PG8_BAR; PG8_SCHED;
	s_setprio 1
	s_waitcnt lgkmcnt(0)
	v_mfma_f32_16x16x32_bf16 v[60:63], v[148:151], v[180:183], v[60:63]
	v_mfma_f32_16x16x32_bf16 v[60:63], v[152:155], v[184:187], v[60:63]
	v_mfma_f32_16x16x32_bf16 v[56:59], v[160:163], v[184:187], v[56:59]
	v_mfma_f32_16x16x32_bf16 v[56:59], v[156:159], v[180:183], v[56:59]
	v_mfma_f32_16x16x32_bf16 v[44:47], v[164:167], v[180:183], v[44:47]
	v_mfma_f32_16x16x32_bf16 v[44:47], v[168:171], v[184:187], v[44:47]
	v_mfma_f32_16x16x32_bf16 v[36:39], v[176:179], v[184:187], v[36:39]
	v_mfma_f32_16x16x32_bf16 v[36:39], v[172:175], v[180:183], v[36:39]
	v_mfma_f32_16x16x32_bf16 v[20:23], v[172:175], v[188:191], v[20:23]
	v_mfma_f32_16x16x32_bf16 v[20:23], v[176:179], v[192:195], v[20:23]
	v_mfma_f32_16x16x32_bf16 v[28:31], v[168:171], v[192:195], v[28:31]
	v_mfma_f32_16x16x32_bf16 v[28:31], v[164:167], v[188:191], v[28:31]
	v_mfma_f32_16x16x32_bf16 v[48:51], v[156:159], v[188:191], v[48:51]
	v_mfma_f32_16x16x32_bf16 v[48:51], v[160:163], v[192:195], v[48:51]
	v_mfma_f32_16x16x32_bf16 v[52:55], v[152:155], v[192:195], v[52:55]
	v_mfma_f32_16x16x32_bf16 v[52:55], v[148:151], v[188:191], v[52:55]
	s_setprio 0
	s_setprio 1
	v_mfma_f32_16x16x32_bf16 v[40:43], v[148:151], v[196:199], v[40:43]
	v_mfma_f32_16x16x32_bf16 v[40:43], v[152:155], v[200:203], v[40:43]
	v_mfma_f32_16x16x32_bf16 v[32:35], v[160:163], v[200:203], v[32:35]
	v_mfma_f32_16x16x32_bf16 v[32:35], v[156:159], v[196:199], v[32:35]
	v_mfma_f32_16x16x32_bf16 v[12:15], v[164:167], v[196:199], v[12:15]
	v_mfma_f32_16x16x32_bf16 v[12:15], v[168:171], v[200:203], v[12:15]
	v_mfma_f32_16x16x32_bf16 v[8:11], v[176:179], v[200:203], v[8:11]
	v_mfma_f32_16x16x32_bf16 v[8:11], v[172:175], v[196:199], v[8:11]
	v_mfma_f32_16x16x32_bf16 v[0:3], v[172:175], v[208:211], v[0:3]
	v_mfma_f32_16x16x32_bf16 v[0:3], v[176:179], v[212:215], v[0:3]
	v_mfma_f32_16x16x32_bf16 v[4:7], v[168:171], v[212:215], v[4:7]
	v_mfma_f32_16x16x32_bf16 v[4:7], v[164:167], v[208:211], v[4:7]
	v_mfma_f32_16x16x32_bf16 v[16:19], v[156:159], v[208:211], v[16:19]
	v_mfma_f32_16x16x32_bf16 v[16:19], v[160:163], v[212:215], v[16:19]
	v_mfma_f32_16x16x32_bf16 v[24:27], v[152:155], v[212:215], v[24:27]
	v_mfma_f32_16x16x32_bf16 v[24:27], v[148:151], v[208:211], v[24:27]
	s_setprio 0
	s_barrier
	s_add_i32 s66, 0, 0x18000
	s_add_i32 s67, 0, 0x1c000
	v_add_u32_e32 v160, s66, v207
	v_add_u32_e32 v176, s67, v207
	ds_read_b128 v[148:151], v160
	ds_read_b128 v[152:155], v160 offset:1024
	ds_read_b128 v[156:159], v160 offset:2048
	ds_read_b128 v[160:163], v160 offset:3072
	ds_read_b128 v[164:167], v176
	ds_read_b128 v[168:171], v176 offset:1024
	ds_read_b128 v[172:175], v176 offset:2048
	ds_read_b128 v[176:179], v176 offset:3072
	s_add_u32 s4, s36, 0x158000
	s_addc_u32 s5, s37, 0
	s_mov_b32 m0, s43
	v_lshl_add_u64 v[230:231], s[4:5], 0, v[128:129]
	ds_read_b128 v[180:183], v220 offset:32768
	ds_read_b128 v[184:187], v220 offset:33792
	ds_read_b128 v[188:191], v220 offset:34816
	ds_read_b128 v[192:195], v220 offset:35840
	ds_read_b128 v[196:199], v220 offset:36864
	ds_read_b128 v[200:203], v220 offset:37888
	ds_read_b128 v[208:211], v220 offset:38912
	ds_read_b128 v[212:215], v220 offset:39936
	global_load_lds_dwordx4 v[230:231], off
	v_lshl_add_u64 v[230:231], s[4:5], 0, v[132:133]
	s_mov_b32 m0, s44
	s_nop 0
	global_load_lds_dwordx4 v[230:231], off
	s_waitcnt vmcnt(8)
	s_waitcnt lgkmcnt(0)
	s_barrier
	s_setprio 1
	s_waitcnt lgkmcnt(0)
	v_mfma_f32_16x16x32_bf16 v[124:127], v[148:151], v[180:183], v[124:127]
	v_mfma_f32_16x16x32_bf16 v[124:127], v[152:155], v[184:187], v[124:127]
	v_mfma_f32_16x16x32_bf16 v[120:123], v[160:163], v[184:187], v[120:123]
	v_mfma_f32_16x16x32_bf16 v[120:123], v[156:159], v[180:183], v[120:123]
	v_mfma_f32_16x16x32_bf16 v[108:111], v[164:167], v[180:183], v[108:111]
	v_mfma_f32_16x16x32_bf16 v[108:111], v[168:171], v[184:187], v[108:111]
	v_mfma_f32_16x16x32_bf16 v[100:103], v[176:179], v[184:187], v[100:103]
	v_mfma_f32_16x16x32_bf16 v[100:103], v[172:175], v[180:183], v[100:103]
	v_mfma_f32_16x16x32_bf16 v[84:87], v[172:175], v[188:191], v[84:87]
	v_mfma_f32_16x16x32_bf16 v[84:87], v[176:179], v[192:195], v[84:87]
	v_mfma_f32_16x16x32_bf16 v[92:95], v[168:171], v[192:195], v[92:95]
	v_mfma_f32_16x16x32_bf16 v[92:95], v[164:167], v[188:191], v[92:95]
	v_mfma_f32_16x16x32_bf16 v[112:115], v[156:159], v[188:191], v[112:115]
	v_mfma_f32_16x16x32_bf16 v[112:115], v[160:163], v[192:195], v[112:115]
	v_mfma_f32_16x16x32_bf16 v[116:119], v[152:155], v[192:195], v[116:119]
	v_mfma_f32_16x16x32_bf16 v[116:119], v[148:151], v[188:191], v[116:119]
	s_setprio 0
	s_setprio 1
	v_mfma_f32_16x16x32_bf16 v[104:107], v[148:151], v[196:199], v[104:107]
	v_mfma_f32_16x16x32_bf16 v[104:107], v[152:155], v[200:203], v[104:107]
	v_mfma_f32_16x16x32_bf16 v[96:99], v[160:163], v[200:203], v[96:99]
	v_mfma_f32_16x16x32_bf16 v[96:99], v[156:159], v[196:199], v[96:99]
	v_mfma_f32_16x16x32_bf16 v[76:79], v[164:167], v[196:199], v[76:79]
	v_mfma_f32_16x16x32_bf16 v[76:79], v[168:171], v[200:203], v[76:79]
	v_mfma_f32_16x16x32_bf16 v[72:75], v[176:179], v[200:203], v[72:75]
	v_mfma_f32_16x16x32_bf16 v[72:75], v[172:175], v[196:199], v[72:75]
	v_mfma_f32_16x16x32_bf16 v[64:67], v[172:175], v[208:211], v[64:67]
	v_mfma_f32_16x16x32_bf16 v[64:67], v[176:179], v[212:215], v[64:67]
	v_mfma_f32_16x16x32_bf16 v[68:71], v[168:171], v[212:215], v[68:71]
	v_mfma_f32_16x16x32_bf16 v[68:71], v[164:167], v[208:211], v[68:71]
	v_mfma_f32_16x16x32_bf16 v[80:83], v[156:159], v[208:211], v[80:83]
	v_mfma_f32_16x16x32_bf16 v[80:83], v[160:163], v[212:215], v[80:83]
	v_mfma_f32_16x16x32_bf16 v[88:91], v[152:155], v[212:215], v[88:91]
	v_mfma_f32_16x16x32_bf16 v[88:91], v[148:151], v[208:211], v[88:91]
	s_setprio 0
	s_barrier
; #define PG8_STAGE(bufoff, gbase, voff) do { _Pragma("unroll") for (int _i = 0; _i < 2; ++_i) \
;         __builtin_amdgcn_global_load_lds((const unsigned*)((const char*)(gbase) + (voff)[_i]), (LAS unsigned*)(lds + (bufoff) + ldsw + _i * 8192), 16, 0, 0); } while (0)
; #define PG8_LDA(dst, b, h) do { _Pragma("unroll") for (int m = 0; m < 4; ++m) _Pragma("unroll") for (int k = 0; k < 2; ++k) dst[m][k] = *(const LAS bf16x8*)(lds + PG8_SA(b, h) + aoff + m * 2048 + k * 1024); } while (0)
; #define PG8_MMA(ai, bj, At, Bt) do { __builtin_amdgcn_s_setprio(1); _Pragma("unroll") for (int m = 0; m < 4; ++m) _Pragma("unroll") for (int n = 0; n < 2; ++n) _Pragma("unroll") for (int k = 0; k < 2; ++k) \
;         acc[ai][bj][m][n] = __builtin_amdgcn_mfma_f32_16x16x32_bf16(Bt[n][k], At[m][k], acc[ai][bj][m][n], 0, 0, 0); __builtin_amdgcn_s_setprio(0); } while (0)
; #define PG8_WAIT_V(n) asm volatile("s_waitcnt vmcnt(" #n ")" ::: "memory")
; #define PG8_WAIT_L(n) asm volatile("s_waitcnt lgkmcnt(" #n ")" ::: "memory")
; #define PG8_BAR __builtin_amdgcn_s_barrier()
; #define PG8_SCHED __builtin_amdgcn_sched_barrier(0)
; template <class Epi>
; __device__ __forceinline__ void gemm_phase(LAS unsigned char* lds, const Gemm g, const StaticOrder& S, const Epi& E) {
;     ...
;             PG8_LDA(At, 1, 1); PG8_STAGE(PG8_SB(1, 0), b3, voffB); PG8_STAGE(PG8_SB(1, 1), b3 + hstepB, voffB); PG8_STAGE(PG8_SA(1, 0), a3, voffA);
;             PG8_WAIT_V(8); PG8_WAIT_L(0); PG8_BAR; PG8_MMA(1, 0, At, B0); PG8_MMA(1, 1, At, B1); PG8_BAR; PG8_SCHED;
	s_add_i32 s4, s66, s40
	v_lshl_add_u64 v[216:217], v[216:217], 0, s[16:17]
	s_mov_b32 m0, s4
	ds_read_b128 v[180:183], v220 offset:49152
	ds_read_b128 v[184:187], v220 offset:50176
	ds_read_b128 v[188:191], v220 offset:51200
	ds_read_b128 v[192:195], v220 offset:52224
	ds_read_b128 v[196:199], v220 offset:53248
	ds_read_b128 v[200:203], v220 offset:54272
	ds_read_b128 v[208:211], v220 offset:55296
	ds_read_b128 v[212:215], v220 offset:56320
	global_load_lds_dwordx4 v[216:217], off
	s_add_i32 m0, s4, 0x2000
	s_add_u32 s4, s34, 0x158080
	v_lshl_add_u64 v[216:217], v[222:223], 0, s[16:17]
	s_addc_u32 s5, s35, 0
	s_add_i32 s34, s67, s40
	global_load_lds_dwordx4 v[216:217], off
	v_lshl_add_u64 v[216:217], s[4:5], 0, v[130:131]
	s_mov_b32 m0, s34
	s_nop 0
	global_load_lds_dwordx4 v[216:217], off
	v_lshl_add_u64 v[216:217], s[4:5], 0, v[134:135]
	s_add_i32 m0, s34, 0x2000
	s_nop 0
	global_load_lds_dwordx4 v[216:217], off
	v_lshl_add_u64 v[216:217], v[224:225], 0, s[16:17]
	s_mov_b32 m0, s47
	s_nop 0
	global_load_lds_dwordx4 v[216:217], off
	v_lshl_add_u64 v[216:217], v[226:227], 0, s[16:17]
	s_mov_b32 m0, s48
	s_nop 0
	global_load_lds_dwordx4 v[216:217], off
	s_waitcnt vmcnt(8)
	s_waitcnt lgkmcnt(0)
	s_barrier
	s_setprio 1
	s_waitcnt lgkmcnt(0)
	v_mfma_f32_16x16x32_bf16 v[60:63], v[148:151], v[180:183], v[60:63]
	v_mfma_f32_16x16x32_bf16 v[60:63], v[152:155], v[184:187], v[60:63]
	v_mfma_f32_16x16x32_bf16 v[56:59], v[160:163], v[184:187], v[56:59]
	v_mfma_f32_16x16x32_bf16 v[56:59], v[156:159], v[180:183], v[56:59]
	v_mfma_f32_16x16x32_bf16 v[44:47], v[164:167], v[180:183], v[44:47]
	v_mfma_f32_16x16x32_bf16 v[44:47], v[168:171], v[184:187], v[44:47]
	v_mfma_f32_16x16x32_bf16 v[36:39], v[176:179], v[184:187], v[36:39]
	v_mfma_f32_16x16x32_bf16 v[36:39], v[172:175], v[180:183], v[36:39]
	v_mfma_f32_16x16x32_bf16 v[20:23], v[172:175], v[188:191], v[20:23]
	v_mfma_f32_16x16x32_bf16 v[20:23], v[176:179], v[192:195], v[20:23]
	v_mfma_f32_16x16x32_bf16 v[28:31], v[168:171], v[192:195], v[28:31]
	v_mfma_f32_16x16x32_bf16 v[28:31], v[164:167], v[188:191], v[28:31]
	v_mfma_f32_16x16x32_bf16 v[48:51], v[156:159], v[188:191], v[48:51]
	v_mfma_f32_16x16x32_bf16 v[48:51], v[160:163], v[192:195], v[48:51]
	v_mfma_f32_16x16x32_bf16 v[52:55], v[152:155], v[192:195], v[52:55]
	v_mfma_f32_16x16x32_bf16 v[52:55], v[148:151], v[188:191], v[52:55]
	s_setprio 0
	s_setprio 1
	v_mfma_f32_16x16x32_bf16 v[40:43], v[148:151], v[196:199], v[40:43]
	v_mfma_f32_16x16x32_bf16 v[40:43], v[152:155], v[200:203], v[40:43]
	v_mfma_f32_16x16x32_bf16 v[32:35], v[160:163], v[200:203], v[32:35]
	v_mfma_f32_16x16x32_bf16 v[32:35], v[156:159], v[196:199], v[32:35]
	v_mfma_f32_16x16x32_bf16 v[12:15], v[164:167], v[196:199], v[12:15]
	v_mfma_f32_16x16x32_bf16 v[12:15], v[168:171], v[200:203], v[12:15]
	v_mfma_f32_16x16x32_bf16 v[8:11], v[176:179], v[200:203], v[8:11]
	v_mfma_f32_16x16x32_bf16 v[8:11], v[172:175], v[196:199], v[8:11]
	v_mfma_f32_16x16x32_bf16 v[0:3], v[172:175], v[208:211], v[0:3]
	v_mfma_f32_16x16x32_bf16 v[0:3], v[176:179], v[212:215], v[0:3]
	v_mfma_f32_16x16x32_bf16 v[4:7], v[168:171], v[212:215], v[4:7]
	v_mfma_f32_16x16x32_bf16 v[4:7], v[164:167], v[208:211], v[4:7]
	v_mfma_f32_16x16x32_bf16 v[16:19], v[156:159], v[208:211], v[16:19]
	v_mfma_f32_16x16x32_bf16 v[16:19], v[160:163], v[212:215], v[16:19]
	v_mfma_f32_16x16x32_bf16 v[24:27], v[152:155], v[212:215], v[24:27]
	v_mfma_f32_16x16x32_bf16 v[24:27], v[148:151], v[208:211], v[24:27]
	s_setprio 0
	s_barrier
	s_add_u32 s1, s1, 0x100
	s_addc_u32 s64, s64, 0
	s_cmp_ge_i32 s65, s46
	s_mov_b64 s[4:5], s[30:31]
	s_mov_b32 s34, s65
	s_cbranch_scc0 .LBB0_445
	v_pk_mul_f32 v[164:165], v[126:127], 0.5 op_sel_hi:[1,0]
	v_pk_mul_f32 v[200:201], v[124:125], 0.5 op_sel_hi:[1,0]
	v_pk_mul_f32 v[202:203], v[122:123], 0.5 op_sel_hi:[1,0]
	v_pk_mul_f32 v[208:209], v[120:121], 0.5 op_sel_hi:[1,0]
	v_pk_mul_f32 v[210:211], v[110:111], 0.5 op_sel_hi:[1,0]
	v_pk_mul_f32 v[212:213], v[108:109], 0.5 op_sel_hi:[1,0]
	v_pk_mul_f32 v[214:215], v[102:103], 0.5 op_sel_hi:[1,0]
	v_pk_mul_f32 v[216:217], v[100:101], 0.5 op_sel_hi:[1,0]
	v_pk_mul_f32 v[188:189], v[118:119], 0.5 op_sel_hi:[1,0]
	v_pk_mul_f32 v[186:187], v[116:117], 0.5 op_sel_hi:[1,0]
	v_pk_mul_f32 v[184:185], v[114:115], 0.5 op_sel_hi:[1,0]
	v_pk_mul_f32 v[182:183], v[112:113], 0.5 op_sel_hi:[1,0]
	v_pk_mul_f32 v[196:197], v[94:95], 0.5 op_sel_hi:[1,0]
	v_pk_mul_f32 v[194:195], v[92:93], 0.5 op_sel_hi:[1,0]
	v_pk_mul_f32 v[192:193], v[86:87], 0.5 op_sel_hi:[1,0]
	v_pk_mul_f32 v[190:191], v[84:85], 0.5 op_sel_hi:[1,0]
	v_pk_mul_f32 v[166:167], v[106:107], 0.5 op_sel_hi:[1,0]
	v_pk_mul_f32 v[168:169], v[104:105], 0.5 op_sel_hi:[1,0]
	v_pk_mul_f32 v[170:171], v[98:99], 0.5 op_sel_hi:[1,0]
	v_pk_mul_f32 v[172:173], v[96:97], 0.5 op_sel_hi:[1,0]
	v_pk_mul_f32 v[174:175], v[78:79], 0.5 op_sel_hi:[1,0]
	v_pk_mul_f32 v[176:177], v[76:77], 0.5 op_sel_hi:[1,0]
	v_pk_mul_f32 v[178:179], v[74:75], 0.5 op_sel_hi:[1,0]
	v_pk_mul_f32 v[180:181], v[72:73], 0.5 op_sel_hi:[1,0]
	v_pk_mul_f32 v[154:155], v[90:91], 0.5 op_sel_hi:[1,0]
	v_pk_mul_f32 v[152:153], v[88:89], 0.5 op_sel_hi:[1,0]
	v_pk_mul_f32 v[150:151], v[82:83], 0.5 op_sel_hi:[1,0]
	v_pk_mul_f32 v[148:149], v[80:81], 0.5 op_sel_hi:[1,0]
	v_pk_mul_f32 v[162:163], v[70:71], 0.5 op_sel_hi:[1,0]
	v_pk_mul_f32 v[160:161], v[68:69], 0.5 op_sel_hi:[1,0]
	v_pk_mul_f32 v[158:159], v[66:67], 0.5 op_sel_hi:[1,0]
	v_pk_mul_f32 v[156:157], v[64:65], 0.5 op_sel_hi:[1,0]
	v_pk_mul_f32 v[112:113], v[62:63], 0.5 op_sel_hi:[1,0]
	v_pk_mul_f32 v[114:115], v[60:61], 0.5 op_sel_hi:[1,0]
	v_pk_mul_f32 v[116:117], v[58:59], 0.5 op_sel_hi:[1,0]
	v_pk_mul_f32 v[118:119], v[56:57], 0.5 op_sel_hi:[1,0]
	v_pk_mul_f32 v[120:121], v[46:47], 0.5 op_sel_hi:[1,0]
	v_pk_mul_f32 v[122:123], v[44:45], 0.5 op_sel_hi:[1,0]
	v_pk_mul_f32 v[124:125], v[38:39], 0.5 op_sel_hi:[1,0]
	v_pk_mul_f32 v[126:127], v[36:37], 0.5 op_sel_hi:[1,0]
	v_pk_mul_f32 v[102:103], v[54:55], 0.5 op_sel_hi:[1,0]
	v_pk_mul_f32 v[100:101], v[52:53], 0.5 op_sel_hi:[1,0]
	v_pk_mul_f32 v[98:99], v[50:51], 0.5 op_sel_hi:[1,0]
	v_pk_mul_f32 v[96:97], v[48:49], 0.5 op_sel_hi:[1,0]
	v_pk_mul_f32 v[110:111], v[30:31], 0.5 op_sel_hi:[1,0]
	v_pk_mul_f32 v[108:109], v[28:29], 0.5 op_sel_hi:[1,0]
	v_pk_mul_f32 v[106:107], v[22:23], 0.5 op_sel_hi:[1,0]
	v_pk_mul_f32 v[104:105], v[20:21], 0.5 op_sel_hi:[1,0]
	v_pk_mul_f32 v[86:87], v[42:43], 0.5 op_sel_hi:[1,0]
	v_pk_mul_f32 v[84:85], v[40:41], 0.5 op_sel_hi:[1,0]
	v_pk_mul_f32 v[82:83], v[34:35], 0.5 op_sel_hi:[1,0]
	v_pk_mul_f32 v[80:81], v[32:33], 0.5 op_sel_hi:[1,0]
	v_pk_mul_f32 v[94:95], v[14:15], 0.5 op_sel_hi:[1,0]
	v_pk_mul_f32 v[92:93], v[12:13], 0.5 op_sel_hi:[1,0]
	v_pk_mul_f32 v[90:91], v[10:11], 0.5 op_sel_hi:[1,0]
	v_pk_mul_f32 v[88:89], v[8:9], 0.5 op_sel_hi:[1,0]
	v_pk_mul_f32 v[70:71], v[26:27], 0.5 op_sel_hi:[1,0]
	v_pk_mul_f32 v[68:69], v[24:25], 0.5 op_sel_hi:[1,0]
	v_pk_mul_f32 v[66:67], v[18:19], 0.5 op_sel_hi:[1,0]
	v_pk_mul_f32 v[64:65], v[16:17], 0.5 op_sel_hi:[1,0]
	v_pk_mul_f32 v[78:79], v[6:7], 0.5 op_sel_hi:[1,0]
	v_pk_mul_f32 v[76:77], v[4:5], 0.5 op_sel_hi:[1,0]
	v_pk_mul_f32 v[74:75], v[2:3], 0.5 op_sel_hi:[1,0]
	v_pk_mul_f32 v[72:73], v[0:1], 0.5 op_sel_hi:[1,0]

; #define PG8_STAGE(bufoff, gbase, voff) do { _Pragma("unroll") for (int _i = 0; _i < 2; ++_i) \
;         __builtin_amdgcn_global_load_lds((const unsigned*)((const char*)(gbase) + (voff)[_i]), (LAS unsigned*)(lds + (bufoff) + ldsw + _i * 8192), 16, 0, 0); } while (0)
; #define PG8_LDA(dst, b, h) do { _Pragma("unroll") for (int m = 0; m < 4; ++m) _Pragma("unroll") for (int k = 0; k < 2; ++k) dst[m][k] = *(const LAS bf16x8*)(lds + PG8_SA(b, h) + aoff + m * 2048 + k * 1024); } while (0)
; #define PG8_LDB(dst, b, h) do { _Pragma("unroll") for (int n = 0; n < 2; ++n) _Pragma("unroll") for (int k = 0; k < 2; ++k) dst[n][k] = *(const LAS bf16x8*)(lds + PG8_SB(b, h) + boff + n * 2048 + k * 1024); } while (0)
; #define PG8_MMA(ai, bj, At, Bt) do { __builtin_amdgcn_s_setprio(1); _Pragma("unroll") for (int m = 0; m < 4; ++m) _Pragma("unroll") for (int n = 0; n < 2; ++n) _Pragma("unroll") for (int k = 0; k < 2; ++k) \
;         acc[ai][bj][m][n] = __builtin_amdgcn_mfma_f32_16x16x32_bf16(Bt[n][k], At[m][k], acc[ai][bj][m][n], 0, 0, 0); __builtin_amdgcn_s_setprio(0); } while (0)
; #define PG8_WAIT_V(n) asm volatile("s_waitcnt vmcnt(" #n ")" ::: "memory")
; #define PG8_WAIT_L(n) asm volatile("s_waitcnt lgkmcnt(" #n ")" ::: "memory")
; #define PG8_BAR __builtin_amdgcn_s_barrier()
; #define PG8_SCHED __builtin_amdgcn_sched_barrier(0)
; template <class Epi>
; __device__ __forceinline__ void gemm_phase(LAS unsigned char* lds, const Gemm g, const StaticOrder& S, const Epi& E) {
;     ...
;         for (int t = 0; t < nt; t += 2) {
;             const bool last = (t == nt - 2);
;             const char* a1 = cA + (size_t)(t + 1) * kstep;
;             const char* a2 = last ? nA : cA + (size_t)(t + 2) * kstep; const char* b2 = last ? nB : cB + (size_t)(t + 2) * kstep;
;             const char* a3 = a2 + kstep; const char* b3 = b2 + kstep;
;             PG8_LDB(B0, 0, 0); PG8_LDB(B1, 0, 1); PG8_SCHED; PG8_LDA(At, 0, 0); PG8_STAGE(PG8_SA(1, 1), a1 + hstepA, voffA);
;             PG8_WAIT_V(8); PG8_WAIT_L(0); PG8_BAR; PG8_MMA(0, 0, At, B0); PG8_MMA(0, 1, At, B1); PG8_BAR; PG8_SCHED;
;             PG8_LDA(At, 0, 1); PG8_STAGE(PG8_SB(0, 0), b2, voffB); PG8_STAGE(PG8_SB(0, 1), b2 + hstepB, voffB); PG8_STAGE(PG8_SA(0, 0), a2, voffA);
;             PG8_WAIT_V(8); PG8_WAIT_L(0); PG8_BAR; PG8_MMA(1, 0, At, B0); PG8_MMA(1, 1, At, B1); PG8_BAR; PG8_SCHED;
.LBB0_541:
	ds_read_b128 v[148:151], v155
	ds_read_b128 v[160:163], v155 offset:1024
	ds_read_b128 v[164:167], v155 offset:2048
	ds_read_b128 v[168:171], v155 offset:3072
	ds_read_b128 v[172:175], v156
	ds_read_b128 v[176:179], v156 offset:1024
	ds_read_b128 v[180:183], v156 offset:2048
	ds_read_b128 v[184:187], v156 offset:3072
	s_add_i32 s35, s26, 2
	s_add_u32 s27, s8, 0xfff80080
	s_addc_u32 s30, s9, -1
	s_cmp_eq_u32 s49, s26
	s_cselect_b32 s26, s21, s33
	s_cselect_b32 s31, s1, s30
	s_cselect_b32 s30, s5, s27
	s_cselect_b32 s27, s19, s34
	v_lshl_add_u64 v[224:225], s[8:9], 0, v[140:141]
	s_add_i32 m0, s39, 0xc000
	ds_read_b128 v[188:191], v157
	ds_read_b128 v[192:195], v157 offset:1024
	ds_read_b128 v[196:199], v157 offset:2048
	ds_read_b128 v[200:203], v157 offset:3072
	ds_read_b128 v[208:211], v157 offset:4096
	ds_read_b128 v[212:215], v157 offset:5120
	ds_read_b128 v[216:219], v157 offset:6144
	ds_read_b128 v[220:223], v157 offset:7168
	global_load_lds_dwordx4 v[224:225], off
	v_lshl_add_u64 v[224:225], s[8:9], 0, v[142:143]
	s_add_i32 m0, s39, 0xe000
	s_nop 0
	global_load_lds_dwordx4 v[224:225], off
	s_waitcnt vmcnt(8)
	s_waitcnt lgkmcnt(0)
	s_barrier
	s_setprio 1
	s_waitcnt lgkmcnt(0)
	v_mfma_f32_16x16x32_bf16 v[120:123], v[148:151], v[188:191], v[120:123]
	v_mfma_f32_16x16x32_bf16 v[120:123], v[160:163], v[192:195], v[120:123]
	v_mfma_f32_16x16x32_bf16 v[124:127], v[168:171], v[192:195], v[124:127]
	v_mfma_f32_16x16x32_bf16 v[124:127], v[164:167], v[188:191], v[124:127]
	v_mfma_f32_16x16x32_bf16 v[116:119], v[172:175], v[188:191], v[116:119]
	v_mfma_f32_16x16x32_bf16 v[116:119], v[176:179], v[192:195], v[116:119]
	v_mfma_f32_16x16x32_bf16 v[112:115], v[184:187], v[192:195], v[112:115]
	v_mfma_f32_16x16x32_bf16 v[112:115], v[180:183], v[188:191], v[112:115]
	v_mfma_f32_16x16x32_bf16 v[96:99], v[180:183], v[196:199], v[96:99]
	v_mfma_f32_16x16x32_bf16 v[96:99], v[184:187], v[200:203], v[96:99]
	v_mfma_f32_16x16x32_bf16 v[100:103], v[176:179], v[200:203], v[100:103]
	v_mfma_f32_16x16x32_bf16 v[100:103], v[172:175], v[196:199], v[100:103]
	v_mfma_f32_16x16x32_bf16 v[104:107], v[164:167], v[196:199], v[104:107]
	v_mfma_f32_16x16x32_bf16 v[104:107], v[168:171], v[200:203], v[104:107]
	v_mfma_f32_16x16x32_bf16 v[108:111], v[160:163], v[200:203], v[108:111]
	v_mfma_f32_16x16x32_bf16 v[108:111], v[148:151], v[196:199], v[108:111]
	s_setprio 0
	s_setprio 1
	v_mfma_f32_16x16x32_bf16 v[92:95], v[148:151], v[208:211], v[92:95]
	v_mfma_f32_16x16x32_bf16 v[92:95], v[160:163], v[212:215], v[92:95]
	v_mfma_f32_16x16x32_bf16 v[88:91], v[168:171], v[212:215], v[88:91]
	v_mfma_f32_16x16x32_bf16 v[88:91], v[164:167], v[208:211], v[88:91]
	v_mfma_f32_16x16x32_bf16 v[84:87], v[172:175], v[208:211], v[84:87]
	v_mfma_f32_16x16x32_bf16 v[84:87], v[176:179], v[212:215], v[84:87]
	v_mfma_f32_16x16x32_bf16 v[80:83], v[184:187], v[212:215], v[80:83]
	v_mfma_f32_16x16x32_bf16 v[80:83], v[180:183], v[208:211], v[80:83]
	v_mfma_f32_16x16x32_bf16 v[64:67], v[180:183], v[216:219], v[64:67]
	v_mfma_f32_16x16x32_bf16 v[64:67], v[184:187], v[220:223], v[64:67]
	v_mfma_f32_16x16x32_bf16 v[68:71], v[176:179], v[220:223], v[68:71]
	v_mfma_f32_16x16x32_bf16 v[68:71], v[172:175], v[216:219], v[68:71]
	v_mfma_f32_16x16x32_bf16 v[72:75], v[164:167], v[216:219], v[72:75]
	v_mfma_f32_16x16x32_bf16 v[72:75], v[168:171], v[220:223], v[72:75]
	v_mfma_f32_16x16x32_bf16 v[76:79], v[160:163], v[220:223], v[76:79]
	v_mfma_f32_16x16x32_bf16 v[76:79], v[148:151], v[216:219], v[76:79]
	s_setprio 0
	s_barrier
	s_add_i32 s58, s54, s38
	v_lshl_add_u64 v[224:225], s[26:27], 0, v[130:131]
	s_mov_b32 m0, s58
	ds_read_b128 v[188:191], v157 offset:16384
	ds_read_b128 v[192:195], v157 offset:17408
	ds_read_b128 v[196:199], v157 offset:18432
	ds_read_b128 v[200:203], v157 offset:19456
	ds_read_b128 v[208:211], v157 offset:20480
	ds_read_b128 v[212:215], v157 offset:21504
	ds_read_b128 v[216:219], v157 offset:22528
	ds_read_b128 v[220:223], v157 offset:23552
	global_load_lds_dwordx4 v[224:225], off
	s_add_i32 m0, s58, 0x2000
	s_add_u32 s58, s26, 0x80000
	v_lshl_add_u64 v[226:227], s[26:27], 0, v[134:135]
	s_addc_u32 s59, s27, 0
	s_add_i32 s60, s55, s38
	global_load_lds_dwordx4 v[226:227], off
	v_lshl_add_u64 v[230:231], s[58:59], 0, v[130:131]
	s_mov_b32 m0, s60
	v_lshl_add_u64 v[232:233], s[30:31], 0, v[132:133]
	global_load_lds_dwordx4 v[230:231], off
	v_lshl_add_u64 v[230:231], s[58:59], 0, v[134:135]
	s_add_i32 m0, s60, 0x2000
	s_nop 0
	global_load_lds_dwordx4 v[230:231], off
	v_lshl_add_u64 v[230:231], s[30:31], 0, v[128:129]
	s_mov_b32 m0, s39
	s_nop 0
	global_load_lds_dwordx4 v[230:231], off
	s_mov_b32 m0, s40
	s_nop 0
	global_load_lds_dwordx4 v[232:233], off
	s_waitcnt vmcnt(8)
	s_waitcnt lgkmcnt(0)
	s_barrier
; #define PG8_STAGE(bufoff, gbase, voff) do { _Pragma("unroll") for (int _i = 0; _i < 2; ++_i) \
;         __builtin_amdgcn_global_load_lds((const unsigned*)((const char*)(gbase) + (voff)[_i]), (LAS unsigned*)(lds + (bufoff) + ldsw + _i * 8192), 16, 0, 0); } while (0)
; #define PG8_LDA(dst, b, h) do { _Pragma("unroll") for (int m = 0; m < 4; ++m) _Pragma("unroll") for (int k = 0; k < 2; ++k) dst[m][k] = *(const LAS bf16x8*)(lds + PG8_SA(b, h) + aoff + m * 2048 + k * 1024); } while (0)
; #define PG8_LDB(dst, b, h) do { _Pragma("unroll") for (int n = 0; n < 2; ++n) _Pragma("unroll") for (int k = 0; k < 2; ++k) dst[n][k] = *(const LAS bf16x8*)(lds + PG8_SB(b, h) + boff + n * 2048 + k * 1024); } while (0)
; #define PG8_MMA(ai, bj, At, Bt) do { __builtin_amdgcn_s_setprio(1); _Pragma("unroll") for (int m = 0; m < 4; ++m) _Pragma("unroll") for (int n = 0; n < 2; ++n) _Pragma("unroll") for (int k = 0; k < 2; ++k) \
;         acc[ai][bj][m][n] = __builtin_amdgcn_mfma_f32_16x16x32_bf16(Bt[n][k], At[m][k], acc[ai][bj][m][n], 0, 0, 0); __builtin_amdgcn_s_setprio(0); } while (0)
; #define PG8_WAIT_V(n) asm volatile("s_waitcnt vmcnt(" #n ")" ::: "memory")
; #define PG8_WAIT_L(n) asm volatile("s_waitcnt lgkmcnt(" #n ")" ::: "memory")
; #define PG8_BAR __builtin_amdgcn_s_barrier()
; #define PG8_SCHED __builtin_amdgcn_sched_barrier(0)
; template <class Epi>
; __device__ __forceinline__ void gemm_phase(LAS unsigned char* lds, const Gemm g, const StaticOrder& S, const Epi& E) {
;     ...
;             PG8_WAIT_V(8); PG8_WAIT_L(0); PG8_BAR; PG8_MMA(1, 0, At, B0); PG8_MMA(1, 1, At, B1); PG8_BAR; PG8_SCHED;
;             PG8_LDB(B0, 1, 0); PG8_LDB(B1, 1, 1); PG8_SCHED; PG8_LDA(At, 1, 0); PG8_STAGE(PG8_SA(0, 1), a2 + hstepA, voffA);
;             PG8_WAIT_V(8); PG8_WAIT_L(0); PG8_BAR; PG8_MMA(0, 0, At, B0); PG8_MMA(0, 1, At, B1); PG8_BAR; PG8_SCHED;
	s_setprio 1
	s_waitcnt lgkmcnt(0)
	v_mfma_f32_16x16x32_bf16 v[60:63], v[148:151], v[188:191], v[60:63]
	v_mfma_f32_16x16x32_bf16 v[60:63], v[160:163], v[192:195], v[60:63]
	v_mfma_f32_16x16x32_bf16 v[56:59], v[168:171], v[192:195], v[56:59]
	v_mfma_f32_16x16x32_bf16 v[56:59], v[164:167], v[188:191], v[56:59]
	v_mfma_f32_16x16x32_bf16 v[52:55], v[172:175], v[188:191], v[52:55]
	v_mfma_f32_16x16x32_bf16 v[52:55], v[176:179], v[192:195], v[52:55]
	v_mfma_f32_16x16x32_bf16 v[48:51], v[184:187], v[192:195], v[48:51]
	v_mfma_f32_16x16x32_bf16 v[48:51], v[180:183], v[188:191], v[48:51]
	v_mfma_f32_16x16x32_bf16 v[32:35], v[180:183], v[196:199], v[32:35]
	v_mfma_f32_16x16x32_bf16 v[32:35], v[184:187], v[200:203], v[32:35]
	v_mfma_f32_16x16x32_bf16 v[36:39], v[176:179], v[200:203], v[36:39]
	v_mfma_f32_16x16x32_bf16 v[36:39], v[172:175], v[196:199], v[36:39]
	v_mfma_f32_16x16x32_bf16 v[40:43], v[164:167], v[196:199], v[40:43]
	v_mfma_f32_16x16x32_bf16 v[40:43], v[168:171], v[200:203], v[40:43]
	v_mfma_f32_16x16x32_bf16 v[44:47], v[160:163], v[200:203], v[44:47]
	v_mfma_f32_16x16x32_bf16 v[44:47], v[148:151], v[196:199], v[44:47]
	s_setprio 0
	s_setprio 1
	v_mfma_f32_16x16x32_bf16 v[28:31], v[148:151], v[208:211], v[28:31]
	v_mfma_f32_16x16x32_bf16 v[28:31], v[160:163], v[212:215], v[28:31]
	v_mfma_f32_16x16x32_bf16 v[24:27], v[168:171], v[212:215], v[24:27]
	v_mfma_f32_16x16x32_bf16 v[24:27], v[164:167], v[208:211], v[24:27]
	v_mfma_f32_16x16x32_bf16 v[20:23], v[172:175], v[208:211], v[20:23]
	v_mfma_f32_16x16x32_bf16 v[20:23], v[176:179], v[212:215], v[20:23]
	v_mfma_f32_16x16x32_bf16 v[16:19], v[184:187], v[212:215], v[16:19]
	v_mfma_f32_16x16x32_bf16 v[16:19], v[180:183], v[208:211], v[16:19]
	v_mfma_f32_16x16x32_bf16 v[0:3], v[180:183], v[216:219], v[0:3]
	v_mfma_f32_16x16x32_bf16 v[0:3], v[184:187], v[220:223], v[0:3]
	v_mfma_f32_16x16x32_bf16 v[4:7], v[176:179], v[220:223], v[4:7]
	v_mfma_f32_16x16x32_bf16 v[4:7], v[172:175], v[216:219], v[4:7]
	v_mfma_f32_16x16x32_bf16 v[8:11], v[164:167], v[216:219], v[8:11]
	v_mfma_f32_16x16x32_bf16 v[8:11], v[168:171], v[220:223], v[8:11]
	v_mfma_f32_16x16x32_bf16 v[12:15], v[160:163], v[220:223], v[12:15]
	v_mfma_f32_16x16x32_bf16 v[12:15], v[148:151], v[216:219], v[12:15]
	s_setprio 0
	s_barrier
	s_add_i32 s58, 0, 0x18000
	v_add_u32_e32 v136, s58, v154
	s_add_i32 s59, 0, 0x1c000
	ds_read_b128 v[148:151], v136
	ds_read_b128 v[160:163], v136 offset:1024
	ds_read_b128 v[164:167], v136 offset:2048
	ds_read_b128 v[168:171], v136 offset:3072
	v_add_u32_e32 v136, s59, v154
	ds_read_b128 v[172:175], v136
	ds_read_b128 v[176:179], v136 offset:1024
	ds_read_b128 v[180:183], v136 offset:2048
	ds_read_b128 v[184:187], v136 offset:3072
	s_add_u32 s30, s30, 0x80000
	s_addc_u32 s31, s31, 0
	s_mov_b32 m0, s41
	v_lshl_add_u64 v[234:235], s[30:31], 0, v[128:129]
	ds_read_b128 v[188:191], v157 offset:32768
	ds_read_b128 v[192:195], v157 offset:33792
	ds_read_b128 v[196:199], v157 offset:34816
	ds_read_b128 v[200:203], v157 offset:35840
	ds_read_b128 v[208:211], v157 offset:36864
	ds_read_b128 v[212:215], v157 offset:37888
	ds_read_b128 v[216:219], v157 offset:38912
	ds_read_b128 v[220:223], v157 offset:39936
	global_load_lds_dwordx4 v[234:235], off
	v_lshl_add_u64 v[234:235], s[30:31], 0, v[132:133]
	s_mov_b32 m0, s42
	s_nop 0
	global_load_lds_dwordx4 v[234:235], off
	s_waitcnt vmcnt(8)
	s_waitcnt lgkmcnt(0)
	s_barrier
	s_setprio 1
	s_waitcnt lgkmcnt(0)
	v_mfma_f32_16x16x32_bf16 v[120:123], v[148:151], v[188:191], v[120:123]
	v_mfma_f32_16x16x32_bf16 v[120:123], v[160:163], v[192:195], v[120:123]
	v_mfma_f32_16x16x32_bf16 v[124:127], v[168:171], v[192:195], v[124:127]
	v_mfma_f32_16x16x32_bf16 v[124:127], v[164:167], v[188:191], v[124:127]
	v_mfma_f32_16x16x32_bf16 v[116:119], v[172:175], v[188:191], v[116:119]
	v_mfma_f32_16x16x32_bf16 v[116:119], v[176:179], v[192:195], v[116:119]
	v_mfma_f32_16x16x32_bf16 v[112:115], v[184:187], v[192:195], v[112:115]
	v_mfma_f32_16x16x32_bf16 v[112:115], v[180:183], v[188:191], v[112:115]
	v_mfma_f32_16x16x32_bf16 v[96:99], v[180:183], v[196:199], v[96:99]
	v_mfma_f32_16x16x32_bf16 v[96:99], v[184:187], v[200:203], v[96:99]
	v_mfma_f32_16x16x32_bf16 v[100:103], v[176:179], v[200:203], v[100:103]
	v_mfma_f32_16x16x32_bf16 v[100:103], v[172:175], v[196:199], v[100:103]
	v_mfma_f32_16x16x32_bf16 v[104:107], v[164:167], v[196:199], v[104:107]
	v_mfma_f32_16x16x32_bf16 v[104:107], v[168:171], v[200:203], v[104:107]
	v_mfma_f32_16x16x32_bf16 v[108:111], v[160:163], v[200:203], v[108:111]
	v_mfma_f32_16x16x32_bf16 v[108:111], v[148:151], v[196:199], v[108:111]
	s_setprio 0
	s_setprio 1
	v_mfma_f32_16x16x32_bf16 v[92:95], v[148:151], v[208:211], v[92:95]
	v_mfma_f32_16x16x32_bf16 v[92:95], v[160:163], v[212:215], v[92:95]
	v_mfma_f32_16x16x32_bf16 v[88:91], v[168:171], v[212:215], v[88:91]
	v_mfma_f32_16x16x32_bf16 v[88:91], v[164:167], v[208:211], v[88:91]
	v_mfma_f32_16x16x32_bf16 v[84:87], v[172:175], v[208:211], v[84:87]
	v_mfma_f32_16x16x32_bf16 v[84:87], v[176:179], v[212:215], v[84:87]
	v_mfma_f32_16x16x32_bf16 v[80:83], v[184:187], v[212:215], v[80:83]
	v_mfma_f32_16x16x32_bf16 v[80:83], v[180:183], v[208:211], v[80:83]
	v_mfma_f32_16x16x32_bf16 v[64:67], v[180:183], v[216:219], v[64:67]
	v_mfma_f32_16x16x32_bf16 v[64:67], v[184:187], v[220:223], v[64:67]
	v_mfma_f32_16x16x32_bf16 v[68:71], v[176:179], v[220:223], v[68:71]
	v_mfma_f32_16x16x32_bf16 v[68:71], v[172:175], v[216:219], v[68:71]
	v_mfma_f32_16x16x32_bf16 v[72:75], v[164:167], v[216:219], v[72:75]
	v_mfma_f32_16x16x32_bf16 v[72:75], v[168:171], v[220:223], v[72:75]
	v_mfma_f32_16x16x32_bf16 v[76:79], v[160:163], v[220:223], v[76:79]
	v_mfma_f32_16x16x32_bf16 v[76:79], v[148:151], v[216:219], v[76:79]
	s_setprio 0
	s_barrier
; #define PG8_STAGE(bufoff, gbase, voff) do { _Pragma("unroll") for (int _i = 0; _i < 2; ++_i) \
;         __builtin_amdgcn_global_load_lds((const unsigned*)((const char*)(gbase) + (voff)[_i]), (LAS unsigned*)(lds + (bufoff) + ldsw + _i * 8192), 16, 0, 0); } while (0)
; #define PG8_LDA(dst, b, h) do { _Pragma("unroll") for (int m = 0; m < 4; ++m) _Pragma("unroll") for (int k = 0; k < 2; ++k) dst[m][k] = *(const LAS bf16x8*)(lds + PG8_SA(b, h) + aoff + m * 2048 + k * 1024); } while (0)
; #define PG8_MMA(ai, bj, At, Bt) do { __builtin_amdgcn_s_setprio(1); _Pragma("unroll") for (int m = 0; m < 4; ++m) _Pragma("unroll") for (int n = 0; n < 2; ++n) _Pragma("unroll") for (int k = 0; k < 2; ++k) \
;         acc[ai][bj][m][n] = __builtin_amdgcn_mfma_f32_16x16x32_bf16(Bt[n][k], At[m][k], acc[ai][bj][m][n], 0, 0, 0); __builtin_amdgcn_s_setprio(0); } while (0)
; #define PG8_WAIT_V(n) asm volatile("s_waitcnt vmcnt(" #n ")" ::: "memory")
; #define PG8_WAIT_L(n) asm volatile("s_waitcnt lgkmcnt(" #n ")" ::: "memory")
; #define PG8_BAR __builtin_amdgcn_s_barrier()
; #define PG8_SCHED __builtin_amdgcn_sched_barrier(0)
; template <class Epi>
; __device__ __forceinline__ void gemm_phase(LAS unsigned char* lds, const Gemm g, const StaticOrder& S, const Epi& E) {
;     ...
;             PG8_LDA(At, 1, 1); PG8_STAGE(PG8_SB(1, 0), b3, voffB); PG8_STAGE(PG8_SB(1, 1), b3 + hstepB, voffB); PG8_STAGE(PG8_SA(1, 0), a3, voffA);
;             PG8_WAIT_V(8); PG8_WAIT_L(0); PG8_BAR; PG8_MMA(1, 0, At, B0); PG8_MMA(1, 1, At, B1); PG8_BAR; PG8_SCHED;
	s_add_i32 s30, s58, s38
	v_lshl_add_u64 v[224:225], v[224:225], 0, s[12:13]
	s_mov_b32 m0, s30
	ds_read_b128 v[188:191], v157 offset:49152
	ds_read_b128 v[192:195], v157 offset:50176
	ds_read_b128 v[196:199], v157 offset:51200
	ds_read_b128 v[200:203], v157 offset:52224
	ds_read_b128 v[208:211], v157 offset:53248
	ds_read_b128 v[212:215], v157 offset:54272
	ds_read_b128 v[216:219], v157 offset:55296
	ds_read_b128 v[220:223], v157 offset:56320
	global_load_lds_dwordx4 v[224:225], off
	s_add_i32 m0, s30, 0x2000
	s_add_u32 s26, s26, 0x80080
	v_lshl_add_u64 v[224:225], v[226:227], 0, s[12:13]
	s_addc_u32 s27, s27, 0
	s_add_i32 s30, s59, s38
	global_load_lds_dwordx4 v[224:225], off
	v_lshl_add_u64 v[224:225], s[26:27], 0, v[130:131]
	s_mov_b32 m0, s30
	s_nop 0
	global_load_lds_dwordx4 v[224:225], off
	v_lshl_add_u64 v[224:225], s[26:27], 0, v[134:135]
	s_add_i32 m0, s30, 0x2000
	s_nop 0
	global_load_lds_dwordx4 v[224:225], off
	v_lshl_add_u64 v[224:225], v[230:231], 0, s[12:13]
	s_mov_b32 m0, s47
	s_nop 0
	global_load_lds_dwordx4 v[224:225], off
	v_lshl_add_u64 v[224:225], v[232:233], 0, s[12:13]
	s_mov_b32 m0, s48
	s_nop 0
	global_load_lds_dwordx4 v[224:225], off
	s_waitcnt vmcnt(8)
	s_waitcnt lgkmcnt(0)
	s_barrier
	s_setprio 1
	s_waitcnt lgkmcnt(0)
	v_mfma_f32_16x16x32_bf16 v[60:63], v[148:151], v[188:191], v[60:63]
	v_mfma_f32_16x16x32_bf16 v[60:63], v[160:163], v[192:195], v[60:63]
	v_mfma_f32_16x16x32_bf16 v[56:59], v[168:171], v[192:195], v[56:59]
	v_mfma_f32_16x16x32_bf16 v[56:59], v[164:167], v[188:191], v[56:59]
	v_mfma_f32_16x16x32_bf16 v[52:55], v[172:175], v[188:191], v[52:55]
	v_mfma_f32_16x16x32_bf16 v[52:55], v[176:179], v[192:195], v[52:55]
	v_mfma_f32_16x16x32_bf16 v[48:51], v[184:187], v[192:195], v[48:51]
	v_mfma_f32_16x16x32_bf16 v[48:51], v[180:183], v[188:191], v[48:51]
	v_mfma_f32_16x16x32_bf16 v[32:35], v[180:183], v[196:199], v[32:35]
	v_mfma_f32_16x16x32_bf16 v[32:35], v[184:187], v[200:203], v[32:35]
	v_mfma_f32_16x16x32_bf16 v[36:39], v[176:179], v[200:203], v[36:39]
	v_mfma_f32_16x16x32_bf16 v[36:39], v[172:175], v[196:199], v[36:39]
	v_mfma_f32_16x16x32_bf16 v[40:43], v[164:167], v[196:199], v[40:43]
	v_mfma_f32_16x16x32_bf16 v[40:43], v[168:171], v[200:203], v[40:43]
	v_mfma_f32_16x16x32_bf16 v[44:47], v[160:163], v[200:203], v[44:47]
	v_mfma_f32_16x16x32_bf16 v[44:47], v[148:151], v[196:199], v[44:47]
	s_setprio 0
	s_setprio 1
	v_mfma_f32_16x16x32_bf16 v[28:31], v[148:151], v[208:211], v[28:31]
	v_mfma_f32_16x16x32_bf16 v[28:31], v[160:163], v[212:215], v[28:31]
	v_mfma_f32_16x16x32_bf16 v[24:27], v[168:171], v[212:215], v[24:27]
	v_mfma_f32_16x16x32_bf16 v[24:27], v[164:167], v[208:211], v[24:27]
	v_mfma_f32_16x16x32_bf16 v[20:23], v[172:175], v[208:211], v[20:23]
	v_mfma_f32_16x16x32_bf16 v[20:23], v[176:179], v[212:215], v[20:23]
	v_mfma_f32_16x16x32_bf16 v[16:19], v[184:187], v[212:215], v[16:19]
	v_mfma_f32_16x16x32_bf16 v[16:19], v[180:183], v[208:211], v[16:19]
	v_mfma_f32_16x16x32_bf16 v[0:3], v[180:183], v[216:219], v[0:3]
	v_mfma_f32_16x16x32_bf16 v[0:3], v[184:187], v[220:223], v[0:3]
	v_mfma_f32_16x16x32_bf16 v[4:7], v[176:179], v[220:223], v[4:7]
	v_mfma_f32_16x16x32_bf16 v[4:7], v[172:175], v[216:219], v[4:7]
	v_mfma_f32_16x16x32_bf16 v[8:11], v[164:167], v[216:219], v[8:11]
	v_mfma_f32_16x16x32_bf16 v[8:11], v[168:171], v[220:223], v[8:11]
	v_mfma_f32_16x16x32_bf16 v[12:15], v[160:163], v[220:223], v[12:15]
	v_mfma_f32_16x16x32_bf16 v[12:15], v[148:151], v[216:219], v[12:15]
	s_setprio 0
	s_barrier
	s_add_u32 s8, s8, 0x100
	s_addc_u32 s9, s9, 0
	s_add_u32 s33, s33, 0x100
	s_addc_u32 s34, s34, 0
	s_cmp_ge_i32 s35, s44
	s_mov_b32 s26, s35
	s_cbranch_scc0 .LBB0_541

; #define PG8_STAGE(bufoff, gbase, voff) do { _Pragma("unroll") for (int _i = 0; _i < 2; ++_i) \
;         __builtin_amdgcn_global_load_lds((const unsigned*)((const char*)(gbase) + (voff)[_i]), (LAS unsigned*)(lds + (bufoff) + ldsw + _i * 8192), 16, 0, 0); } while (0)
; #define PG8_LDA(dst, b, h) do { _Pragma("unroll") for (int m = 0; m < 4; ++m) _Pragma("unroll") for (int k = 0; k < 2; ++k) dst[m][k] = *(const LAS bf16x8*)(lds + PG8_SA(b, h) + aoff + m * 2048 + k * 1024); } while (0)
; #define PG8_LDB(dst, b, h) do { _Pragma("unroll") for (int n = 0; n < 2; ++n) _Pragma("unroll") for (int k = 0; k < 2; ++k) dst[n][k] = *(const LAS bf16x8*)(lds + PG8_SB(b, h) + boff + n * 2048 + k * 1024); } while (0)
; #define PG8_MMA(ai, bj, At, Bt) do { __builtin_amdgcn_s_setprio(1); _Pragma("unroll") for (int m = 0; m < 4; ++m) _Pragma("unroll") for (int n = 0; n < 2; ++n) _Pragma("unroll") for (int k = 0; k < 2; ++k) \
;         acc[ai][bj][m][n] = __builtin_amdgcn_mfma_f32_16x16x32_bf16(Bt[n][k], At[m][k], acc[ai][bj][m][n], 0, 0, 0); __builtin_amdgcn_s_setprio(0); } while (0)
; #define PG8_BAR __builtin_amdgcn_s_barrier()
; template <class Epi>
; __device__ __forceinline__ void gemm_phase(LAS unsigned char* lds, const Gemm g, const StaticOrder& S, const Epi& E) {
;     ...
;         for (int t = 0; t < nt; t += 2) {
;             const bool last = (t == nt - 2);
;             const char* a1 = cA + (size_t)(t + 1) * kstep;
;             const char* a2 = last ? nA : cA + (size_t)(t + 2) * kstep; const char* b2 = last ? nB : cB + (size_t)(t + 2) * kstep;
;             const char* a3 = a2 + kstep; const char* b3 = b2 + kstep;
;             PG8_LDB(B0, 0, 0); PG8_LDB(B1, 0, 1); PG8_SCHED; PG8_LDA(At, 0, 0); PG8_STAGE(PG8_SA(1, 1), a1 + hstepA, voffA);
;             PG8_WAIT_V(8); PG8_WAIT_L(0); PG8_BAR; PG8_MMA(0, 0, At, B0); PG8_MMA(0, 1, At, B1); PG8_BAR; PG8_SCHED;
;             PG8_LDA(At, 0, 1); PG8_STAGE(PG8_SB(0, 0), b2, voffB); PG8_STAGE(PG8_SB(0, 1), b2 + hstepB, voffB); PG8_STAGE(PG8_SA(0, 0), a2, voffA);
;             PG8_WAIT_V(8); PG8_WAIT_L(0); PG8_BAR; PG8_MMA(1, 0, At, B0); PG8_MMA(1, 1, At, B1); PG8_BAR; PG8_SCHED;
;             PG8_LDB(B0, 1, 0); PG8_LDB(B1, 1, 1); PG8_SCHED; PG8_LDA(At, 1, 0); PG8_STAGE(PG8_SA(0, 1), a2 + hstepA, voffA);
;             PG8_WAIT_V(8); PG8_WAIT_L(0); PG8_BAR; PG8_MMA(0, 0, At, B0); PG8_MMA(0, 1, At, B1); PG8_BAR; PG8_SCHED;
.LBB0_685:
	ds_read_b128 v[88:91], v85
	ds_read_b128 v[92:95], v85 offset:1024
	ds_read_b128 v[96:99], v85 offset:2048
	ds_read_b128 v[100:103], v85 offset:3072
	s_add_i32 s61, s34, 2
	s_add_u32 s8, s30, 0x100
	s_addc_u32 s9, s31, 0
	s_cmp_eq_u32 s53, s34
	s_cselect_b32 s34, s25, s59
	s_cselect_b32 s37, s27, s9
	s_cselect_b32 s36, s26, s8
	s_cselect_b32 s35, s17, s60
	v_lshl_add_u64 v[136:137], s[30:31], 0, v[76:77]
	s_add_i32 m0, s40, 0xc000
	ds_read_b128 v[104:107], v86
	ds_read_b128 v[108:111], v86 offset:1024
	ds_read_b128 v[112:115], v86 offset:2048
	ds_read_b128 v[116:119], v86 offset:3072
	ds_read_b128 v[120:123], v86 offset:4096
	ds_read_b128 v[124:127], v86 offset:5120
	ds_read_b128 v[128:131], v86 offset:6144
	ds_read_b128 v[132:135], v86 offset:7168
	global_load_lds_dwordx4 v[136:137], off
	v_lshl_add_u64 v[136:137], s[30:31], 0, v[78:79]
	s_add_i32 m0, s40, 0xe000
	s_nop 0
	global_load_lds_dwordx4 v[136:137], off
	s_waitcnt vmcnt(8)
	s_waitcnt lgkmcnt(0)
	s_barrier
	s_setprio 1
	s_waitcnt lgkmcnt(0)
	v_mfma_f32_16x16x32_bf16 v[60:63], v[88:91], v[104:107], v[60:63]
	v_mfma_f32_16x16x32_bf16 v[60:63], v[92:95], v[108:111], v[60:63]
	v_mfma_f32_16x16x32_bf16 v[56:59], v[100:103], v[108:111], v[56:59]
	v_mfma_f32_16x16x32_bf16 v[56:59], v[96:99], v[104:107], v[56:59]
	v_mfma_f32_16x16x32_bf16 v[48:51], v[96:99], v[112:115], v[48:51]
	v_mfma_f32_16x16x32_bf16 v[48:51], v[100:103], v[116:119], v[48:51]
	v_mfma_f32_16x16x32_bf16 v[52:55], v[92:95], v[116:119], v[52:55]
	v_mfma_f32_16x16x32_bf16 v[52:55], v[88:91], v[112:115], v[52:55]
	v_mfma_f32_16x16x32_bf16 v[44:47], v[88:91], v[120:123], v[44:47]
	v_mfma_f32_16x16x32_bf16 v[44:47], v[92:95], v[124:127], v[44:47]
	v_mfma_f32_16x16x32_bf16 v[40:43], v[100:103], v[124:127], v[40:43]
	v_mfma_f32_16x16x32_bf16 v[40:43], v[96:99], v[120:123], v[40:43]
	v_mfma_f32_16x16x32_bf16 v[32:35], v[96:99], v[128:131], v[32:35]
	v_mfma_f32_16x16x32_bf16 v[32:35], v[100:103], v[132:135], v[32:35]
	v_mfma_f32_16x16x32_bf16 v[36:39], v[92:95], v[132:135], v[36:39]
	v_mfma_f32_16x16x32_bf16 v[36:39], v[88:91], v[128:131], v[36:39]
	s_setprio 0
	s_setprio 1
	s_setprio 0
	s_barrier
	s_add_i32 s30, s56, s39
	v_lshl_add_u64 v[136:137], s[34:35], 0, v[66:67]
	s_mov_b32 m0, s30
	ds_read_b128 v[104:107], v86 offset:16384
	ds_read_b128 v[108:111], v86 offset:17408
	ds_read_b128 v[112:115], v86 offset:18432
	ds_read_b128 v[116:119], v86 offset:19456
	ds_read_b128 v[120:123], v86 offset:20480
	ds_read_b128 v[124:127], v86 offset:21504
	ds_read_b128 v[128:131], v86 offset:22528
	ds_read_b128 v[132:135], v86 offset:23552
	global_load_lds_dwordx4 v[136:137], off
	s_add_i32 m0, s30, 0x2000
	s_add_u32 s30, s34, 0x10000
	v_lshl_add_u64 v[138:139], s[34:35], 0, v[70:71]
	s_addc_u32 s31, s35, 0
	global_load_lds_dwordx4 v[138:139], off
	v_lshl_add_u64 v[140:141], s[30:31], 0, v[66:67]
	s_mov_b32 m0, s41
	v_lshl_add_u64 v[142:143], s[36:37], 0, v[68:69]
	global_load_lds_dwordx4 v[140:141], off
	v_lshl_add_u64 v[140:141], s[30:31], 0, v[70:71]
	s_mov_b32 m0, s42
	s_nop 0
	global_load_lds_dwordx4 v[140:141], off
	v_lshl_add_u64 v[140:141], s[36:37], 0, v[64:65]
	s_mov_b32 m0, s40
	s_nop 0
	global_load_lds_dwordx4 v[140:141], off
	s_mov_b32 m0, s43
	s_nop 0
	global_load_lds_dwordx4 v[142:143], off
	s_waitcnt vmcnt(8)
	s_waitcnt lgkmcnt(0)
	s_barrier
	s_setprio 1
	s_waitcnt lgkmcnt(0)
	v_mfma_f32_16x16x32_bf16 v[28:31], v[88:91], v[104:107], v[28:31]
	v_mfma_f32_16x16x32_bf16 v[28:31], v[92:95], v[108:111], v[28:31]
	v_mfma_f32_16x16x32_bf16 v[24:27], v[100:103], v[108:111], v[24:27]
	v_mfma_f32_16x16x32_bf16 v[24:27], v[96:99], v[104:107], v[24:27]
	v_mfma_f32_16x16x32_bf16 v[16:19], v[96:99], v[112:115], v[16:19]
	v_mfma_f32_16x16x32_bf16 v[16:19], v[100:103], v[116:119], v[16:19]
	v_mfma_f32_16x16x32_bf16 v[20:23], v[92:95], v[116:119], v[20:23]
	v_mfma_f32_16x16x32_bf16 v[20:23], v[88:91], v[112:115], v[20:23]
	v_mfma_f32_16x16x32_bf16 v[12:15], v[88:91], v[120:123], v[12:15]
	v_mfma_f32_16x16x32_bf16 v[12:15], v[92:95], v[124:127], v[12:15]
	v_mfma_f32_16x16x32_bf16 v[8:11], v[100:103], v[124:127], v[8:11]
	v_mfma_f32_16x16x32_bf16 v[8:11], v[96:99], v[120:123], v[8:11]
	v_mfma_f32_16x16x32_bf16 v[0:3], v[96:99], v[128:131], v[0:3]
	v_mfma_f32_16x16x32_bf16 v[0:3], v[100:103], v[132:135], v[0:3]
	v_mfma_f32_16x16x32_bf16 v[4:7], v[92:95], v[132:135], v[4:7]
	v_mfma_f32_16x16x32_bf16 v[4:7], v[88:91], v[128:131], v[4:7]
	s_setprio 0
	s_setprio 1
	s_setprio 0
	s_barrier
; #define PG8_STAGE(bufoff, gbase, voff) do { _Pragma("unroll") for (int _i = 0; _i < 2; ++_i) \
;         __builtin_amdgcn_global_load_lds((const unsigned*)((const char*)(gbase) + (voff)[_i]), (LAS unsigned*)(lds + (bufoff) + ldsw + _i * 8192), 16, 0, 0); } while (0)
; #define PG8_LDA(dst, b, h) do { _Pragma("unroll") for (int m = 0; m < 4; ++m) _Pragma("unroll") for (int k = 0; k < 2; ++k) dst[m][k] = *(const LAS bf16x8*)(lds + PG8_SA(b, h) + aoff + m * 2048 + k * 1024); } while (0)
; #define PG8_MMA(ai, bj, At, Bt) do { __builtin_amdgcn_s_setprio(1); _Pragma("unroll") for (int m = 0; m < 4; ++m) _Pragma("unroll") for (int n = 0; n < 2; ++n) _Pragma("unroll") for (int k = 0; k < 2; ++k) \
;         acc[ai][bj][m][n] = __builtin_amdgcn_mfma_f32_16x16x32_bf16(Bt[n][k], At[m][k], acc[ai][bj][m][n], 0, 0, 0); __builtin_amdgcn_s_setprio(0); } while (0)
; #define PG8_WAIT_V(n) asm volatile("s_waitcnt vmcnt(" #n ")" ::: "memory")
; #define PG8_WAIT_L(n) asm volatile("s_waitcnt lgkmcnt(" #n ")" ::: "memory")
; #define PG8_BAR __builtin_amdgcn_s_barrier()
; #define PG8_SCHED __builtin_amdgcn_sched_barrier(0)
; template <class Epi>
; __device__ __forceinline__ void gemm_phase(LAS unsigned char* lds, const Gemm g, const StaticOrder& S, const Epi& E) {
;     ...
;             PG8_WAIT_V(8); PG8_WAIT_L(0); PG8_BAR; PG8_MMA(0, 0, At, B0); PG8_MMA(0, 1, At, B1); PG8_BAR; PG8_SCHED;
;             PG8_LDA(At, 1, 1); PG8_STAGE(PG8_SB(1, 0), b3, voffB); PG8_STAGE(PG8_SB(1, 1), b3 + hstepB, voffB); PG8_STAGE(PG8_SA(1, 0), a3, voffA);
;             PG8_WAIT_V(8); PG8_WAIT_L(0); PG8_BAR; PG8_MMA(1, 0, At, B0); PG8_MMA(1, 1, At, B1); PG8_BAR; PG8_SCHED;
	s_add_i32 s62, 0, 0x18000
	v_add_u32_e32 v87, s62, v84
	ds_read_b128 v[88:91], v87
	ds_read_b128 v[92:95], v87 offset:1024
	ds_read_b128 v[96:99], v87 offset:2048
	ds_read_b128 v[100:103], v87 offset:3072
	s_add_u32 s30, s36, 0x18000
	s_addc_u32 s31, s37, 0
	s_mov_b32 m0, s44
	v_lshl_add_u64 v[144:145], s[30:31], 0, v[64:65]
	ds_read_b128 v[104:107], v86 offset:32768
	ds_read_b128 v[108:111], v86 offset:33792
	ds_read_b128 v[112:115], v86 offset:34816
	ds_read_b128 v[116:119], v86 offset:35840
	ds_read_b128 v[120:123], v86 offset:36864
	ds_read_b128 v[124:127], v86 offset:37888
	ds_read_b128 v[128:131], v86 offset:38912
	ds_read_b128 v[132:135], v86 offset:39936
	global_load_lds_dwordx4 v[144:145], off
	v_lshl_add_u64 v[144:145], s[30:31], 0, v[68:69]
	s_mov_b32 m0, s45
	s_nop 0
	global_load_lds_dwordx4 v[144:145], off
	s_waitcnt vmcnt(8)
	s_waitcnt lgkmcnt(0)
	s_barrier
	s_setprio 1
	s_waitcnt lgkmcnt(0)
	v_mfma_f32_16x16x32_bf16 v[60:63], v[88:91], v[104:107], v[60:63]
	v_mfma_f32_16x16x32_bf16 v[60:63], v[92:95], v[108:111], v[60:63]
	v_mfma_f32_16x16x32_bf16 v[56:59], v[100:103], v[108:111], v[56:59]
	v_mfma_f32_16x16x32_bf16 v[56:59], v[96:99], v[104:107], v[56:59]
	v_mfma_f32_16x16x32_bf16 v[48:51], v[96:99], v[112:115], v[48:51]
	v_mfma_f32_16x16x32_bf16 v[48:51], v[100:103], v[116:119], v[48:51]
	v_mfma_f32_16x16x32_bf16 v[52:55], v[92:95], v[116:119], v[52:55]
	v_mfma_f32_16x16x32_bf16 v[52:55], v[88:91], v[112:115], v[52:55]
	v_mfma_f32_16x16x32_bf16 v[44:47], v[88:91], v[120:123], v[44:47]
	v_mfma_f32_16x16x32_bf16 v[44:47], v[92:95], v[124:127], v[44:47]
	v_mfma_f32_16x16x32_bf16 v[40:43], v[100:103], v[124:127], v[40:43]
	v_mfma_f32_16x16x32_bf16 v[40:43], v[96:99], v[120:123], v[40:43]
	v_mfma_f32_16x16x32_bf16 v[32:35], v[96:99], v[128:131], v[32:35]
	v_mfma_f32_16x16x32_bf16 v[32:35], v[100:103], v[132:135], v[32:35]
	v_mfma_f32_16x16x32_bf16 v[36:39], v[92:95], v[132:135], v[36:39]
	v_mfma_f32_16x16x32_bf16 v[36:39], v[88:91], v[128:131], v[36:39]
	s_setprio 0
	s_setprio 1
	s_setprio 0
	s_barrier
	s_add_i32 s30, s62, s39
	v_lshl_add_u64 v[136:137], v[136:137], 0, s[10:11]
	s_mov_b32 m0, s30
	ds_read_b128 v[104:107], v86 offset:49152
	ds_read_b128 v[108:111], v86 offset:50176
	ds_read_b128 v[112:115], v86 offset:51200
	ds_read_b128 v[116:119], v86 offset:52224
	ds_read_b128 v[120:123], v86 offset:53248
	ds_read_b128 v[124:127], v86 offset:54272
	ds_read_b128 v[128:131], v86 offset:55296
	ds_read_b128 v[132:135], v86 offset:56320
	global_load_lds_dwordx4 v[136:137], off
	s_add_i32 m0, s30, 0x2000
	s_add_u32 s30, s34, 0x10080
	v_lshl_add_u64 v[136:137], v[138:139], 0, s[10:11]
	s_addc_u32 s31, s35, 0
	global_load_lds_dwordx4 v[136:137], off
	v_lshl_add_u64 v[136:137], s[30:31], 0, v[66:67]
	s_mov_b32 m0, s49
	s_nop 0
	global_load_lds_dwordx4 v[136:137], off
	v_lshl_add_u64 v[136:137], s[30:31], 0, v[70:71]
	s_mov_b32 m0, s52
	s_nop 0
	global_load_lds_dwordx4 v[136:137], off
	v_lshl_add_u64 v[136:137], v[140:141], 0, s[10:11]
	s_mov_b32 m0, s47
	s_nop 0
	global_load_lds_dwordx4 v[136:137], off
	v_lshl_add_u64 v[136:137], v[142:143], 0, s[10:11]
	s_mov_b32 m0, s48
	s_nop 0
	global_load_lds_dwordx4 v[136:137], off
	s_waitcnt vmcnt(8)
	s_waitcnt lgkmcnt(0)
	s_barrier
	s_setprio 1
	s_waitcnt lgkmcnt(0)
	v_mfma_f32_16x16x32_bf16 v[28:31], v[88:91], v[104:107], v[28:31]
	v_mfma_f32_16x16x32_bf16 v[28:31], v[92:95], v[108:111], v[28:31]
	v_mfma_f32_16x16x32_bf16 v[24:27], v[100:103], v[108:111], v[24:27]
	v_mfma_f32_16x16x32_bf16 v[24:27], v[96:99], v[104:107], v[24:27]
	v_mfma_f32_16x16x32_bf16 v[16:19], v[96:99], v[112:115], v[16:19]
	v_mfma_f32_16x16x32_bf16 v[16:19], v[100:103], v[116:119], v[16:19]
	v_mfma_f32_16x16x32_bf16 v[20:23], v[92:95], v[116:119], v[20:23]
	v_mfma_f32_16x16x32_bf16 v[20:23], v[88:91], v[112:115], v[20:23]
	v_mfma_f32_16x16x32_bf16 v[12:15], v[88:91], v[120:123], v[12:15]
	v_mfma_f32_16x16x32_bf16 v[12:15], v[92:95], v[124:127], v[12:15]
	v_mfma_f32_16x16x32_bf16 v[8:11], v[100:103], v[124:127], v[8:11]
	v_mfma_f32_16x16x32_bf16 v[8:11], v[96:99], v[120:123], v[8:11]
	v_mfma_f32_16x16x32_bf16 v[0:3], v[96:99], v[128:131], v[0:3]
	v_mfma_f32_16x16x32_bf16 v[0:3], v[100:103], v[132:135], v[0:3]
	v_mfma_f32_16x16x32_bf16 v[4:7], v[92:95], v[132:135], v[4:7]
	v_mfma_f32_16x16x32_bf16 v[4:7], v[88:91], v[128:131], v[4:7]
	s_setprio 0
	s_setprio 1
	s_setprio 0
	s_barrier
	s_add_u32 s59, s59, 0x100
	s_addc_u32 s60, s60, 0
	s_cmp_ge_i32 s61, s46
	s_mov_b64 s[30:31], s[8:9]
	s_mov_b32 s34, s61
	s_cbranch_scc0 .LBB0_685

; #define PG8_STAGE(bufoff, gbase, voff) do { _Pragma("unroll") for (int _i = 0; _i < 2; ++_i) \
;         __builtin_amdgcn_global_load_lds((const unsigned*)((const char*)(gbase) + (voff)[_i]), (LAS unsigned*)(lds + (bufoff) + ldsw + _i * 8192), 16, 0, 0); } while (0)
; #define PG8_LDA(dst, b, h) do { _Pragma("unroll") for (int m = 0; m < 4; ++m) _Pragma("unroll") for (int k = 0; k < 2; ++k) dst[m][k] = *(const LAS bf16x8*)(lds + PG8_SA(b, h) + aoff + m * 2048 + k * 1024); } while (0)
; #define PG8_LDB(dst, b, h) do { _Pragma("unroll") for (int n = 0; n < 2; ++n) _Pragma("unroll") for (int k = 0; k < 2; ++k) dst[n][k] = *(const LAS bf16x8*)(lds + PG8_SB(b, h) + boff + n * 2048 + k * 1024); } while (0)
; #define PG8_MMA(ai, bj, At, Bt) do { __builtin_amdgcn_s_setprio(1); _Pragma("unroll") for (int m = 0; m < 4; ++m) _Pragma("unroll") for (int n = 0; n < 2; ++n) _Pragma("unroll") for (int k = 0; k < 2; ++k) \
;         acc[ai][bj][m][n] = __builtin_amdgcn_mfma_f32_16x16x32_bf16(Bt[n][k], At[m][k], acc[ai][bj][m][n], 0, 0, 0); __builtin_amdgcn_s_setprio(0); } while (0)
; #define PG8_WAIT_V(n) asm volatile("s_waitcnt vmcnt(" #n ")" ::: "memory")
; #define PG8_WAIT_L(n) asm volatile("s_waitcnt lgkmcnt(" #n ")" ::: "memory")
; #define PG8_BAR __builtin_amdgcn_s_barrier()
; #define PG8_SCHED __builtin_amdgcn_sched_barrier(0)
; template <class Epi>
; __device__ __forceinline__ void gemm_phase(LAS unsigned char* lds, const Gemm g, const StaticOrder& S, const Epi& E) {
;     ...
;         for (int t = 0; t < nt; t += 2) {
;             const bool last = (t == nt - 2);
;             const char* a1 = cA + (size_t)(t + 1) * kstep;
;             const char* a2 = last ? nA : cA + (size_t)(t + 2) * kstep; const char* b2 = last ? nB : cB + (size_t)(t + 2) * kstep;
;             const char* a3 = a2 + kstep; const char* b3 = b2 + kstep;
;             PG8_LDB(B0, 0, 0); PG8_LDB(B1, 0, 1); PG8_SCHED; PG8_LDA(At, 0, 0); PG8_STAGE(PG8_SA(1, 1), a1 + hstepA, voffA);
;             PG8_WAIT_V(8); PG8_WAIT_L(0); PG8_BAR; PG8_MMA(0, 0, At, B0); PG8_MMA(0, 1, At, B1); PG8_BAR; PG8_SCHED;
;             PG8_LDA(At, 0, 1); PG8_STAGE(PG8_SB(0, 0), b2, voffB); PG8_STAGE(PG8_SB(0, 1), b2 + hstepB, voffB); PG8_STAGE(PG8_SA(0, 0), a2, voffA);
;             PG8_WAIT_V(8); PG8_WAIT_L(0); PG8_BAR; PG8_MMA(1, 0, At, B0); PG8_MMA(1, 1, At, B1); PG8_BAR; PG8_SCHED;
.LBB0_834:
	ds_read_b128 v[156:159], v152
	ds_read_b128 v[160:163], v152 offset:1024
	ds_read_b128 v[164:167], v152 offset:2048
	ds_read_b128 v[168:171], v152 offset:3072
	ds_read_b128 v[172:175], v153
	ds_read_b128 v[176:179], v153 offset:1024
	ds_read_b128 v[180:183], v153 offset:2048
	ds_read_b128 v[184:187], v153 offset:3072
	s_add_i32 s49, s22, 2
	s_add_u32 s4, s0, 0x100
	s_addc_u32 s5, s1, 0
	s_cmp_eq_u32 s40, s22
	s_cselect_b32 s22, s20, s47
	s_cselect_b32 s25, s11, s5
	s_cselect_b32 s24, s10, s4
	s_cselect_b32 s23, s21, s48
	v_lshl_add_u64 v[224:225], s[0:1], 0, v[138:139]
	s_add_i32 m0, s29, 0xc000
	ds_read_b128 v[188:191], v154
	ds_read_b128 v[192:195], v154 offset:1024
	ds_read_b128 v[196:199], v154 offset:2048
	ds_read_b128 v[200:203], v154 offset:3072
	ds_read_b128 v[208:211], v154 offset:4096
	ds_read_b128 v[212:215], v154 offset:5120
	ds_read_b128 v[216:219], v154 offset:6144
	ds_read_b128 v[220:223], v154 offset:7168
	global_load_lds_dwordx4 v[224:225], off
	v_lshl_add_u64 v[224:225], s[0:1], 0, v[140:141]
	s_add_i32 m0, s29, 0xe000
	s_nop 0
	global_load_lds_dwordx4 v[224:225], off
	s_waitcnt vmcnt(8)
	s_waitcnt lgkmcnt(0)
	s_barrier
	s_setprio 1
	s_waitcnt lgkmcnt(0)
	v_mfma_f32_16x16x32_bf16 v[124:127], v[156:159], v[188:191], v[124:127]
	v_mfma_f32_16x16x32_bf16 v[124:127], v[160:163], v[192:195], v[124:127]
	v_mfma_f32_16x16x32_bf16 v[120:123], v[168:171], v[192:195], v[120:123]
	v_mfma_f32_16x16x32_bf16 v[120:123], v[164:167], v[188:191], v[120:123]
	v_mfma_f32_16x16x32_bf16 v[116:119], v[172:175], v[188:191], v[116:119]
	v_mfma_f32_16x16x32_bf16 v[116:119], v[176:179], v[192:195], v[116:119]
	v_mfma_f32_16x16x32_bf16 v[112:115], v[184:187], v[192:195], v[112:115]
	v_mfma_f32_16x16x32_bf16 v[112:115], v[180:183], v[188:191], v[112:115]
	v_mfma_f32_16x16x32_bf16 v[96:99], v[180:183], v[196:199], v[96:99]
	v_mfma_f32_16x16x32_bf16 v[96:99], v[184:187], v[200:203], v[96:99]
	v_mfma_f32_16x16x32_bf16 v[100:103], v[176:179], v[200:203], v[100:103]
	v_mfma_f32_16x16x32_bf16 v[100:103], v[172:175], v[196:199], v[100:103]
	v_mfma_f32_16x16x32_bf16 v[104:107], v[164:167], v[196:199], v[104:107]
	v_mfma_f32_16x16x32_bf16 v[104:107], v[168:171], v[200:203], v[104:107]
	v_mfma_f32_16x16x32_bf16 v[108:111], v[160:163], v[200:203], v[108:111]
	v_mfma_f32_16x16x32_bf16 v[108:111], v[156:159], v[196:199], v[108:111]
	s_setprio 0
	s_setprio 1
	v_mfma_f32_16x16x32_bf16 v[92:95], v[156:159], v[208:211], v[92:95]
	v_mfma_f32_16x16x32_bf16 v[92:95], v[160:163], v[212:215], v[92:95]
	v_mfma_f32_16x16x32_bf16 v[88:91], v[168:171], v[212:215], v[88:91]
	v_mfma_f32_16x16x32_bf16 v[88:91], v[164:167], v[208:211], v[88:91]
	v_mfma_f32_16x16x32_bf16 v[84:87], v[172:175], v[208:211], v[84:87]
	v_mfma_f32_16x16x32_bf16 v[84:87], v[176:179], v[212:215], v[84:87]
	v_mfma_f32_16x16x32_bf16 v[80:83], v[184:187], v[212:215], v[80:83]
	v_mfma_f32_16x16x32_bf16 v[80:83], v[180:183], v[208:211], v[80:83]
	v_mfma_f32_16x16x32_bf16 v[64:67], v[180:183], v[216:219], v[64:67]
	v_mfma_f32_16x16x32_bf16 v[64:67], v[184:187], v[220:223], v[64:67]
	v_mfma_f32_16x16x32_bf16 v[68:71], v[176:179], v[220:223], v[68:71]
	v_mfma_f32_16x16x32_bf16 v[68:71], v[172:175], v[216:219], v[68:71]
	v_mfma_f32_16x16x32_bf16 v[72:75], v[164:167], v[216:219], v[72:75]
	v_mfma_f32_16x16x32_bf16 v[72:75], v[168:171], v[220:223], v[72:75]
	v_mfma_f32_16x16x32_bf16 v[76:79], v[160:163], v[220:223], v[76:79]
	v_mfma_f32_16x16x32_bf16 v[76:79], v[156:159], v[216:219], v[76:79]
	s_setprio 0
	s_barrier
	s_add_i32 s0, s43, s28
	v_lshl_add_u64 v[224:225], s[22:23], 0, v[130:131]
	s_mov_b32 m0, s0
	ds_read_b128 v[188:191], v154 offset:16384
	ds_read_b128 v[192:195], v154 offset:17408
	ds_read_b128 v[196:199], v154 offset:18432
	ds_read_b128 v[200:203], v154 offset:19456
	ds_read_b128 v[208:211], v154 offset:20480
	ds_read_b128 v[212:215], v154 offset:21504
	ds_read_b128 v[216:219], v154 offset:22528
	ds_read_b128 v[220:223], v154 offset:23552
	global_load_lds_dwordx4 v[224:225], off
	s_add_i32 m0, s0, 0x2000
	s_add_u32 s0, s22, 0x18000
	v_lshl_add_u64 v[226:227], s[22:23], 0, v[134:135]
	s_addc_u32 s1, s23, 0
	s_add_i32 s50, s44, s28
	global_load_lds_dwordx4 v[226:227], off
	v_lshl_add_u64 v[230:231], s[0:1], 0, v[130:131]
	s_mov_b32 m0, s50
	v_lshl_add_u64 v[232:233], s[24:25], 0, v[132:133]
	global_load_lds_dwordx4 v[230:231], off
	v_lshl_add_u64 v[230:231], s[0:1], 0, v[134:135]
	s_add_i32 m0, s50, 0x2000
	s_nop 0
	global_load_lds_dwordx4 v[230:231], off
	v_lshl_add_u64 v[230:231], s[24:25], 0, v[128:129]
	s_mov_b32 m0, s29
	s_nop 0
	global_load_lds_dwordx4 v[230:231], off
	s_mov_b32 m0, s30
	s_nop 0
	global_load_lds_dwordx4 v[232:233], off
	s_waitcnt vmcnt(8)
	s_waitcnt lgkmcnt(0)
	s_barrier
; #define PG8_STAGE(bufoff, gbase, voff) do { _Pragma("unroll") for (int _i = 0; _i < 2; ++_i) \
;         __builtin_amdgcn_global_load_lds((const unsigned*)((const char*)(gbase) + (voff)[_i]), (LAS unsigned*)(lds + (bufoff) + ldsw + _i * 8192), 16, 0, 0); } while (0)
; #define PG8_LDA(dst, b, h) do { _Pragma("unroll") for (int m = 0; m < 4; ++m) _Pragma("unroll") for (int k = 0; k < 2; ++k) dst[m][k] = *(const LAS bf16x8*)(lds + PG8_SA(b, h) + aoff + m * 2048 + k * 1024); } while (0)
; #define PG8_LDB(dst, b, h) do { _Pragma("unroll") for (int n = 0; n < 2; ++n) _Pragma("unroll") for (int k = 0; k < 2; ++k) dst[n][k] = *(const LAS bf16x8*)(lds + PG8_SB(b, h) + boff + n * 2048 + k * 1024); } while (0)
; #define PG8_MMA(ai, bj, At, Bt) do { __builtin_amdgcn_s_setprio(1); _Pragma("unroll") for (int m = 0; m < 4; ++m) _Pragma("unroll") for (int n = 0; n < 2; ++n) _Pragma("unroll") for (int k = 0; k < 2; ++k) \
;         acc[ai][bj][m][n] = __builtin_amdgcn_mfma_f32_16x16x32_bf16(Bt[n][k], At[m][k], acc[ai][bj][m][n], 0, 0, 0); __builtin_amdgcn_s_setprio(0); } while (0)
; #define PG8_WAIT_V(n) asm volatile("s_waitcnt vmcnt(" #n ")" ::: "memory")
; #define PG8_WAIT_L(n) asm volatile("s_waitcnt lgkmcnt(" #n ")" ::: "memory")
; #define PG8_BAR __builtin_amdgcn_s_barrier()
; #define PG8_SCHED __builtin_amdgcn_sched_barrier(0)
; template <class Epi>
; __device__ __forceinline__ void gemm_phase(LAS unsigned char* lds, const Gemm g, const StaticOrder& S, const Epi& E) {
;     ...
;             PG8_WAIT_V(8); PG8_WAIT_L(0); PG8_BAR; PG8_MMA(1, 0, At, B0); PG8_MMA(1, 1, At, B1); PG8_BAR; PG8_SCHED;
;             PG8_LDB(B0, 1, 0); PG8_LDB(B1, 1, 1); PG8_SCHED; PG8_LDA(At, 1, 0); PG8_STAGE(PG8_SA(0, 1), a2 + hstepA, voffA);
;             PG8_WAIT_V(8); PG8_WAIT_L(0); PG8_BAR; PG8_MMA(0, 0, At, B0); PG8_MMA(0, 1, At, B1); PG8_BAR; PG8_SCHED;
	s_setprio 1
	s_waitcnt lgkmcnt(0)
	v_mfma_f32_16x16x32_bf16 v[60:63], v[156:159], v[188:191], v[60:63]
	v_mfma_f32_16x16x32_bf16 v[60:63], v[160:163], v[192:195], v[60:63]
	v_mfma_f32_16x16x32_bf16 v[56:59], v[168:171], v[192:195], v[56:59]
	v_mfma_f32_16x16x32_bf16 v[56:59], v[164:167], v[188:191], v[56:59]
	v_mfma_f32_16x16x32_bf16 v[52:55], v[172:175], v[188:191], v[52:55]
	v_mfma_f32_16x16x32_bf16 v[52:55], v[176:179], v[192:195], v[52:55]
	v_mfma_f32_16x16x32_bf16 v[48:51], v[184:187], v[192:195], v[48:51]
	v_mfma_f32_16x16x32_bf16 v[48:51], v[180:183], v[188:191], v[48:51]
	v_mfma_f32_16x16x32_bf16 v[32:35], v[180:183], v[196:199], v[32:35]
	v_mfma_f32_16x16x32_bf16 v[32:35], v[184:187], v[200:203], v[32:35]
	v_mfma_f32_16x16x32_bf16 v[36:39], v[176:179], v[200:203], v[36:39]
	v_mfma_f32_16x16x32_bf16 v[36:39], v[172:175], v[196:199], v[36:39]
	v_mfma_f32_16x16x32_bf16 v[40:43], v[164:167], v[196:199], v[40:43]
	v_mfma_f32_16x16x32_bf16 v[40:43], v[168:171], v[200:203], v[40:43]
	v_mfma_f32_16x16x32_bf16 v[44:47], v[160:163], v[200:203], v[44:47]
	v_mfma_f32_16x16x32_bf16 v[44:47], v[156:159], v[196:199], v[44:47]
	s_setprio 0
	s_setprio 1
	v_mfma_f32_16x16x32_bf16 v[28:31], v[156:159], v[208:211], v[28:31]
	v_mfma_f32_16x16x32_bf16 v[28:31], v[160:163], v[212:215], v[28:31]
	v_mfma_f32_16x16x32_bf16 v[24:27], v[168:171], v[212:215], v[24:27]
	v_mfma_f32_16x16x32_bf16 v[24:27], v[164:167], v[208:211], v[24:27]
	v_mfma_f32_16x16x32_bf16 v[20:23], v[172:175], v[208:211], v[20:23]
	v_mfma_f32_16x16x32_bf16 v[20:23], v[176:179], v[212:215], v[20:23]
	v_mfma_f32_16x16x32_bf16 v[16:19], v[184:187], v[212:215], v[16:19]
	v_mfma_f32_16x16x32_bf16 v[16:19], v[180:183], v[208:211], v[16:19]
	v_mfma_f32_16x16x32_bf16 v[0:3], v[180:183], v[216:219], v[0:3]
	v_mfma_f32_16x16x32_bf16 v[0:3], v[184:187], v[220:223], v[0:3]
	v_mfma_f32_16x16x32_bf16 v[4:7], v[176:179], v[220:223], v[4:7]
	v_mfma_f32_16x16x32_bf16 v[4:7], v[172:175], v[216:219], v[4:7]
	v_mfma_f32_16x16x32_bf16 v[8:11], v[164:167], v[216:219], v[8:11]
	v_mfma_f32_16x16x32_bf16 v[8:11], v[168:171], v[220:223], v[8:11]
	v_mfma_f32_16x16x32_bf16 v[12:15], v[160:163], v[220:223], v[12:15]
	v_mfma_f32_16x16x32_bf16 v[12:15], v[156:159], v[216:219], v[12:15]
	s_setprio 0
	s_barrier
	s_add_i32 s50, 0, 0x18000
	v_add_u32_e32 v136, s50, v149
	s_add_i32 s51, 0, 0x1c000
	ds_read_b128 v[156:159], v136
	ds_read_b128 v[160:163], v136 offset:1024
	ds_read_b128 v[164:167], v136 offset:2048
	ds_read_b128 v[168:171], v136 offset:3072
	v_add_u32_e32 v136, s51, v149
	ds_read_b128 v[172:175], v136
	ds_read_b128 v[176:179], v136 offset:1024
	ds_read_b128 v[180:183], v136 offset:2048
	ds_read_b128 v[184:187], v136 offset:3072
	s_add_u32 s0, s24, 0x18000
	s_addc_u32 s1, s25, 0
	s_mov_b32 m0, s31
	v_lshl_add_u64 v[234:235], s[0:1], 0, v[128:129]
	ds_read_b128 v[188:191], v154 offset:32768
	ds_read_b128 v[192:195], v154 offset:33792
	ds_read_b128 v[196:199], v154 offset:34816
	ds_read_b128 v[200:203], v154 offset:35840
	ds_read_b128 v[208:211], v154 offset:36864
	ds_read_b128 v[212:215], v154 offset:37888
	ds_read_b128 v[216:219], v154 offset:38912
	ds_read_b128 v[220:223], v154 offset:39936
	global_load_lds_dwordx4 v[234:235], off
	v_lshl_add_u64 v[234:235], s[0:1], 0, v[132:133]
	s_mov_b32 m0, s34
	s_nop 0
	global_load_lds_dwordx4 v[234:235], off
	s_waitcnt vmcnt(8)
	s_waitcnt lgkmcnt(0)
	s_barrier
	s_setprio 1
	s_waitcnt lgkmcnt(0)
	v_mfma_f32_16x16x32_bf16 v[124:127], v[156:159], v[188:191], v[124:127]
	v_mfma_f32_16x16x32_bf16 v[124:127], v[160:163], v[192:195], v[124:127]
	v_mfma_f32_16x16x32_bf16 v[120:123], v[168:171], v[192:195], v[120:123]
	v_mfma_f32_16x16x32_bf16 v[120:123], v[164:167], v[188:191], v[120:123]
	v_mfma_f32_16x16x32_bf16 v[116:119], v[172:175], v[188:191], v[116:119]
	v_mfma_f32_16x16x32_bf16 v[116:119], v[176:179], v[192:195], v[116:119]
	v_mfma_f32_16x16x32_bf16 v[112:115], v[184:187], v[192:195], v[112:115]
	v_mfma_f32_16x16x32_bf16 v[112:115], v[180:183], v[188:191], v[112:115]
	v_mfma_f32_16x16x32_bf16 v[96:99], v[180:183], v[196:199], v[96:99]
	v_mfma_f32_16x16x32_bf16 v[96:99], v[184:187], v[200:203], v[96:99]
	v_mfma_f32_16x16x32_bf16 v[100:103], v[176:179], v[200:203], v[100:103]
	v_mfma_f32_16x16x32_bf16 v[100:103], v[172:175], v[196:199], v[100:103]
	v_mfma_f32_16x16x32_bf16 v[104:107], v[164:167], v[196:199], v[104:107]
	v_mfma_f32_16x16x32_bf16 v[104:107], v[168:171], v[200:203], v[104:107]
	v_mfma_f32_16x16x32_bf16 v[108:111], v[160:163], v[200:203], v[108:111]
	v_mfma_f32_16x16x32_bf16 v[108:111], v[156:159], v[196:199], v[108:111]
	s_setprio 0
	s_setprio 1
	v_mfma_f32_16x16x32_bf16 v[92:95], v[156:159], v[208:211], v[92:95]
	v_mfma_f32_16x16x32_bf16 v[92:95], v[160:163], v[212:215], v[92:95]
	v_mfma_f32_16x16x32_bf16 v[88:91], v[168:171], v[212:215], v[88:91]
	v_mfma_f32_16x16x32_bf16 v[88:91], v[164:167], v[208:211], v[88:91]
	v_mfma_f32_16x16x32_bf16 v[84:87], v[172:175], v[208:211], v[84:87]
	v_mfma_f32_16x16x32_bf16 v[84:87], v[176:179], v[212:215], v[84:87]
	v_mfma_f32_16x16x32_bf16 v[80:83], v[184:187], v[212:215], v[80:83]
	v_mfma_f32_16x16x32_bf16 v[80:83], v[180:183], v[208:211], v[80:83]
	v_mfma_f32_16x16x32_bf16 v[64:67], v[180:183], v[216:219], v[64:67]
	v_mfma_f32_16x16x32_bf16 v[64:67], v[184:187], v[220:223], v[64:67]
	v_mfma_f32_16x16x32_bf16 v[68:71], v[176:179], v[220:223], v[68:71]
	v_mfma_f32_16x16x32_bf16 v[68:71], v[172:175], v[216:219], v[68:71]
	v_mfma_f32_16x16x32_bf16 v[72:75], v[164:167], v[216:219], v[72:75]
	v_mfma_f32_16x16x32_bf16 v[72:75], v[168:171], v[220:223], v[72:75]
	v_mfma_f32_16x16x32_bf16 v[76:79], v[160:163], v[220:223], v[76:79]
	v_mfma_f32_16x16x32_bf16 v[76:79], v[156:159], v[216:219], v[76:79]
	s_setprio 0
	s_barrier
; #define PG8_STAGE(bufoff, gbase, voff) do { _Pragma("unroll") for (int _i = 0; _i < 2; ++_i) \
;         __builtin_amdgcn_global_load_lds((const unsigned*)((const char*)(gbase) + (voff)[_i]), (LAS unsigned*)(lds + (bufoff) + ldsw + _i * 8192), 16, 0, 0); } while (0)
; #define PG8_LDA(dst, b, h) do { _Pragma("unroll") for (int m = 0; m < 4; ++m) _Pragma("unroll") for (int k = 0; k < 2; ++k) dst[m][k] = *(const LAS bf16x8*)(lds + PG8_SA(b, h) + aoff + m * 2048 + k * 1024); } while (0)
; #define PG8_MMA(ai, bj, At, Bt) do { __builtin_amdgcn_s_setprio(1); _Pragma("unroll") for (int m = 0; m < 4; ++m) _Pragma("unroll") for (int n = 0; n < 2; ++n) _Pragma("unroll") for (int k = 0; k < 2; ++k) \
;         acc[ai][bj][m][n] = __builtin_amdgcn_mfma_f32_16x16x32_bf16(Bt[n][k], At[m][k], acc[ai][bj][m][n], 0, 0, 0); __builtin_amdgcn_s_setprio(0); } while (0)
; #define PG8_WAIT_V(n) asm volatile("s_waitcnt vmcnt(" #n ")" ::: "memory")
; #define PG8_WAIT_L(n) asm volatile("s_waitcnt lgkmcnt(" #n ")" ::: "memory")
; #define PG8_BAR __builtin_amdgcn_s_barrier()
; #define PG8_SCHED __builtin_amdgcn_sched_barrier(0)
; template <class Epi>
; __device__ __forceinline__ void gemm_phase(LAS unsigned char* lds, const Gemm g, const StaticOrder& S, const Epi& E) {
;     ...
;             PG8_LDA(At, 1, 1); PG8_STAGE(PG8_SB(1, 0), b3, voffB); PG8_STAGE(PG8_SB(1, 1), b3 + hstepB, voffB); PG8_STAGE(PG8_SA(1, 0), a3, voffA);
;             PG8_WAIT_V(8); PG8_WAIT_L(0); PG8_BAR; PG8_MMA(1, 0, At, B0); PG8_MMA(1, 1, At, B1); PG8_BAR; PG8_SCHED;
	s_add_i32 s0, s50, s28
	v_lshl_add_u64 v[224:225], v[224:225], 0, s[14:15]
	s_mov_b32 m0, s0
	ds_read_b128 v[188:191], v154 offset:49152
	ds_read_b128 v[192:195], v154 offset:50176
	ds_read_b128 v[196:199], v154 offset:51200
	ds_read_b128 v[200:203], v154 offset:52224
	ds_read_b128 v[208:211], v154 offset:53248
	ds_read_b128 v[212:215], v154 offset:54272
	ds_read_b128 v[216:219], v154 offset:55296
	ds_read_b128 v[220:223], v154 offset:56320
	global_load_lds_dwordx4 v[224:225], off
	s_add_i32 m0, s0, 0x2000
	s_add_u32 s0, s22, 0x18080
	v_lshl_add_u64 v[224:225], v[226:227], 0, s[14:15]
	s_addc_u32 s1, s23, 0
	s_add_i32 s22, s51, s28
	global_load_lds_dwordx4 v[224:225], off
	v_lshl_add_u64 v[224:225], s[0:1], 0, v[130:131]
	s_mov_b32 m0, s22
	s_nop 0
	global_load_lds_dwordx4 v[224:225], off
	v_lshl_add_u64 v[224:225], s[0:1], 0, v[134:135]
	s_add_i32 m0, s22, 0x2000
	s_nop 0
	global_load_lds_dwordx4 v[224:225], off
	v_lshl_add_u64 v[224:225], v[230:231], 0, s[14:15]
	s_mov_b32 m0, s38
	s_nop 0
	global_load_lds_dwordx4 v[224:225], off
	v_lshl_add_u64 v[224:225], v[232:233], 0, s[14:15]
	s_mov_b32 m0, s39
	s_nop 0
	global_load_lds_dwordx4 v[224:225], off
	s_waitcnt vmcnt(8)
	s_waitcnt lgkmcnt(0)
	s_barrier
	s_setprio 1
	s_waitcnt lgkmcnt(0)
	v_mfma_f32_16x16x32_bf16 v[60:63], v[156:159], v[188:191], v[60:63]
	v_mfma_f32_16x16x32_bf16 v[60:63], v[160:163], v[192:195], v[60:63]
	v_mfma_f32_16x16x32_bf16 v[56:59], v[168:171], v[192:195], v[56:59]
	v_mfma_f32_16x16x32_bf16 v[56:59], v[164:167], v[188:191], v[56:59]
	v_mfma_f32_16x16x32_bf16 v[52:55], v[172:175], v[188:191], v[52:55]
	v_mfma_f32_16x16x32_bf16 v[52:55], v[176:179], v[192:195], v[52:55]
	v_mfma_f32_16x16x32_bf16 v[48:51], v[184:187], v[192:195], v[48:51]
	v_mfma_f32_16x16x32_bf16 v[48:51], v[180:183], v[188:191], v[48:51]
	v_mfma_f32_16x16x32_bf16 v[32:35], v[180:183], v[196:199], v[32:35]
	v_mfma_f32_16x16x32_bf16 v[32:35], v[184:187], v[200:203], v[32:35]
	v_mfma_f32_16x16x32_bf16 v[36:39], v[176:179], v[200:203], v[36:39]
	v_mfma_f32_16x16x32_bf16 v[36:39], v[172:175], v[196:199], v[36:39]
	v_mfma_f32_16x16x32_bf16 v[40:43], v[164:167], v[196:199], v[40:43]
	v_mfma_f32_16x16x32_bf16 v[40:43], v[168:171], v[200:203], v[40:43]
	v_mfma_f32_16x16x32_bf16 v[44:47], v[160:163], v[200:203], v[44:47]
	v_mfma_f32_16x16x32_bf16 v[44:47], v[156:159], v[196:199], v[44:47]
	s_setprio 0
	s_setprio 1
	v_mfma_f32_16x16x32_bf16 v[28:31], v[156:159], v[208:211], v[28:31]
	v_mfma_f32_16x16x32_bf16 v[28:31], v[160:163], v[212:215], v[28:31]
	v_mfma_f32_16x16x32_bf16 v[24:27], v[168:171], v[212:215], v[24:27]
	v_mfma_f32_16x16x32_bf16 v[24:27], v[164:167], v[208:211], v[24:27]
	v_mfma_f32_16x16x32_bf16 v[20:23], v[172:175], v[208:211], v[20:23]
	v_mfma_f32_16x16x32_bf16 v[20:23], v[176:179], v[212:215], v[20:23]
	v_mfma_f32_16x16x32_bf16 v[16:19], v[184:187], v[212:215], v[16:19]
	v_mfma_f32_16x16x32_bf16 v[16:19], v[180:183], v[208:211], v[16:19]
	v_mfma_f32_16x16x32_bf16 v[0:3], v[180:183], v[216:219], v[0:3]
	v_mfma_f32_16x16x32_bf16 v[0:3], v[184:187], v[220:223], v[0:3]
	v_mfma_f32_16x16x32_bf16 v[4:7], v[176:179], v[220:223], v[4:7]
	v_mfma_f32_16x16x32_bf16 v[4:7], v[172:175], v[216:219], v[4:7]
	v_mfma_f32_16x16x32_bf16 v[8:11], v[164:167], v[216:219], v[8:11]
	v_mfma_f32_16x16x32_bf16 v[8:11], v[168:171], v[220:223], v[8:11]
	v_mfma_f32_16x16x32_bf16 v[12:15], v[160:163], v[220:223], v[12:15]
	v_mfma_f32_16x16x32_bf16 v[12:15], v[156:159], v[216:219], v[12:15]
	s_setprio 0
	s_barrier
	s_add_u32 s47, s47, 0x100
	s_addc_u32 s48, s48, 0
	s_cmp_ge_i32 s49, s36
	s_mov_b64 s[0:1], s[4:5]
	s_mov_b32 s22, s49
	s_cbranch_scc0 .LBB0_834

; #define PG8_STAGE(bufoff, gbase, voff) do { _Pragma("unroll") for (int _i = 0; _i < 2; ++_i) \
;         __builtin_amdgcn_global_load_lds((const unsigned*)((const char*)(gbase) + (voff)[_i]), (LAS unsigned*)(lds + (bufoff) + ldsw + _i * 8192), 16, 0, 0); } while (0)
; #define PG8_LDA(dst, b, h) do { _Pragma("unroll") for (int m = 0; m < 4; ++m) _Pragma("unroll") for (int k = 0; k < 2; ++k) dst[m][k] = *(const LAS bf16x8*)(lds + PG8_SA(b, h) + aoff + m * 2048 + k * 1024); } while (0)
; #define PG8_LDB(dst, b, h) do { _Pragma("unroll") for (int n = 0; n < 2; ++n) _Pragma("unroll") for (int k = 0; k < 2; ++k) dst[n][k] = *(const LAS bf16x8*)(lds + PG8_SB(b, h) + boff + n * 2048 + k * 1024); } while (0)
; #define PG8_MMA(ai, bj, At, Bt) do { __builtin_amdgcn_s_setprio(1); _Pragma("unroll") for (int m = 0; m < 4; ++m) _Pragma("unroll") for (int n = 0; n < 2; ++n) _Pragma("unroll") for (int k = 0; k < 2; ++k) \
;         acc[ai][bj][m][n] = __builtin_amdgcn_mfma_f32_16x16x32_bf16(Bt[n][k], At[m][k], acc[ai][bj][m][n], 0, 0, 0); __builtin_amdgcn_s_setprio(0); } while (0)
; #define PG8_WAIT_V(n) asm volatile("s_waitcnt vmcnt(" #n ")" ::: "memory")
; #define PG8_WAIT_L(n) asm volatile("s_waitcnt lgkmcnt(" #n ")" ::: "memory")
; #define PG8_BAR __builtin_amdgcn_s_barrier()
; #define PG8_SCHED __builtin_amdgcn_sched_barrier(0)
; template <class Epi>
; __device__ __forceinline__ void gemm_phase(LAS unsigned char* lds, const Gemm g, const StaticOrder& S, const Epi& E) {
;     ...
;         for (int t = 0; t < nt; t += 2) {
;             const bool last = (t == nt - 2);
;             const char* a1 = cA + (size_t)(t + 1) * kstep;
;             const char* a2 = last ? nA : cA + (size_t)(t + 2) * kstep; const char* b2 = last ? nB : cB + (size_t)(t + 2) * kstep;
;             const char* a3 = a2 + kstep; const char* b3 = b2 + kstep;
;             PG8_LDB(B0, 0, 0); PG8_LDB(B1, 0, 1); PG8_SCHED; PG8_LDA(At, 0, 0); PG8_STAGE(PG8_SA(1, 1), a1 + hstepA, voffA);
;             PG8_WAIT_V(8); PG8_WAIT_L(0); PG8_BAR; PG8_MMA(0, 0, At, B0); PG8_MMA(0, 1, At, B1); PG8_BAR; PG8_SCHED;
;             PG8_LDA(At, 0, 1); PG8_STAGE(PG8_SB(0, 0), b2, voffB); PG8_STAGE(PG8_SB(0, 1), b2 + hstepB, voffB); PG8_STAGE(PG8_SA(0, 0), a2, voffA);
;             PG8_WAIT_V(8); PG8_WAIT_L(0); PG8_BAR; PG8_MMA(1, 0, At, B0); PG8_MMA(1, 1, At, B1); PG8_BAR; PG8_SCHED;
.LBB0_912:
	ds_read_b128 v[96:99], v230
	ds_read_b128 v[100:103], v230 offset:1024
	ds_read_b128 v[104:107], v230 offset:2048
	ds_read_b128 v[116:119], v230 offset:3072
	ds_read_b128 v[120:123], v231
	ds_read_b128 v[124:127], v231 offset:1024
	ds_read_b128 v[136:139], v231 offset:2048
	ds_read_b128 v[148:151], v231 offset:3072
	s_add_i32 s56, s24, 2
	s_add_u32 s25, s4, 0xfffc0080
	s_addc_u32 s26, s5, -1
	s_cmp_eq_u32 s44, s24
	s_cselect_b32 s24, s53, s54
	s_cselect_b32 s27, s17, s26
	s_cselect_b32 s26, s19, s25
	s_cselect_b32 s25, s33, s55
	v_lshl_add_u64 v[192:193], s[4:5], 0, v[220:221]
	s_add_i32 m0, s31, 0xc000
	ds_read_b128 v[160:163], v232
	ds_read_b128 v[164:167], v232 offset:1024
	ds_read_b128 v[168:171], v232 offset:2048
	ds_read_b128 v[172:175], v232 offset:3072
	ds_read_b128 v[176:179], v232 offset:4096
	ds_read_b128 v[180:183], v232 offset:5120
	ds_read_b128 v[184:187], v232 offset:6144
	ds_read_b128 v[188:191], v232 offset:7168
	global_load_lds_dwordx4 v[192:193], off
	v_lshl_add_u64 v[192:193], s[4:5], 0, v[222:223]
	s_add_i32 m0, s31, 0xe000
	s_nop 0
	global_load_lds_dwordx4 v[192:193], off
	s_waitcnt vmcnt(8)
	s_waitcnt lgkmcnt(0)
	s_barrier
	s_setprio 1
	s_waitcnt lgkmcnt(0)
	v_mfma_f32_16x16x32_bf16 v[156:159], v[96:99], v[160:163], v[156:159]
	v_mfma_f32_16x16x32_bf16 v[156:159], v[100:103], v[164:167], v[156:159]
	v_mfma_f32_16x16x32_bf16 v[152:155], v[116:119], v[164:167], v[152:155]
	v_mfma_f32_16x16x32_bf16 v[152:155], v[104:107], v[160:163], v[152:155]
	v_mfma_f32_16x16x32_bf16 v[144:147], v[120:123], v[160:163], v[144:147]
	v_mfma_f32_16x16x32_bf16 v[144:147], v[124:127], v[164:167], v[144:147]
	v_mfma_f32_16x16x32_bf16 v[140:143], v[148:151], v[164:167], v[140:143]
	v_mfma_f32_16x16x32_bf16 v[140:143], v[136:139], v[160:163], v[140:143]
	v_mfma_f32_16x16x32_bf16 v[108:111], v[136:139], v[168:171], v[108:111]
	v_mfma_f32_16x16x32_bf16 v[108:111], v[148:151], v[172:175], v[108:111]
	v_mfma_f32_16x16x32_bf16 v[112:115], v[124:127], v[172:175], v[112:115]
	v_mfma_f32_16x16x32_bf16 v[112:115], v[120:123], v[168:171], v[112:115]
	v_mfma_f32_16x16x32_bf16 v[128:131], v[104:107], v[168:171], v[128:131]
	v_mfma_f32_16x16x32_bf16 v[128:131], v[116:119], v[172:175], v[128:131]
	v_mfma_f32_16x16x32_bf16 v[132:135], v[100:103], v[172:175], v[132:135]
	v_mfma_f32_16x16x32_bf16 v[132:135], v[96:99], v[168:171], v[132:135]
	s_setprio 0
	s_setprio 1
	v_mfma_f32_16x16x32_bf16 v[92:95], v[96:99], v[176:179], v[92:95]
	v_mfma_f32_16x16x32_bf16 v[92:95], v[100:103], v[180:183], v[92:95]
	v_mfma_f32_16x16x32_bf16 v[88:91], v[116:119], v[180:183], v[88:91]
	v_mfma_f32_16x16x32_bf16 v[88:91], v[104:107], v[176:179], v[88:91]
	v_mfma_f32_16x16x32_bf16 v[84:87], v[120:123], v[176:179], v[84:87]
	v_mfma_f32_16x16x32_bf16 v[84:87], v[124:127], v[180:183], v[84:87]
	v_mfma_f32_16x16x32_bf16 v[80:83], v[148:151], v[180:183], v[80:83]
	v_mfma_f32_16x16x32_bf16 v[80:83], v[136:139], v[176:179], v[80:83]
	v_mfma_f32_16x16x32_bf16 v[64:67], v[136:139], v[184:187], v[64:67]
	v_mfma_f32_16x16x32_bf16 v[64:67], v[148:151], v[188:191], v[64:67]
	v_mfma_f32_16x16x32_bf16 v[68:71], v[124:127], v[188:191], v[68:71]
	v_mfma_f32_16x16x32_bf16 v[68:71], v[120:123], v[184:187], v[68:71]
	v_mfma_f32_16x16x32_bf16 v[72:75], v[104:107], v[184:187], v[72:75]
	v_mfma_f32_16x16x32_bf16 v[72:75], v[116:119], v[188:191], v[72:75]
	v_mfma_f32_16x16x32_bf16 v[76:79], v[100:103], v[188:191], v[76:79]
	v_mfma_f32_16x16x32_bf16 v[76:79], v[96:99], v[184:187], v[76:79]
	s_setprio 0
	s_barrier
	s_add_i32 s57, s47, s30
	v_lshl_add_u64 v[192:193], s[24:25], 0, v[210:211]
	s_mov_b32 m0, s57
	ds_read_b128 v[160:163], v232 offset:16384
	ds_read_b128 v[164:167], v232 offset:17408
	ds_read_b128 v[168:171], v232 offset:18432
	ds_read_b128 v[172:175], v232 offset:19456
	ds_read_b128 v[176:179], v232 offset:20480
	ds_read_b128 v[180:183], v232 offset:21504
	ds_read_b128 v[184:187], v232 offset:22528
	ds_read_b128 v[188:191], v232 offset:23552
	global_load_lds_dwordx4 v[192:193], off
	s_add_i32 m0, s57, 0x2000
	s_add_u32 s58, s24, 0x40000
	v_lshl_add_u64 v[194:195], s[24:25], 0, v[214:215]
	s_addc_u32 s59, s25, 0
	s_add_i32 s57, s48, s30
	global_load_lds_dwordx4 v[194:195], off
	v_lshl_add_u64 v[196:197], s[58:59], 0, v[210:211]
	s_mov_b32 m0, s57
	v_lshl_add_u64 v[198:199], s[26:27], 0, v[212:213]
	global_load_lds_dwordx4 v[196:197], off
	v_lshl_add_u64 v[196:197], s[58:59], 0, v[214:215]
	s_add_i32 m0, s57, 0x2000
	s_nop 0
	global_load_lds_dwordx4 v[196:197], off
	v_lshl_add_u64 v[196:197], s[26:27], 0, v[208:209]
	s_mov_b32 m0, s31
	s_nop 0
	global_load_lds_dwordx4 v[196:197], off
	s_mov_b32 m0, s34
	s_nop 0
	global_load_lds_dwordx4 v[198:199], off
	s_waitcnt vmcnt(8)
	s_waitcnt lgkmcnt(0)
	s_barrier
; #define PG8_STAGE(bufoff, gbase, voff) do { _Pragma("unroll") for (int _i = 0; _i < 2; ++_i) \
;         __builtin_amdgcn_global_load_lds((const unsigned*)((const char*)(gbase) + (voff)[_i]), (LAS unsigned*)(lds + (bufoff) + ldsw + _i * 8192), 16, 0, 0); } while (0)
; #define PG8_LDA(dst, b, h) do { _Pragma("unroll") for (int m = 0; m < 4; ++m) _Pragma("unroll") for (int k = 0; k < 2; ++k) dst[m][k] = *(const LAS bf16x8*)(lds + PG8_SA(b, h) + aoff + m * 2048 + k * 1024); } while (0)
; #define PG8_LDB(dst, b, h) do { _Pragma("unroll") for (int n = 0; n < 2; ++n) _Pragma("unroll") for (int k = 0; k < 2; ++k) dst[n][k] = *(const LAS bf16x8*)(lds + PG8_SB(b, h) + boff + n * 2048 + k * 1024); } while (0)
; #define PG8_MMA(ai, bj, At, Bt) do { __builtin_amdgcn_s_setprio(1); _Pragma("unroll") for (int m = 0; m < 4; ++m) _Pragma("unroll") for (int n = 0; n < 2; ++n) _Pragma("unroll") for (int k = 0; k < 2; ++k) \
;         acc[ai][bj][m][n] = __builtin_amdgcn_mfma_f32_16x16x32_bf16(Bt[n][k], At[m][k], acc[ai][bj][m][n], 0, 0, 0); __builtin_amdgcn_s_setprio(0); } while (0)
; #define PG8_WAIT_V(n) asm volatile("s_waitcnt vmcnt(" #n ")" ::: "memory")
; #define PG8_WAIT_L(n) asm volatile("s_waitcnt lgkmcnt(" #n ")" ::: "memory")
; #define PG8_BAR __builtin_amdgcn_s_barrier()
; #define PG8_SCHED __builtin_amdgcn_sched_barrier(0)
; template <class Epi>
; __device__ __forceinline__ void gemm_phase(LAS unsigned char* lds, const Gemm g, const StaticOrder& S, const Epi& E) {
;     ...
;             PG8_WAIT_V(8); PG8_WAIT_L(0); PG8_BAR; PG8_MMA(1, 0, At, B0); PG8_MMA(1, 1, At, B1); PG8_BAR; PG8_SCHED;
;             PG8_LDB(B0, 1, 0); PG8_LDB(B1, 1, 1); PG8_SCHED; PG8_LDA(At, 1, 0); PG8_STAGE(PG8_SA(0, 1), a2 + hstepA, voffA);
;             PG8_WAIT_V(8); PG8_WAIT_L(0); PG8_BAR; PG8_MMA(0, 0, At, B0); PG8_MMA(0, 1, At, B1); PG8_BAR; PG8_SCHED;
	s_setprio 1
	s_waitcnt lgkmcnt(0)
	v_mfma_f32_16x16x32_bf16 v[60:63], v[96:99], v[160:163], v[60:63]
	v_mfma_f32_16x16x32_bf16 v[60:63], v[100:103], v[164:167], v[60:63]
	v_mfma_f32_16x16x32_bf16 v[56:59], v[116:119], v[164:167], v[56:59]
	v_mfma_f32_16x16x32_bf16 v[56:59], v[104:107], v[160:163], v[56:59]
	v_mfma_f32_16x16x32_bf16 v[52:55], v[120:123], v[160:163], v[52:55]
	v_mfma_f32_16x16x32_bf16 v[52:55], v[124:127], v[164:167], v[52:55]
	v_mfma_f32_16x16x32_bf16 v[48:51], v[148:151], v[164:167], v[48:51]
	v_mfma_f32_16x16x32_bf16 v[48:51], v[136:139], v[160:163], v[48:51]
	v_mfma_f32_16x16x32_bf16 v[32:35], v[136:139], v[168:171], v[32:35]
	v_mfma_f32_16x16x32_bf16 v[32:35], v[148:151], v[172:175], v[32:35]
	v_mfma_f32_16x16x32_bf16 v[36:39], v[124:127], v[172:175], v[36:39]
	v_mfma_f32_16x16x32_bf16 v[36:39], v[120:123], v[168:171], v[36:39]
	v_mfma_f32_16x16x32_bf16 v[40:43], v[104:107], v[168:171], v[40:43]
	v_mfma_f32_16x16x32_bf16 v[40:43], v[116:119], v[172:175], v[40:43]
	v_mfma_f32_16x16x32_bf16 v[44:47], v[100:103], v[172:175], v[44:47]
	v_mfma_f32_16x16x32_bf16 v[44:47], v[96:99], v[168:171], v[44:47]
	s_setprio 0
	s_setprio 1
	v_mfma_f32_16x16x32_bf16 v[28:31], v[96:99], v[176:179], v[28:31]
	v_mfma_f32_16x16x32_bf16 v[28:31], v[100:103], v[180:183], v[28:31]
	v_mfma_f32_16x16x32_bf16 v[24:27], v[116:119], v[180:183], v[24:27]
	v_mfma_f32_16x16x32_bf16 v[24:27], v[104:107], v[176:179], v[24:27]
	v_mfma_f32_16x16x32_bf16 v[20:23], v[120:123], v[176:179], v[20:23]
	v_mfma_f32_16x16x32_bf16 v[20:23], v[124:127], v[180:183], v[20:23]
	v_mfma_f32_16x16x32_bf16 v[16:19], v[148:151], v[180:183], v[16:19]
	v_mfma_f32_16x16x32_bf16 v[16:19], v[136:139], v[176:179], v[16:19]
	v_mfma_f32_16x16x32_bf16 v[0:3], v[136:139], v[184:187], v[0:3]
	v_mfma_f32_16x16x32_bf16 v[0:3], v[148:151], v[188:191], v[0:3]
	v_mfma_f32_16x16x32_bf16 v[4:7], v[124:127], v[188:191], v[4:7]
	v_mfma_f32_16x16x32_bf16 v[4:7], v[120:123], v[184:187], v[4:7]
	v_mfma_f32_16x16x32_bf16 v[8:11], v[104:107], v[184:187], v[8:11]
	v_mfma_f32_16x16x32_bf16 v[8:11], v[116:119], v[188:191], v[8:11]
	v_mfma_f32_16x16x32_bf16 v[12:15], v[100:103], v[188:191], v[12:15]
	v_mfma_f32_16x16x32_bf16 v[12:15], v[96:99], v[184:187], v[12:15]
	s_setprio 0
	s_barrier
	s_add_i32 s57, 0, 0x18000
	s_add_i32 s58, 0, 0x1c000
	v_add_u32_e32 v116, s57, v229
	v_add_u32_e32 v148, s58, v229
	ds_read_b128 v[96:99], v116
	ds_read_b128 v[100:103], v116 offset:1024
	ds_read_b128 v[104:107], v116 offset:2048
	ds_read_b128 v[116:119], v116 offset:3072
	ds_read_b128 v[120:123], v148
	ds_read_b128 v[124:127], v148 offset:1024
	ds_read_b128 v[136:139], v148 offset:2048
	ds_read_b128 v[148:151], v148 offset:3072
	s_add_u32 s26, s26, 0x40000
	s_addc_u32 s27, s27, 0
	s_mov_b32 m0, s35
	v_lshl_add_u64 v[200:201], s[26:27], 0, v[208:209]
	ds_read_b128 v[160:163], v232 offset:32768
	ds_read_b128 v[164:167], v232 offset:33792
	ds_read_b128 v[168:171], v232 offset:34816
	ds_read_b128 v[172:175], v232 offset:35840
	ds_read_b128 v[176:179], v232 offset:36864
	ds_read_b128 v[180:183], v232 offset:37888
	ds_read_b128 v[184:187], v232 offset:38912
	ds_read_b128 v[188:191], v232 offset:39936
	global_load_lds_dwordx4 v[200:201], off
	v_lshl_add_u64 v[200:201], s[26:27], 0, v[212:213]
	s_mov_b32 m0, s36
	s_nop 0
	global_load_lds_dwordx4 v[200:201], off
	s_waitcnt vmcnt(8)
	s_waitcnt lgkmcnt(0)
	s_barrier
	s_setprio 1
	s_waitcnt lgkmcnt(0)
	v_mfma_f32_16x16x32_bf16 v[156:159], v[96:99], v[160:163], v[156:159]
	v_mfma_f32_16x16x32_bf16 v[156:159], v[100:103], v[164:167], v[156:159]
	v_mfma_f32_16x16x32_bf16 v[152:155], v[116:119], v[164:167], v[152:155]
	v_mfma_f32_16x16x32_bf16 v[152:155], v[104:107], v[160:163], v[152:155]
	v_mfma_f32_16x16x32_bf16 v[144:147], v[120:123], v[160:163], v[144:147]
	v_mfma_f32_16x16x32_bf16 v[144:147], v[124:127], v[164:167], v[144:147]
	v_mfma_f32_16x16x32_bf16 v[140:143], v[148:151], v[164:167], v[140:143]
	v_mfma_f32_16x16x32_bf16 v[140:143], v[136:139], v[160:163], v[140:143]
	v_mfma_f32_16x16x32_bf16 v[108:111], v[136:139], v[168:171], v[108:111]
	v_mfma_f32_16x16x32_bf16 v[108:111], v[148:151], v[172:175], v[108:111]
	v_mfma_f32_16x16x32_bf16 v[112:115], v[124:127], v[172:175], v[112:115]
	v_mfma_f32_16x16x32_bf16 v[112:115], v[120:123], v[168:171], v[112:115]
	v_mfma_f32_16x16x32_bf16 v[128:131], v[104:107], v[168:171], v[128:131]
	v_mfma_f32_16x16x32_bf16 v[128:131], v[116:119], v[172:175], v[128:131]
	v_mfma_f32_16x16x32_bf16 v[132:135], v[100:103], v[172:175], v[132:135]
	v_mfma_f32_16x16x32_bf16 v[132:135], v[96:99], v[168:171], v[132:135]
	s_setprio 0
	s_setprio 1
	v_mfma_f32_16x16x32_bf16 v[92:95], v[96:99], v[176:179], v[92:95]
	v_mfma_f32_16x16x32_bf16 v[92:95], v[100:103], v[180:183], v[92:95]
	v_mfma_f32_16x16x32_bf16 v[88:91], v[116:119], v[180:183], v[88:91]
	v_mfma_f32_16x16x32_bf16 v[88:91], v[104:107], v[176:179], v[88:91]
	v_mfma_f32_16x16x32_bf16 v[84:87], v[120:123], v[176:179], v[84:87]
	v_mfma_f32_16x16x32_bf16 v[84:87], v[124:127], v[180:183], v[84:87]
	v_mfma_f32_16x16x32_bf16 v[80:83], v[148:151], v[180:183], v[80:83]
	v_mfma_f32_16x16x32_bf16 v[80:83], v[136:139], v[176:179], v[80:83]
	v_mfma_f32_16x16x32_bf16 v[64:67], v[136:139], v[184:187], v[64:67]
	v_mfma_f32_16x16x32_bf16 v[64:67], v[148:151], v[188:191], v[64:67]
	v_mfma_f32_16x16x32_bf16 v[68:71], v[124:127], v[188:191], v[68:71]
	v_mfma_f32_16x16x32_bf16 v[68:71], v[120:123], v[184:187], v[68:71]
	v_mfma_f32_16x16x32_bf16 v[72:75], v[104:107], v[184:187], v[72:75]
	v_mfma_f32_16x16x32_bf16 v[72:75], v[116:119], v[188:191], v[72:75]
	v_mfma_f32_16x16x32_bf16 v[76:79], v[100:103], v[188:191], v[76:79]
	v_mfma_f32_16x16x32_bf16 v[76:79], v[96:99], v[184:187], v[76:79]
	s_setprio 0
	s_barrier
; #define PG8_STAGE(bufoff, gbase, voff) do { _Pragma("unroll") for (int _i = 0; _i < 2; ++_i) \
;         __builtin_amdgcn_global_load_lds((const unsigned*)((const char*)(gbase) + (voff)[_i]), (LAS unsigned*)(lds + (bufoff) + ldsw + _i * 8192), 16, 0, 0); } while (0)
; #define PG8_LDA(dst, b, h) do { _Pragma("unroll") for (int m = 0; m < 4; ++m) _Pragma("unroll") for (int k = 0; k < 2; ++k) dst[m][k] = *(const LAS bf16x8*)(lds + PG8_SA(b, h) + aoff + m * 2048 + k * 1024); } while (0)
; #define PG8_MMA(ai, bj, At, Bt) do { __builtin_amdgcn_s_setprio(1); _Pragma("unroll") for (int m = 0; m < 4; ++m) _Pragma("unroll") for (int n = 0; n < 2; ++n) _Pragma("unroll") for (int k = 0; k < 2; ++k) \
;         acc[ai][bj][m][n] = __builtin_amdgcn_mfma_f32_16x16x32_bf16(Bt[n][k], At[m][k], acc[ai][bj][m][n], 0, 0, 0); __builtin_amdgcn_s_setprio(0); } while (0)
; #define PG8_WAIT_V(n) asm volatile("s_waitcnt vmcnt(" #n ")" ::: "memory")
; #define PG8_WAIT_L(n) asm volatile("s_waitcnt lgkmcnt(" #n ")" ::: "memory")
; #define PG8_BAR __builtin_amdgcn_s_barrier()
; #define PG8_SCHED __builtin_amdgcn_sched_barrier(0)
; template <class Epi>
; __device__ __forceinline__ void gemm_phase(LAS unsigned char* lds, const Gemm g, const StaticOrder& S, const Epi& E) {
;     ...
;             PG8_LDA(At, 1, 1); PG8_STAGE(PG8_SB(1, 0), b3, voffB); PG8_STAGE(PG8_SB(1, 1), b3 + hstepB, voffB); PG8_STAGE(PG8_SA(1, 0), a3, voffA);
;             PG8_WAIT_V(8); PG8_WAIT_L(0); PG8_BAR; PG8_MMA(1, 0, At, B0); PG8_MMA(1, 1, At, B1); PG8_BAR; PG8_SCHED;
	s_add_i32 s26, s57, s30
	v_lshl_add_u64 v[192:193], v[192:193], 0, s[10:11]
	s_mov_b32 m0, s26
	ds_read_b128 v[160:163], v232 offset:49152
	ds_read_b128 v[164:167], v232 offset:50176
	ds_read_b128 v[168:171], v232 offset:51200
	ds_read_b128 v[172:175], v232 offset:52224
	ds_read_b128 v[176:179], v232 offset:53248
	ds_read_b128 v[180:183], v232 offset:54272
	ds_read_b128 v[184:187], v232 offset:55296
	ds_read_b128 v[188:191], v232 offset:56320
	global_load_lds_dwordx4 v[192:193], off
	s_add_i32 m0, s26, 0x2000
	s_add_u32 s24, s24, 0x40080
	v_lshl_add_u64 v[192:193], v[194:195], 0, s[10:11]
	s_addc_u32 s25, s25, 0
	s_add_i32 s26, s58, s30
	global_load_lds_dwordx4 v[192:193], off
	v_lshl_add_u64 v[192:193], s[24:25], 0, v[210:211]
	s_mov_b32 m0, s26
	s_nop 0
	global_load_lds_dwordx4 v[192:193], off
	v_lshl_add_u64 v[192:193], s[24:25], 0, v[214:215]
	s_add_i32 m0, s26, 0x2000
	s_nop 0
	global_load_lds_dwordx4 v[192:193], off
	v_lshl_add_u64 v[192:193], v[196:197], 0, s[10:11]
	s_mov_b32 m0, s40
	s_nop 0
	global_load_lds_dwordx4 v[192:193], off
	v_lshl_add_u64 v[192:193], v[198:199], 0, s[10:11]
	s_mov_b32 m0, s41
	s_nop 0
	global_load_lds_dwordx4 v[192:193], off
	s_waitcnt vmcnt(8)
	s_waitcnt lgkmcnt(0)
	s_barrier
	s_setprio 1
	s_waitcnt lgkmcnt(0)
	v_mfma_f32_16x16x32_bf16 v[60:63], v[96:99], v[160:163], v[60:63]
	v_mfma_f32_16x16x32_bf16 v[60:63], v[100:103], v[164:167], v[60:63]
	v_mfma_f32_16x16x32_bf16 v[56:59], v[116:119], v[164:167], v[56:59]
	v_mfma_f32_16x16x32_bf16 v[56:59], v[104:107], v[160:163], v[56:59]
	v_mfma_f32_16x16x32_bf16 v[52:55], v[120:123], v[160:163], v[52:55]
	v_mfma_f32_16x16x32_bf16 v[52:55], v[124:127], v[164:167], v[52:55]
	v_mfma_f32_16x16x32_bf16 v[48:51], v[148:151], v[164:167], v[48:51]
	v_mfma_f32_16x16x32_bf16 v[48:51], v[136:139], v[160:163], v[48:51]
	v_mfma_f32_16x16x32_bf16 v[32:35], v[136:139], v[168:171], v[32:35]
	v_mfma_f32_16x16x32_bf16 v[32:35], v[148:151], v[172:175], v[32:35]
	v_mfma_f32_16x16x32_bf16 v[36:39], v[124:127], v[172:175], v[36:39]
	v_mfma_f32_16x16x32_bf16 v[36:39], v[120:123], v[168:171], v[36:39]
	v_mfma_f32_16x16x32_bf16 v[40:43], v[104:107], v[168:171], v[40:43]
	v_mfma_f32_16x16x32_bf16 v[40:43], v[116:119], v[172:175], v[40:43]
	v_mfma_f32_16x16x32_bf16 v[44:47], v[100:103], v[172:175], v[44:47]
	v_mfma_f32_16x16x32_bf16 v[44:47], v[96:99], v[168:171], v[44:47]
	s_setprio 0
	s_setprio 1
	v_mfma_f32_16x16x32_bf16 v[28:31], v[96:99], v[176:179], v[28:31]
	v_mfma_f32_16x16x32_bf16 v[28:31], v[100:103], v[180:183], v[28:31]
	v_mfma_f32_16x16x32_bf16 v[24:27], v[116:119], v[180:183], v[24:27]
	v_mfma_f32_16x16x32_bf16 v[24:27], v[104:107], v[176:179], v[24:27]
	v_mfma_f32_16x16x32_bf16 v[20:23], v[120:123], v[176:179], v[20:23]
	v_mfma_f32_16x16x32_bf16 v[20:23], v[124:127], v[180:183], v[20:23]
	v_mfma_f32_16x16x32_bf16 v[16:19], v[148:151], v[180:183], v[16:19]
	v_mfma_f32_16x16x32_bf16 v[16:19], v[136:139], v[176:179], v[16:19]
	v_mfma_f32_16x16x32_bf16 v[0:3], v[136:139], v[184:187], v[0:3]
	v_mfma_f32_16x16x32_bf16 v[0:3], v[148:151], v[188:191], v[0:3]
	v_mfma_f32_16x16x32_bf16 v[4:7], v[124:127], v[188:191], v[4:7]
	v_mfma_f32_16x16x32_bf16 v[4:7], v[120:123], v[184:187], v[4:7]
	v_mfma_f32_16x16x32_bf16 v[8:11], v[104:107], v[184:187], v[8:11]
	v_mfma_f32_16x16x32_bf16 v[8:11], v[116:119], v[188:191], v[8:11]
	v_mfma_f32_16x16x32_bf16 v[12:15], v[100:103], v[188:191], v[12:15]
	v_mfma_f32_16x16x32_bf16 v[12:15], v[96:99], v[184:187], v[12:15]
	s_setprio 0
	s_barrier
	s_add_u32 s4, s4, 0x100
	s_addc_u32 s5, s5, 0
	s_add_u32 s54, s54, 0x100
	s_addc_u32 s55, s55, 0
	s_cmp_ge_i32 s56, s39
	s_mov_b32 s24, s56
	s_cbranch_scc0 .LBB0_912

; #define PG8_STAGE(bufoff, gbase, voff) do { _Pragma("unroll") for (int _i = 0; _i < 2; ++_i) \
;         __builtin_amdgcn_global_load_lds((const unsigned*)((const char*)(gbase) + (voff)[_i]), (LAS unsigned*)(lds + (bufoff) + ldsw + _i * 8192), 16, 0, 0); } while (0)
; #define PG8_LDA(dst, b, h) do { _Pragma("unroll") for (int m = 0; m < 4; ++m) _Pragma("unroll") for (int k = 0; k < 2; ++k) dst[m][k] = *(const LAS bf16x8*)(lds + PG8_SA(b, h) + aoff + m * 2048 + k * 1024); } while (0)
; #define PG8_LDB(dst, b, h) do { _Pragma("unroll") for (int n = 0; n < 2; ++n) _Pragma("unroll") for (int k = 0; k < 2; ++k) dst[n][k] = *(const LAS bf16x8*)(lds + PG8_SB(b, h) + boff + n * 2048 + k * 1024); } while (0)
; #define PG8_MMA(ai, bj, At, Bt) do { __builtin_amdgcn_s_setprio(1); _Pragma("unroll") for (int m = 0; m < 4; ++m) _Pragma("unroll") for (int n = 0; n < 2; ++n) _Pragma("unroll") for (int k = 0; k < 2; ++k) \
;         acc[ai][bj][m][n] = __builtin_amdgcn_mfma_f32_16x16x32_bf16(Bt[n][k], At[m][k], acc[ai][bj][m][n], 0, 0, 0); __builtin_amdgcn_s_setprio(0); } while (0)
; #define PG8_WAIT_V(n) asm volatile("s_waitcnt vmcnt(" #n ")" ::: "memory")
; #define PG8_WAIT_L(n) asm volatile("s_waitcnt lgkmcnt(" #n ")" ::: "memory")
; #define PG8_BAR __builtin_amdgcn_s_barrier()
; #define PG8_SCHED __builtin_amdgcn_sched_barrier(0)
; template <class Epi>
; __device__ __forceinline__ void gemm_phase(LAS unsigned char* lds, const Gemm g, const StaticOrder& S, const Epi& E) {
;     ...
;         for (int t = 0; t < nt; t += 2) {
;             const bool last = (t == nt - 2);
;             const char* a1 = cA + (size_t)(t + 1) * kstep;
;             const char* a2 = last ? nA : cA + (size_t)(t + 2) * kstep; const char* b2 = last ? nB : cB + (size_t)(t + 2) * kstep;
;             const char* a3 = a2 + kstep; const char* b3 = b2 + kstep;
;             PG8_LDB(B0, 0, 0); PG8_LDB(B1, 0, 1); PG8_SCHED; PG8_LDA(At, 0, 0); PG8_STAGE(PG8_SA(1, 1), a1 + hstepA, voffA);
;             PG8_WAIT_V(8); PG8_WAIT_L(0); PG8_BAR; PG8_MMA(0, 0, At, B0); PG8_MMA(0, 1, At, B1); PG8_BAR; PG8_SCHED;
;             PG8_LDA(At, 0, 1); PG8_STAGE(PG8_SB(0, 0), b2, voffB); PG8_STAGE(PG8_SB(0, 1), b2 + hstepB, voffB); PG8_STAGE(PG8_SA(0, 0), a2, voffA);
;             PG8_WAIT_V(8); PG8_WAIT_L(0); PG8_BAR; PG8_MMA(1, 0, At, B0); PG8_MMA(1, 1, At, B1); PG8_BAR; PG8_SCHED;
.LBB0_1046:
	ds_read_b128 v[128:131], v185
	ds_read_b128 v[132:135], v185 offset:1024
	ds_read_b128 v[136:139], v185 offset:2048
	ds_read_b128 v[140:143], v185 offset:3072
	ds_read_b128 v[144:147], v186
	ds_read_b128 v[148:151], v186 offset:1024
	ds_read_b128 v[152:155], v186 offset:2048
	ds_read_b128 v[156:159], v186 offset:3072
	s_add_i32 s73, s46, 2
	s_add_u32 s47, s12, 0xfff80080
	s_addc_u32 s48, s13, -1
	s_cmp_eq_u32 s62, s46
	s_cselect_b32 s46, s41, s71
	s_cselect_b32 s49, s1, s48
	s_cselect_b32 s48, s33, s47
	s_cselect_b32 s47, s39, s72
	v_lshl_add_u64 v[182:183], s[12:13], 0, v[174:175]
	s_add_i32 m0, s5, 0xc000
	ds_read_b128 v[190:193], v187
	ds_read_b128 v[194:197], v187 offset:1024
	ds_read_b128 v[198:201], v187 offset:2048
	ds_read_b128 v[208:211], v187 offset:3072
	ds_read_b128 v[212:215], v187 offset:4096
	ds_read_b128 v[216:219], v187 offset:5120
	ds_read_b128 v[220:223], v187 offset:6144
	ds_read_b128 v[224:227], v187 offset:7168
	global_load_lds_dwordx4 v[182:183], off
	v_lshl_add_u64 v[182:183], s[12:13], 0, v[176:177]
	s_add_i32 m0, s5, 0xe000
	s_nop 0
	global_load_lds_dwordx4 v[182:183], off
	s_waitcnt vmcnt(8)
	s_waitcnt lgkmcnt(0)
	s_barrier
	s_setprio 1
	s_waitcnt lgkmcnt(0)
	v_mfma_f32_16x16x32_bf16 v[120:123], v[128:131], v[190:193], v[120:123]
	v_mfma_f32_16x16x32_bf16 v[120:123], v[132:135], v[194:197], v[120:123]
	v_mfma_f32_16x16x32_bf16 v[124:127], v[140:143], v[194:197], v[124:127]
	v_mfma_f32_16x16x32_bf16 v[124:127], v[136:139], v[190:193], v[124:127]
	v_mfma_f32_16x16x32_bf16 v[116:119], v[144:147], v[190:193], v[116:119]
	v_mfma_f32_16x16x32_bf16 v[116:119], v[148:151], v[194:197], v[116:119]
	v_mfma_f32_16x16x32_bf16 v[112:115], v[156:159], v[194:197], v[112:115]
	v_mfma_f32_16x16x32_bf16 v[112:115], v[152:155], v[190:193], v[112:115]
	v_mfma_f32_16x16x32_bf16 v[96:99], v[152:155], v[198:201], v[96:99]
	v_mfma_f32_16x16x32_bf16 v[96:99], v[156:159], v[208:211], v[96:99]
	v_mfma_f32_16x16x32_bf16 v[100:103], v[148:151], v[208:211], v[100:103]
	v_mfma_f32_16x16x32_bf16 v[100:103], v[144:147], v[198:201], v[100:103]
	v_mfma_f32_16x16x32_bf16 v[104:107], v[136:139], v[198:201], v[104:107]
	v_mfma_f32_16x16x32_bf16 v[104:107], v[140:143], v[208:211], v[104:107]
	v_mfma_f32_16x16x32_bf16 v[108:111], v[132:135], v[208:211], v[108:111]
	v_mfma_f32_16x16x32_bf16 v[108:111], v[128:131], v[198:201], v[108:111]
	s_setprio 0
	s_setprio 1
	v_mfma_f32_16x16x32_bf16 v[92:95], v[128:131], v[212:215], v[92:95]
	v_mfma_f32_16x16x32_bf16 v[92:95], v[132:135], v[216:219], v[92:95]
	v_mfma_f32_16x16x32_bf16 v[88:91], v[140:143], v[216:219], v[88:91]
	v_mfma_f32_16x16x32_bf16 v[88:91], v[136:139], v[212:215], v[88:91]
	v_mfma_f32_16x16x32_bf16 v[84:87], v[144:147], v[212:215], v[84:87]
	v_mfma_f32_16x16x32_bf16 v[84:87], v[148:151], v[216:219], v[84:87]
	v_mfma_f32_16x16x32_bf16 v[80:83], v[156:159], v[216:219], v[80:83]
	v_mfma_f32_16x16x32_bf16 v[80:83], v[152:155], v[212:215], v[80:83]
	v_mfma_f32_16x16x32_bf16 v[64:67], v[152:155], v[220:223], v[64:67]
	v_mfma_f32_16x16x32_bf16 v[64:67], v[156:159], v[224:227], v[64:67]
	v_mfma_f32_16x16x32_bf16 v[68:71], v[148:151], v[224:227], v[68:71]
	v_mfma_f32_16x16x32_bf16 v[68:71], v[144:147], v[220:223], v[68:71]
	v_mfma_f32_16x16x32_bf16 v[72:75], v[136:139], v[220:223], v[72:75]
	v_mfma_f32_16x16x32_bf16 v[72:75], v[140:143], v[224:227], v[72:75]
	v_mfma_f32_16x16x32_bf16 v[76:79], v[132:135], v[224:227], v[76:79]
	v_mfma_f32_16x16x32_bf16 v[76:79], v[128:131], v[220:223], v[76:79]
	s_setprio 0
	s_barrier
	s_add_i32 s76, s65, s54
	v_lshl_add_u64 v[182:183], s[46:47], 0, v[162:163]
	s_mov_b32 m0, s76
	ds_read_b128 v[190:193], v187 offset:16384
	ds_read_b128 v[194:197], v187 offset:17408
	ds_read_b128 v[198:201], v187 offset:18432
	ds_read_b128 v[208:211], v187 offset:19456
	ds_read_b128 v[212:215], v187 offset:20480
	ds_read_b128 v[216:219], v187 offset:21504
	ds_read_b128 v[220:223], v187 offset:22528
	ds_read_b128 v[224:227], v187 offset:23552
	global_load_lds_dwordx4 v[182:183], off
	s_add_i32 m0, s76, 0x2000
	s_add_u32 s76, s46, 0x80000
	v_lshl_add_u64 v[202:203], s[46:47], 0, v[166:167]
	s_addc_u32 s77, s47, 0
	s_add_i32 s78, s66, s54
	global_load_lds_dwordx4 v[202:203], off
	v_lshl_add_u64 v[230:231], s[76:77], 0, v[162:163]
	s_mov_b32 m0, s78
	v_lshl_add_u64 v[232:233], s[48:49], 0, v[164:165]
	global_load_lds_dwordx4 v[230:231], off
	v_lshl_add_u64 v[230:231], s[76:77], 0, v[166:167]
	s_add_i32 m0, s78, 0x2000
	s_nop 0
	global_load_lds_dwordx4 v[230:231], off
	v_lshl_add_u64 v[230:231], s[48:49], 0, v[160:161]
	s_mov_b32 m0, s5
	s_nop 0
	global_load_lds_dwordx4 v[230:231], off
	s_mov_b32 m0, s55
	s_nop 0
	global_load_lds_dwordx4 v[232:233], off
	s_waitcnt vmcnt(8)
	s_waitcnt lgkmcnt(0)
	s_barrier
; #define PG8_STAGE(bufoff, gbase, voff) do { _Pragma("unroll") for (int _i = 0; _i < 2; ++_i) \
;         __builtin_amdgcn_global_load_lds((const unsigned*)((const char*)(gbase) + (voff)[_i]), (LAS unsigned*)(lds + (bufoff) + ldsw + _i * 8192), 16, 0, 0); } while (0)
; #define PG8_LDA(dst, b, h) do { _Pragma("unroll") for (int m = 0; m < 4; ++m) _Pragma("unroll") for (int k = 0; k < 2; ++k) dst[m][k] = *(const LAS bf16x8*)(lds + PG8_SA(b, h) + aoff + m * 2048 + k * 1024); } while (0)
; #define PG8_LDB(dst, b, h) do { _Pragma("unroll") for (int n = 0; n < 2; ++n) _Pragma("unroll") for (int k = 0; k < 2; ++k) dst[n][k] = *(const LAS bf16x8*)(lds + PG8_SB(b, h) + boff + n * 2048 + k * 1024); } while (0)
; #define PG8_MMA(ai, bj, At, Bt) do { __builtin_amdgcn_s_setprio(1); _Pragma("unroll") for (int m = 0; m < 4; ++m) _Pragma("unroll") for (int n = 0; n < 2; ++n) _Pragma("unroll") for (int k = 0; k < 2; ++k) \
;         acc[ai][bj][m][n] = __builtin_amdgcn_mfma_f32_16x16x32_bf16(Bt[n][k], At[m][k], acc[ai][bj][m][n], 0, 0, 0); __builtin_amdgcn_s_setprio(0); } while (0)
; #define PG8_WAIT_V(n) asm volatile("s_waitcnt vmcnt(" #n ")" ::: "memory")
; #define PG8_WAIT_L(n) asm volatile("s_waitcnt lgkmcnt(" #n ")" ::: "memory")
; #define PG8_BAR __builtin_amdgcn_s_barrier()
; #define PG8_SCHED __builtin_amdgcn_sched_barrier(0)
; template <class Epi>
; __device__ __forceinline__ void gemm_phase(LAS unsigned char* lds, const Gemm g, const StaticOrder& S, const Epi& E) {
;     ...
;             PG8_WAIT_V(8); PG8_WAIT_L(0); PG8_BAR; PG8_MMA(1, 0, At, B0); PG8_MMA(1, 1, At, B1); PG8_BAR; PG8_SCHED;
;             PG8_LDB(B0, 1, 0); PG8_LDB(B1, 1, 1); PG8_SCHED; PG8_LDA(At, 1, 0); PG8_STAGE(PG8_SA(0, 1), a2 + hstepA, voffA);
;             PG8_WAIT_V(8); PG8_WAIT_L(0); PG8_BAR; PG8_MMA(0, 0, At, B0); PG8_MMA(0, 1, At, B1); PG8_BAR; PG8_SCHED;
	s_setprio 1
	s_waitcnt lgkmcnt(0)
	v_mfma_f32_16x16x32_bf16 v[60:63], v[128:131], v[190:193], v[60:63]
	v_mfma_f32_16x16x32_bf16 v[60:63], v[132:135], v[194:197], v[60:63]
	v_mfma_f32_16x16x32_bf16 v[56:59], v[140:143], v[194:197], v[56:59]
	v_mfma_f32_16x16x32_bf16 v[56:59], v[136:139], v[190:193], v[56:59]
	v_mfma_f32_16x16x32_bf16 v[52:55], v[144:147], v[190:193], v[52:55]
	v_mfma_f32_16x16x32_bf16 v[52:55], v[148:151], v[194:197], v[52:55]
	v_mfma_f32_16x16x32_bf16 v[48:51], v[156:159], v[194:197], v[48:51]
	v_mfma_f32_16x16x32_bf16 v[48:51], v[152:155], v[190:193], v[48:51]
	v_mfma_f32_16x16x32_bf16 v[32:35], v[152:155], v[198:201], v[32:35]
	v_mfma_f32_16x16x32_bf16 v[32:35], v[156:159], v[208:211], v[32:35]
	v_mfma_f32_16x16x32_bf16 v[36:39], v[148:151], v[208:211], v[36:39]
	v_mfma_f32_16x16x32_bf16 v[36:39], v[144:147], v[198:201], v[36:39]
	v_mfma_f32_16x16x32_bf16 v[40:43], v[136:139], v[198:201], v[40:43]
	v_mfma_f32_16x16x32_bf16 v[40:43], v[140:143], v[208:211], v[40:43]
	v_mfma_f32_16x16x32_bf16 v[44:47], v[132:135], v[208:211], v[44:47]
	v_mfma_f32_16x16x32_bf16 v[44:47], v[128:131], v[198:201], v[44:47]
	s_setprio 0
	s_setprio 1
	v_mfma_f32_16x16x32_bf16 v[28:31], v[128:131], v[212:215], v[28:31]
	v_mfma_f32_16x16x32_bf16 v[28:31], v[132:135], v[216:219], v[28:31]
	v_mfma_f32_16x16x32_bf16 v[24:27], v[140:143], v[216:219], v[24:27]
	v_mfma_f32_16x16x32_bf16 v[24:27], v[136:139], v[212:215], v[24:27]
	v_mfma_f32_16x16x32_bf16 v[20:23], v[144:147], v[212:215], v[20:23]
	v_mfma_f32_16x16x32_bf16 v[20:23], v[148:151], v[216:219], v[20:23]
	v_mfma_f32_16x16x32_bf16 v[16:19], v[156:159], v[216:219], v[16:19]
	v_mfma_f32_16x16x32_bf16 v[16:19], v[152:155], v[212:215], v[16:19]
	v_mfma_f32_16x16x32_bf16 v[0:3], v[152:155], v[220:223], v[0:3]
	v_mfma_f32_16x16x32_bf16 v[0:3], v[156:159], v[224:227], v[0:3]
	v_mfma_f32_16x16x32_bf16 v[4:7], v[148:151], v[224:227], v[4:7]
	v_mfma_f32_16x16x32_bf16 v[4:7], v[144:147], v[220:223], v[4:7]
	v_mfma_f32_16x16x32_bf16 v[8:11], v[136:139], v[220:223], v[8:11]
	v_mfma_f32_16x16x32_bf16 v[8:11], v[140:143], v[224:227], v[8:11]
	v_mfma_f32_16x16x32_bf16 v[12:15], v[132:135], v[224:227], v[12:15]
	v_mfma_f32_16x16x32_bf16 v[12:15], v[128:131], v[220:223], v[12:15]
	s_setprio 0
	s_barrier
	s_add_i32 s76, 0, 0x18000
	s_add_i32 s77, 0, 0x1c000
	v_add_u32_e32 v140, s76, v184
	v_add_u32_e32 v156, s77, v184
	ds_read_b128 v[128:131], v140
	ds_read_b128 v[132:135], v140 offset:1024
	ds_read_b128 v[136:139], v140 offset:2048
	ds_read_b128 v[140:143], v140 offset:3072
	ds_read_b128 v[144:147], v156
	ds_read_b128 v[148:151], v156 offset:1024
	ds_read_b128 v[152:155], v156 offset:2048
	ds_read_b128 v[156:159], v156 offset:3072
	s_add_u32 s48, s48, 0x80000
	s_addc_u32 s49, s49, 0
	s_mov_b32 m0, s56
	v_lshl_add_u64 v[234:235], s[48:49], 0, v[160:161]
	ds_read_b128 v[190:193], v187 offset:32768
	ds_read_b128 v[194:197], v187 offset:33792
	ds_read_b128 v[198:201], v187 offset:34816
	ds_read_b128 v[208:211], v187 offset:35840
	ds_read_b128 v[212:215], v187 offset:36864
	ds_read_b128 v[216:219], v187 offset:37888
	ds_read_b128 v[220:223], v187 offset:38912
	ds_read_b128 v[224:227], v187 offset:39936
	global_load_lds_dwordx4 v[234:235], off
	v_lshl_add_u64 v[234:235], s[48:49], 0, v[164:165]
	s_mov_b32 m0, s57
	s_nop 0
	global_load_lds_dwordx4 v[234:235], off
	s_waitcnt vmcnt(8)
	s_waitcnt lgkmcnt(0)
	s_barrier
	s_setprio 1
	s_waitcnt lgkmcnt(0)
	v_mfma_f32_16x16x32_bf16 v[120:123], v[128:131], v[190:193], v[120:123]
	v_mfma_f32_16x16x32_bf16 v[120:123], v[132:135], v[194:197], v[120:123]
	v_mfma_f32_16x16x32_bf16 v[124:127], v[140:143], v[194:197], v[124:127]
	v_mfma_f32_16x16x32_bf16 v[124:127], v[136:139], v[190:193], v[124:127]
	v_mfma_f32_16x16x32_bf16 v[116:119], v[144:147], v[190:193], v[116:119]
	v_mfma_f32_16x16x32_bf16 v[116:119], v[148:151], v[194:197], v[116:119]
	v_mfma_f32_16x16x32_bf16 v[112:115], v[156:159], v[194:197], v[112:115]
	v_mfma_f32_16x16x32_bf16 v[112:115], v[152:155], v[190:193], v[112:115]
	v_mfma_f32_16x16x32_bf16 v[96:99], v[152:155], v[198:201], v[96:99]
	v_mfma_f32_16x16x32_bf16 v[96:99], v[156:159], v[208:211], v[96:99]
	v_mfma_f32_16x16x32_bf16 v[100:103], v[148:151], v[208:211], v[100:103]
	v_mfma_f32_16x16x32_bf16 v[100:103], v[144:147], v[198:201], v[100:103]
	v_mfma_f32_16x16x32_bf16 v[104:107], v[136:139], v[198:201], v[104:107]
	v_mfma_f32_16x16x32_bf16 v[104:107], v[140:143], v[208:211], v[104:107]
	v_mfma_f32_16x16x32_bf16 v[108:111], v[132:135], v[208:211], v[108:111]
	v_mfma_f32_16x16x32_bf16 v[108:111], v[128:131], v[198:201], v[108:111]
	s_setprio 0
	s_setprio 1
	v_mfma_f32_16x16x32_bf16 v[92:95], v[128:131], v[212:215], v[92:95]
	v_mfma_f32_16x16x32_bf16 v[92:95], v[132:135], v[216:219], v[92:95]
	v_mfma_f32_16x16x32_bf16 v[88:91], v[140:143], v[216:219], v[88:91]
	v_mfma_f32_16x16x32_bf16 v[88:91], v[136:139], v[212:215], v[88:91]
	v_mfma_f32_16x16x32_bf16 v[84:87], v[144:147], v[212:215], v[84:87]
	v_mfma_f32_16x16x32_bf16 v[84:87], v[148:151], v[216:219], v[84:87]
	v_mfma_f32_16x16x32_bf16 v[80:83], v[156:159], v[216:219], v[80:83]
	v_mfma_f32_16x16x32_bf16 v[80:83], v[152:155], v[212:215], v[80:83]
	v_mfma_f32_16x16x32_bf16 v[64:67], v[152:155], v[220:223], v[64:67]
	v_mfma_f32_16x16x32_bf16 v[64:67], v[156:159], v[224:227], v[64:67]
	v_mfma_f32_16x16x32_bf16 v[68:71], v[148:151], v[224:227], v[68:71]
	v_mfma_f32_16x16x32_bf16 v[68:71], v[144:147], v[220:223], v[68:71]
	v_mfma_f32_16x16x32_bf16 v[72:75], v[136:139], v[220:223], v[72:75]
	v_mfma_f32_16x16x32_bf16 v[72:75], v[140:143], v[224:227], v[72:75]
	v_mfma_f32_16x16x32_bf16 v[76:79], v[132:135], v[224:227], v[76:79]
	v_mfma_f32_16x16x32_bf16 v[76:79], v[128:131], v[220:223], v[76:79]
	s_setprio 0
	s_barrier
; #define PG8_STAGE(bufoff, gbase, voff) do { _Pragma("unroll") for (int _i = 0; _i < 2; ++_i) \
;         __builtin_amdgcn_global_load_lds((const unsigned*)((const char*)(gbase) + (voff)[_i]), (LAS unsigned*)(lds + (bufoff) + ldsw + _i * 8192), 16, 0, 0); } while (0)
; #define PG8_LDA(dst, b, h) do { _Pragma("unroll") for (int m = 0; m < 4; ++m) _Pragma("unroll") for (int k = 0; k < 2; ++k) dst[m][k] = *(const LAS bf16x8*)(lds + PG8_SA(b, h) + aoff + m * 2048 + k * 1024); } while (0)
; #define PG8_MMA(ai, bj, At, Bt) do { __builtin_amdgcn_s_setprio(1); _Pragma("unroll") for (int m = 0; m < 4; ++m) _Pragma("unroll") for (int n = 0; n < 2; ++n) _Pragma("unroll") for (int k = 0; k < 2; ++k) \
;         acc[ai][bj][m][n] = __builtin_amdgcn_mfma_f32_16x16x32_bf16(Bt[n][k], At[m][k], acc[ai][bj][m][n], 0, 0, 0); __builtin_amdgcn_s_setprio(0); } while (0)
; #define PG8_WAIT_V(n) asm volatile("s_waitcnt vmcnt(" #n ")" ::: "memory")
; #define PG8_WAIT_L(n) asm volatile("s_waitcnt lgkmcnt(" #n ")" ::: "memory")
; #define PG8_BAR __builtin_amdgcn_s_barrier()
; #define PG8_SCHED __builtin_amdgcn_sched_barrier(0)
; template <class Epi>
; __device__ __forceinline__ void gemm_phase(LAS unsigned char* lds, const Gemm g, const StaticOrder& S, const Epi& E) {
;     ...
;             PG8_LDA(At, 1, 1); PG8_STAGE(PG8_SB(1, 0), b3, voffB); PG8_STAGE(PG8_SB(1, 1), b3 + hstepB, voffB); PG8_STAGE(PG8_SA(1, 0), a3, voffA);
;             PG8_WAIT_V(8); PG8_WAIT_L(0); PG8_BAR; PG8_MMA(1, 0, At, B0); PG8_MMA(1, 1, At, B1); PG8_BAR; PG8_SCHED;
	s_add_i32 s48, s76, s54
	v_lshl_add_u64 v[182:183], v[182:183], 0, s[16:17]
	s_mov_b32 m0, s48
	ds_read_b128 v[190:193], v187 offset:49152
	ds_read_b128 v[194:197], v187 offset:50176
	ds_read_b128 v[198:201], v187 offset:51200
	ds_read_b128 v[208:211], v187 offset:52224
	ds_read_b128 v[212:215], v187 offset:53248
	ds_read_b128 v[216:219], v187 offset:54272
	ds_read_b128 v[220:223], v187 offset:55296
	ds_read_b128 v[224:227], v187 offset:56320
	global_load_lds_dwordx4 v[182:183], off
	s_add_i32 m0, s48, 0x2000
	s_add_u32 s46, s46, 0x80080
	v_lshl_add_u64 v[182:183], v[202:203], 0, s[16:17]
	s_addc_u32 s47, s47, 0
	s_add_i32 s48, s77, s54
	global_load_lds_dwordx4 v[182:183], off
	v_lshl_add_u64 v[182:183], s[46:47], 0, v[162:163]
	s_mov_b32 m0, s48
	s_nop 0
	global_load_lds_dwordx4 v[182:183], off
	v_lshl_add_u64 v[182:183], s[46:47], 0, v[166:167]
	s_add_i32 m0, s48, 0x2000
	s_nop 0
	global_load_lds_dwordx4 v[182:183], off
	v_lshl_add_u64 v[182:183], v[230:231], 0, s[16:17]
	s_mov_b32 m0, s60
	s_nop 0
	global_load_lds_dwordx4 v[182:183], off
	v_lshl_add_u64 v[182:183], v[232:233], 0, s[16:17]
	s_mov_b32 m0, s61
	s_nop 0
	global_load_lds_dwordx4 v[182:183], off
	s_waitcnt vmcnt(8)
	s_waitcnt lgkmcnt(0)
	s_barrier
	s_setprio 1
	s_waitcnt lgkmcnt(0)
	v_mfma_f32_16x16x32_bf16 v[60:63], v[128:131], v[190:193], v[60:63]
	v_mfma_f32_16x16x32_bf16 v[60:63], v[132:135], v[194:197], v[60:63]
	v_mfma_f32_16x16x32_bf16 v[56:59], v[140:143], v[194:197], v[56:59]
	v_mfma_f32_16x16x32_bf16 v[56:59], v[136:139], v[190:193], v[56:59]
	v_mfma_f32_16x16x32_bf16 v[52:55], v[144:147], v[190:193], v[52:55]
	v_mfma_f32_16x16x32_bf16 v[52:55], v[148:151], v[194:197], v[52:55]
	v_mfma_f32_16x16x32_bf16 v[48:51], v[156:159], v[194:197], v[48:51]
	v_mfma_f32_16x16x32_bf16 v[48:51], v[152:155], v[190:193], v[48:51]
	v_mfma_f32_16x16x32_bf16 v[32:35], v[152:155], v[198:201], v[32:35]
	v_mfma_f32_16x16x32_bf16 v[32:35], v[156:159], v[208:211], v[32:35]
	v_mfma_f32_16x16x32_bf16 v[36:39], v[148:151], v[208:211], v[36:39]
	v_mfma_f32_16x16x32_bf16 v[36:39], v[144:147], v[198:201], v[36:39]
	v_mfma_f32_16x16x32_bf16 v[40:43], v[136:139], v[198:201], v[40:43]
	v_mfma_f32_16x16x32_bf16 v[40:43], v[140:143], v[208:211], v[40:43]
	v_mfma_f32_16x16x32_bf16 v[44:47], v[132:135], v[208:211], v[44:47]
	v_mfma_f32_16x16x32_bf16 v[44:47], v[128:131], v[198:201], v[44:47]
	s_setprio 0
	s_setprio 1
	v_mfma_f32_16x16x32_bf16 v[28:31], v[128:131], v[212:215], v[28:31]
	v_mfma_f32_16x16x32_bf16 v[28:31], v[132:135], v[216:219], v[28:31]
	v_mfma_f32_16x16x32_bf16 v[24:27], v[140:143], v[216:219], v[24:27]
	v_mfma_f32_16x16x32_bf16 v[24:27], v[136:139], v[212:215], v[24:27]
	v_mfma_f32_16x16x32_bf16 v[20:23], v[144:147], v[212:215], v[20:23]
	v_mfma_f32_16x16x32_bf16 v[20:23], v[148:151], v[216:219], v[20:23]
	v_mfma_f32_16x16x32_bf16 v[16:19], v[156:159], v[216:219], v[16:19]
	v_mfma_f32_16x16x32_bf16 v[16:19], v[152:155], v[212:215], v[16:19]
	v_mfma_f32_16x16x32_bf16 v[0:3], v[152:155], v[220:223], v[0:3]
	v_mfma_f32_16x16x32_bf16 v[0:3], v[156:159], v[224:227], v[0:3]
	v_mfma_f32_16x16x32_bf16 v[4:7], v[148:151], v[224:227], v[4:7]
	v_mfma_f32_16x16x32_bf16 v[4:7], v[144:147], v[220:223], v[4:7]
	v_mfma_f32_16x16x32_bf16 v[8:11], v[136:139], v[220:223], v[8:11]
	v_mfma_f32_16x16x32_bf16 v[8:11], v[140:143], v[224:227], v[8:11]
	v_mfma_f32_16x16x32_bf16 v[12:15], v[132:135], v[224:227], v[12:15]
	v_mfma_f32_16x16x32_bf16 v[12:15], v[128:131], v[220:223], v[12:15]
	s_setprio 0
	s_barrier
	s_add_u32 s12, s12, 0x100
	s_addc_u32 s13, s13, 0
	s_add_u32 s71, s71, 0x100
	s_addc_u32 s72, s72, 0
	s_cmp_ge_i32 s73, s59
	s_mov_b32 s46, s73
	s_cbranch_scc0 .LBB0_1046

; #define PG8_STAGE(bufoff, gbase, voff) do { _Pragma("unroll") for (int _i = 0; _i < 2; ++_i) \
;         __builtin_amdgcn_global_load_lds((const unsigned*)((const char*)(gbase) + (voff)[_i]), (LAS unsigned*)(lds + (bufoff) + ldsw + _i * 8192), 16, 0, 0); } while (0)
; #define PG8_LDA(dst, b, h) do { _Pragma("unroll") for (int m = 0; m < 4; ++m) _Pragma("unroll") for (int k = 0; k < 2; ++k) dst[m][k] = *(const LAS bf16x8*)(lds + PG8_SA(b, h) + aoff + m * 2048 + k * 1024); } while (0)
; #define PG8_LDB(dst, b, h) do { _Pragma("unroll") for (int n = 0; n < 2; ++n) _Pragma("unroll") for (int k = 0; k < 2; ++k) dst[n][k] = *(const LAS bf16x8*)(lds + PG8_SB(b, h) + boff + n * 2048 + k * 1024); } while (0)
; #define PG8_MMA(ai, bj, At, Bt) do { __builtin_amdgcn_s_setprio(1); _Pragma("unroll") for (int m = 0; m < 4; ++m) _Pragma("unroll") for (int n = 0; n < 2; ++n) _Pragma("unroll") for (int k = 0; k < 2; ++k) \
;         acc[ai][bj][m][n] = __builtin_amdgcn_mfma_f32_16x16x32_bf16(Bt[n][k], At[m][k], acc[ai][bj][m][n], 0, 0, 0); __builtin_amdgcn_s_setprio(0); } while (0)
; #define PG8_WAIT_V(n) asm volatile("s_waitcnt vmcnt(" #n ")" ::: "memory")
; #define PG8_WAIT_L(n) asm volatile("s_waitcnt lgkmcnt(" #n ")" ::: "memory")
; #define PG8_BAR __builtin_amdgcn_s_barrier()
; #define PG8_SCHED __builtin_amdgcn_sched_barrier(0)
; template <class Epi>
; __device__ __forceinline__ void gemm_phase(LAS unsigned char* lds, const Gemm g, const StaticOrder& S, const Epi& E) {
;     ...
;         for (int t = 0; t < nt; t += 2) {
;             const bool last = (t == nt - 2);
;             const char* a1 = cA + (size_t)(t + 1) * kstep;
;             const char* a2 = last ? nA : cA + (size_t)(t + 2) * kstep; const char* b2 = last ? nB : cB + (size_t)(t + 2) * kstep;
;             const char* a3 = a2 + kstep; const char* b3 = b2 + kstep;
;             PG8_LDB(B0, 0, 0); PG8_LDB(B1, 0, 1); PG8_SCHED; PG8_LDA(At, 0, 0); PG8_STAGE(PG8_SA(1, 1), a1 + hstepA, voffA);
;             PG8_WAIT_V(8); PG8_WAIT_L(0); PG8_BAR; PG8_MMA(0, 0, At, B0); PG8_MMA(0, 1, At, B1); PG8_BAR; PG8_SCHED;
;             PG8_LDA(At, 0, 1); PG8_STAGE(PG8_SB(0, 0), b2, voffB); PG8_STAGE(PG8_SB(0, 1), b2 + hstepB, voffB); PG8_STAGE(PG8_SA(0, 0), a2, voffA);
;             PG8_WAIT_V(8); PG8_WAIT_L(0); PG8_BAR; PG8_MMA(1, 0, At, B0); PG8_MMA(1, 1, At, B1); PG8_BAR; PG8_SCHED;
.LBB0_1131:
	ds_read_b128 v[164:167], v182
	ds_read_b128 v[168:171], v182 offset:1024
	ds_read_b128 v[172:175], v182 offset:2048
	ds_read_b128 v[176:179], v182 offset:3072
	ds_read_b128 v[186:189], v183
	ds_read_b128 v[190:193], v183 offset:1024
	ds_read_b128 v[194:197], v183 offset:2048
	ds_read_b128 v[198:201], v183 offset:3072
	s_add_i32 s22, s12, 2
	s_add_u32 s13, s10, 0xfff80080
	s_addc_u32 s14, s11, -1
	s_cmp_eq_u32 s58, s12
	s_cselect_b32 s12, s19, s20
	s_cselect_b32 s15, s16, s14
	s_cselect_b32 s14, s17, s13
	s_cselect_b32 s13, s18, s21
	v_lshl_add_u64 v[202:203], s[10:11], 0, v[140:141]
	s_add_i32 m0, s33, 0xc000
	ds_read_b128 v[208:211], v184
	ds_read_b128 v[212:215], v184 offset:1024
	ds_read_b128 v[216:219], v184 offset:2048
	ds_read_b128 v[220:223], v184 offset:3072
	ds_read_b128 v[224:227], v184 offset:4096
	ds_read_b128 v[230:233], v184 offset:5120
	ds_read_b128 v[234:237], v184 offset:6144
	ds_read_b128 v[238:241], v184 offset:7168
	global_load_lds_dwordx4 v[202:203], off
	v_lshl_add_u64 v[202:203], s[10:11], 0, v[142:143]
	s_add_i32 m0, s33, 0xe000
	s_nop 0
	global_load_lds_dwordx4 v[202:203], off
	s_waitcnt vmcnt(8)
	s_waitcnt lgkmcnt(0)
	s_barrier
	s_setprio 1
	s_waitcnt lgkmcnt(0)
	v_mfma_f32_16x16x32_bf16 v[120:123], v[164:167], v[208:211], v[120:123]
	v_mfma_f32_16x16x32_bf16 v[120:123], v[168:171], v[212:215], v[120:123]
	v_mfma_f32_16x16x32_bf16 v[116:119], v[176:179], v[212:215], v[116:119]
	v_mfma_f32_16x16x32_bf16 v[116:119], v[172:175], v[208:211], v[116:119]
	v_mfma_f32_16x16x32_bf16 v[124:127], v[186:189], v[208:211], v[124:127]
	v_mfma_f32_16x16x32_bf16 v[124:127], v[190:193], v[212:215], v[124:127]
	v_mfma_f32_16x16x32_bf16 v[112:115], v[198:201], v[212:215], v[112:115]
	v_mfma_f32_16x16x32_bf16 v[112:115], v[194:197], v[208:211], v[112:115]
	v_mfma_f32_16x16x32_bf16 v[96:99], v[194:197], v[216:219], v[96:99]
	v_mfma_f32_16x16x32_bf16 v[96:99], v[198:201], v[220:223], v[96:99]
	v_mfma_f32_16x16x32_bf16 v[104:107], v[190:193], v[220:223], v[104:107]
	v_mfma_f32_16x16x32_bf16 v[104:107], v[186:189], v[216:219], v[104:107]
	v_mfma_f32_16x16x32_bf16 v[100:103], v[172:175], v[216:219], v[100:103]
	v_mfma_f32_16x16x32_bf16 v[100:103], v[176:179], v[220:223], v[100:103]
	v_mfma_f32_16x16x32_bf16 v[108:111], v[168:171], v[220:223], v[108:111]
	v_mfma_f32_16x16x32_bf16 v[108:111], v[164:167], v[216:219], v[108:111]
	s_setprio 0
	s_setprio 1
	v_mfma_f32_16x16x32_bf16 v[92:95], v[164:167], v[224:227], v[92:95]
	v_mfma_f32_16x16x32_bf16 v[92:95], v[168:171], v[230:233], v[92:95]
	v_mfma_f32_16x16x32_bf16 v[84:87], v[176:179], v[230:233], v[84:87]
	v_mfma_f32_16x16x32_bf16 v[84:87], v[172:175], v[224:227], v[84:87]
	v_mfma_f32_16x16x32_bf16 v[88:91], v[186:189], v[224:227], v[88:91]
	v_mfma_f32_16x16x32_bf16 v[88:91], v[190:193], v[230:233], v[88:91]
	v_mfma_f32_16x16x32_bf16 v[80:83], v[198:201], v[230:233], v[80:83]
	v_mfma_f32_16x16x32_bf16 v[80:83], v[194:197], v[224:227], v[80:83]
	v_mfma_f32_16x16x32_bf16 v[64:67], v[194:197], v[234:237], v[64:67]
	v_mfma_f32_16x16x32_bf16 v[64:67], v[198:201], v[238:241], v[64:67]
	v_mfma_f32_16x16x32_bf16 v[72:75], v[190:193], v[238:241], v[72:75]
	v_mfma_f32_16x16x32_bf16 v[72:75], v[186:189], v[234:237], v[72:75]
	v_mfma_f32_16x16x32_bf16 v[68:71], v[172:175], v[234:237], v[68:71]
	v_mfma_f32_16x16x32_bf16 v[68:71], v[176:179], v[238:241], v[68:71]
	v_mfma_f32_16x16x32_bf16 v[76:79], v[168:171], v[238:241], v[76:79]
	v_mfma_f32_16x16x32_bf16 v[76:79], v[164:167], v[234:237], v[76:79]
	s_setprio 0
	s_barrier
	s_add_i32 s23, s62, s37
	v_lshl_add_u64 v[202:203], s[12:13], 0, v[132:133]
	s_mov_b32 m0, s23
	ds_read_b128 v[208:211], v184 offset:16384
	ds_read_b128 v[212:215], v184 offset:17408
	ds_read_b128 v[216:219], v184 offset:18432
	ds_read_b128 v[220:223], v184 offset:19456
	ds_read_b128 v[224:227], v184 offset:20480
	ds_read_b128 v[230:233], v184 offset:21504
	ds_read_b128 v[234:237], v184 offset:22528
	ds_read_b128 v[238:241], v184 offset:23552
	global_load_lds_dwordx4 v[202:203], off
	s_add_i32 m0, s23, 0x2000
	s_add_u32 s50, s12, 0x80000
	v_lshl_add_u64 v[242:243], s[12:13], 0, v[128:129]
	s_addc_u32 s51, s13, 0
	s_add_i32 s23, s63, s37
	global_load_lds_dwordx4 v[242:243], off
	v_lshl_add_u64 v[244:245], s[50:51], 0, v[132:133]
	s_mov_b32 m0, s23
	v_lshl_add_u64 v[246:247], s[14:15], 0, v[130:131]
	global_load_lds_dwordx4 v[244:245], off
	v_lshl_add_u64 v[244:245], s[50:51], 0, v[128:129]
	s_add_i32 m0, s23, 0x2000
	s_nop 0
	global_load_lds_dwordx4 v[244:245], off
	v_lshl_add_u64 v[244:245], s[14:15], 0, v[134:135]
	s_mov_b32 m0, s33
	s_nop 0
	global_load_lds_dwordx4 v[244:245], off
	s_mov_b32 m0, s52
	s_nop 0
	global_load_lds_dwordx4 v[246:247], off
	s_waitcnt vmcnt(8)
	s_waitcnt lgkmcnt(0)
	s_barrier
; #define PG8_STAGE(bufoff, gbase, voff) do { _Pragma("unroll") for (int _i = 0; _i < 2; ++_i) \
;         __builtin_amdgcn_global_load_lds((const unsigned*)((const char*)(gbase) + (voff)[_i]), (LAS unsigned*)(lds + (bufoff) + ldsw + _i * 8192), 16, 0, 0); } while (0)
; #define PG8_LDA(dst, b, h) do { _Pragma("unroll") for (int m = 0; m < 4; ++m) _Pragma("unroll") for (int k = 0; k < 2; ++k) dst[m][k] = *(const LAS bf16x8*)(lds + PG8_SA(b, h) + aoff + m * 2048 + k * 1024); } while (0)
; #define PG8_LDB(dst, b, h) do { _Pragma("unroll") for (int n = 0; n < 2; ++n) _Pragma("unroll") for (int k = 0; k < 2; ++k) dst[n][k] = *(const LAS bf16x8*)(lds + PG8_SB(b, h) + boff + n * 2048 + k * 1024); } while (0)
; #define PG8_MMA(ai, bj, At, Bt) do { __builtin_amdgcn_s_setprio(1); _Pragma("unroll") for (int m = 0; m < 4; ++m) _Pragma("unroll") for (int n = 0; n < 2; ++n) _Pragma("unroll") for (int k = 0; k < 2; ++k) \
;         acc[ai][bj][m][n] = __builtin_amdgcn_mfma_f32_16x16x32_bf16(Bt[n][k], At[m][k], acc[ai][bj][m][n], 0, 0, 0); __builtin_amdgcn_s_setprio(0); } while (0)
; #define PG8_WAIT_V(n) asm volatile("s_waitcnt vmcnt(" #n ")" ::: "memory")
; #define PG8_WAIT_L(n) asm volatile("s_waitcnt lgkmcnt(" #n ")" ::: "memory")
; #define PG8_BAR __builtin_amdgcn_s_barrier()
; #define PG8_SCHED __builtin_amdgcn_sched_barrier(0)
; template <class Epi>
; __device__ __forceinline__ void gemm_phase(LAS unsigned char* lds, const Gemm g, const StaticOrder& S, const Epi& E) {
;     ...
;             PG8_WAIT_V(8); PG8_WAIT_L(0); PG8_BAR; PG8_MMA(1, 0, At, B0); PG8_MMA(1, 1, At, B1); PG8_BAR; PG8_SCHED;
;             PG8_LDB(B0, 1, 0); PG8_LDB(B1, 1, 1); PG8_SCHED; PG8_LDA(At, 1, 0); PG8_STAGE(PG8_SA(0, 1), a2 + hstepA, voffA);
;             PG8_WAIT_V(8); PG8_WAIT_L(0); PG8_BAR; PG8_MMA(0, 0, At, B0); PG8_MMA(0, 1, At, B1); PG8_BAR; PG8_SCHED;
	s_setprio 1
	s_waitcnt lgkmcnt(0)
	v_mfma_f32_16x16x32_bf16 v[60:63], v[164:167], v[208:211], v[60:63]
	v_mfma_f32_16x16x32_bf16 v[60:63], v[168:171], v[212:215], v[60:63]
	v_mfma_f32_16x16x32_bf16 v[52:55], v[176:179], v[212:215], v[52:55]
	v_mfma_f32_16x16x32_bf16 v[52:55], v[172:175], v[208:211], v[52:55]
	v_mfma_f32_16x16x32_bf16 v[56:59], v[186:189], v[208:211], v[56:59]
	v_mfma_f32_16x16x32_bf16 v[56:59], v[190:193], v[212:215], v[56:59]
	v_mfma_f32_16x16x32_bf16 v[48:51], v[198:201], v[212:215], v[48:51]
	v_mfma_f32_16x16x32_bf16 v[48:51], v[194:197], v[208:211], v[48:51]
	v_mfma_f32_16x16x32_bf16 v[32:35], v[194:197], v[216:219], v[32:35]
	v_mfma_f32_16x16x32_bf16 v[32:35], v[198:201], v[220:223], v[32:35]
	v_mfma_f32_16x16x32_bf16 v[40:43], v[190:193], v[220:223], v[40:43]
	v_mfma_f32_16x16x32_bf16 v[40:43], v[186:189], v[216:219], v[40:43]
	v_mfma_f32_16x16x32_bf16 v[36:39], v[172:175], v[216:219], v[36:39]
	v_mfma_f32_16x16x32_bf16 v[36:39], v[176:179], v[220:223], v[36:39]
	v_mfma_f32_16x16x32_bf16 v[44:47], v[168:171], v[220:223], v[44:47]
	v_mfma_f32_16x16x32_bf16 v[44:47], v[164:167], v[216:219], v[44:47]
	s_setprio 0
	s_setprio 1
	v_mfma_f32_16x16x32_bf16 v[28:31], v[164:167], v[224:227], v[28:31]
	v_mfma_f32_16x16x32_bf16 v[28:31], v[168:171], v[230:233], v[28:31]
	v_mfma_f32_16x16x32_bf16 v[20:23], v[176:179], v[230:233], v[20:23]
	v_mfma_f32_16x16x32_bf16 v[20:23], v[172:175], v[224:227], v[20:23]
	v_mfma_f32_16x16x32_bf16 v[24:27], v[186:189], v[224:227], v[24:27]
	v_mfma_f32_16x16x32_bf16 v[24:27], v[190:193], v[230:233], v[24:27]
	v_mfma_f32_16x16x32_bf16 v[16:19], v[198:201], v[230:233], v[16:19]
	v_mfma_f32_16x16x32_bf16 v[16:19], v[194:197], v[224:227], v[16:19]
	v_mfma_f32_16x16x32_bf16 v[0:3], v[194:197], v[234:237], v[0:3]
	v_mfma_f32_16x16x32_bf16 v[0:3], v[198:201], v[238:241], v[0:3]
	v_mfma_f32_16x16x32_bf16 v[8:11], v[190:193], v[238:241], v[8:11]
	v_mfma_f32_16x16x32_bf16 v[8:11], v[186:189], v[234:237], v[8:11]
	v_mfma_f32_16x16x32_bf16 v[4:7], v[172:175], v[234:237], v[4:7]
	v_mfma_f32_16x16x32_bf16 v[4:7], v[176:179], v[238:241], v[4:7]
	v_mfma_f32_16x16x32_bf16 v[12:15], v[168:171], v[238:241], v[12:15]
	v_mfma_f32_16x16x32_bf16 v[12:15], v[164:167], v[234:237], v[12:15]
	s_setprio 0
	s_barrier
	s_add_i32 s23, 0, 0x18000
	s_add_i32 s25, 0, 0x1c000
	v_add_u32_e32 v176, s23, v180
	v_add_u32_e32 v185, s25, v180
	ds_read_b128 v[164:167], v176
	ds_read_b128 v[168:171], v176 offset:1024
	ds_read_b128 v[172:175], v176 offset:2048
	ds_read_b128 v[176:179], v176 offset:3072
	ds_read_b128 v[186:189], v185
	ds_read_b128 v[190:193], v185 offset:1024
	ds_read_b128 v[194:197], v185 offset:2048
	ds_read_b128 v[198:201], v185 offset:3072
	s_add_u32 s14, s14, 0x80000
	s_addc_u32 s15, s15, 0
	s_mov_b32 m0, s53
	v_lshl_add_u64 v[248:249], s[14:15], 0, v[134:135]
	ds_read_b128 v[208:211], v184 offset:32768
	ds_read_b128 v[212:215], v184 offset:33792
	ds_read_b128 v[216:219], v184 offset:34816
	ds_read_b128 v[220:223], v184 offset:35840
	ds_read_b128 v[224:227], v184 offset:36864
	ds_read_b128 v[230:233], v184 offset:37888
	ds_read_b128 v[234:237], v184 offset:38912
	ds_read_b128 v[238:241], v184 offset:39936
	global_load_lds_dwordx4 v[248:249], off
	v_lshl_add_u64 v[248:249], s[14:15], 0, v[130:131]
	s_mov_b32 m0, s54
	s_nop 0
	global_load_lds_dwordx4 v[248:249], off
	s_waitcnt vmcnt(8)
	s_waitcnt lgkmcnt(0)
	s_barrier
	s_setprio 1
	s_waitcnt lgkmcnt(0)
	v_mfma_f32_16x16x32_bf16 v[120:123], v[164:167], v[208:211], v[120:123]
	v_mfma_f32_16x16x32_bf16 v[120:123], v[168:171], v[212:215], v[120:123]
	v_mfma_f32_16x16x32_bf16 v[116:119], v[176:179], v[212:215], v[116:119]
	v_mfma_f32_16x16x32_bf16 v[116:119], v[172:175], v[208:211], v[116:119]
	v_mfma_f32_16x16x32_bf16 v[124:127], v[186:189], v[208:211], v[124:127]
	v_mfma_f32_16x16x32_bf16 v[124:127], v[190:193], v[212:215], v[124:127]
	v_mfma_f32_16x16x32_bf16 v[112:115], v[198:201], v[212:215], v[112:115]
	v_mfma_f32_16x16x32_bf16 v[112:115], v[194:197], v[208:211], v[112:115]
	v_mfma_f32_16x16x32_bf16 v[96:99], v[194:197], v[216:219], v[96:99]
	v_mfma_f32_16x16x32_bf16 v[96:99], v[198:201], v[220:223], v[96:99]
	v_mfma_f32_16x16x32_bf16 v[104:107], v[190:193], v[220:223], v[104:107]
	v_mfma_f32_16x16x32_bf16 v[104:107], v[186:189], v[216:219], v[104:107]
	v_mfma_f32_16x16x32_bf16 v[100:103], v[172:175], v[216:219], v[100:103]
	v_mfma_f32_16x16x32_bf16 v[100:103], v[176:179], v[220:223], v[100:103]
	v_mfma_f32_16x16x32_bf16 v[108:111], v[168:171], v[220:223], v[108:111]
	v_mfma_f32_16x16x32_bf16 v[108:111], v[164:167], v[216:219], v[108:111]
	s_setprio 0
	s_setprio 1
	v_mfma_f32_16x16x32_bf16 v[92:95], v[164:167], v[224:227], v[92:95]
	v_mfma_f32_16x16x32_bf16 v[92:95], v[168:171], v[230:233], v[92:95]
	v_mfma_f32_16x16x32_bf16 v[84:87], v[176:179], v[230:233], v[84:87]
	v_mfma_f32_16x16x32_bf16 v[84:87], v[172:175], v[224:227], v[84:87]
	v_mfma_f32_16x16x32_bf16 v[88:91], v[186:189], v[224:227], v[88:91]
	v_mfma_f32_16x16x32_bf16 v[88:91], v[190:193], v[230:233], v[88:91]
	v_mfma_f32_16x16x32_bf16 v[80:83], v[198:201], v[230:233], v[80:83]
	v_mfma_f32_16x16x32_bf16 v[80:83], v[194:197], v[224:227], v[80:83]
	v_mfma_f32_16x16x32_bf16 v[64:67], v[194:197], v[234:237], v[64:67]
	v_mfma_f32_16x16x32_bf16 v[64:67], v[198:201], v[238:241], v[64:67]
	v_mfma_f32_16x16x32_bf16 v[72:75], v[190:193], v[238:241], v[72:75]
	v_mfma_f32_16x16x32_bf16 v[72:75], v[186:189], v[234:237], v[72:75]
	v_mfma_f32_16x16x32_bf16 v[68:71], v[172:175], v[234:237], v[68:71]
	v_mfma_f32_16x16x32_bf16 v[68:71], v[176:179], v[238:241], v[68:71]
	v_mfma_f32_16x16x32_bf16 v[76:79], v[168:171], v[238:241], v[76:79]
	v_mfma_f32_16x16x32_bf16 v[76:79], v[164:167], v[234:237], v[76:79]
	s_setprio 0
	s_barrier
; #define PG8_STAGE(bufoff, gbase, voff) do { _Pragma("unroll") for (int _i = 0; _i < 2; ++_i) \
;         __builtin_amdgcn_global_load_lds((const unsigned*)((const char*)(gbase) + (voff)[_i]), (LAS unsigned*)(lds + (bufoff) + ldsw + _i * 8192), 16, 0, 0); } while (0)
; #define PG8_LDA(dst, b, h) do { _Pragma("unroll") for (int m = 0; m < 4; ++m) _Pragma("unroll") for (int k = 0; k < 2; ++k) dst[m][k] = *(const LAS bf16x8*)(lds + PG8_SA(b, h) + aoff + m * 2048 + k * 1024); } while (0)
; #define PG8_MMA(ai, bj, At, Bt) do { __builtin_amdgcn_s_setprio(1); _Pragma("unroll") for (int m = 0; m < 4; ++m) _Pragma("unroll") for (int n = 0; n < 2; ++n) _Pragma("unroll") for (int k = 0; k < 2; ++k) \
;         acc[ai][bj][m][n] = __builtin_amdgcn_mfma_f32_16x16x32_bf16(Bt[n][k], At[m][k], acc[ai][bj][m][n], 0, 0, 0); __builtin_amdgcn_s_setprio(0); } while (0)
; #define PG8_WAIT_V(n) asm volatile("s_waitcnt vmcnt(" #n ")" ::: "memory")
; #define PG8_WAIT_L(n) asm volatile("s_waitcnt lgkmcnt(" #n ")" ::: "memory")
; #define PG8_BAR __builtin_amdgcn_s_barrier()
; #define PG8_SCHED __builtin_amdgcn_sched_barrier(0)
; template <class Epi>
; __device__ __forceinline__ void gemm_phase(LAS unsigned char* lds, const Gemm g, const StaticOrder& S, const Epi& E) {
;     ...
;             PG8_LDA(At, 1, 1); PG8_STAGE(PG8_SB(1, 0), b3, voffB); PG8_STAGE(PG8_SB(1, 1), b3 + hstepB, voffB); PG8_STAGE(PG8_SA(1, 0), a3, voffA);
;             PG8_WAIT_V(8); PG8_WAIT_L(0); PG8_BAR; PG8_MMA(1, 0, At, B0); PG8_MMA(1, 1, At, B1); PG8_BAR; PG8_SCHED;
	s_add_i32 s14, s23, s37
	v_lshl_add_u64 v[202:203], v[202:203], 0, s[4:5]
	s_mov_b32 m0, s14
	ds_read_b128 v[208:211], v184 offset:49152
	ds_read_b128 v[212:215], v184 offset:50176
	ds_read_b128 v[216:219], v184 offset:51200
	ds_read_b128 v[220:223], v184 offset:52224
	ds_read_b128 v[224:227], v184 offset:53248
	ds_read_b128 v[230:233], v184 offset:54272
	ds_read_b128 v[234:237], v184 offset:55296
	ds_read_b128 v[238:241], v184 offset:56320
	global_load_lds_dwordx4 v[202:203], off
	s_add_i32 m0, s14, 0x2000
	s_add_u32 s12, s12, 0x80080
	v_lshl_add_u64 v[202:203], v[242:243], 0, s[4:5]
	s_addc_u32 s13, s13, 0
	s_add_i32 s14, s25, s37
	global_load_lds_dwordx4 v[202:203], off
	v_lshl_add_u64 v[202:203], s[12:13], 0, v[132:133]
	s_mov_b32 m0, s14
	s_nop 0
	global_load_lds_dwordx4 v[202:203], off
	v_lshl_add_u64 v[202:203], s[12:13], 0, v[128:129]
	s_add_i32 m0, s14, 0x2000
	s_nop 0
	global_load_lds_dwordx4 v[202:203], off
	v_lshl_add_u64 v[202:203], v[244:245], 0, s[4:5]
	s_mov_b32 m0, s56
	s_nop 0
	global_load_lds_dwordx4 v[202:203], off
	v_lshl_add_u64 v[202:203], v[246:247], 0, s[4:5]
	s_mov_b32 m0, s57
	s_nop 0
	global_load_lds_dwordx4 v[202:203], off
	s_waitcnt vmcnt(8)
	s_waitcnt lgkmcnt(0)
	s_barrier
	s_setprio 1
	s_waitcnt lgkmcnt(0)
	v_mfma_f32_16x16x32_bf16 v[60:63], v[164:167], v[208:211], v[60:63]
	v_mfma_f32_16x16x32_bf16 v[60:63], v[168:171], v[212:215], v[60:63]
	v_mfma_f32_16x16x32_bf16 v[52:55], v[176:179], v[212:215], v[52:55]
	v_mfma_f32_16x16x32_bf16 v[52:55], v[172:175], v[208:211], v[52:55]
	v_mfma_f32_16x16x32_bf16 v[56:59], v[186:189], v[208:211], v[56:59]
	v_mfma_f32_16x16x32_bf16 v[56:59], v[190:193], v[212:215], v[56:59]
	v_mfma_f32_16x16x32_bf16 v[48:51], v[198:201], v[212:215], v[48:51]
	v_mfma_f32_16x16x32_bf16 v[48:51], v[194:197], v[208:211], v[48:51]
	v_mfma_f32_16x16x32_bf16 v[32:35], v[194:197], v[216:219], v[32:35]
	v_mfma_f32_16x16x32_bf16 v[32:35], v[198:201], v[220:223], v[32:35]
	v_mfma_f32_16x16x32_bf16 v[40:43], v[190:193], v[220:223], v[40:43]
	v_mfma_f32_16x16x32_bf16 v[40:43], v[186:189], v[216:219], v[40:43]
	v_mfma_f32_16x16x32_bf16 v[36:39], v[172:175], v[216:219], v[36:39]
	v_mfma_f32_16x16x32_bf16 v[36:39], v[176:179], v[220:223], v[36:39]
	v_mfma_f32_16x16x32_bf16 v[44:47], v[168:171], v[220:223], v[44:47]
	v_mfma_f32_16x16x32_bf16 v[44:47], v[164:167], v[216:219], v[44:47]
	s_setprio 0
	s_setprio 1
	v_mfma_f32_16x16x32_bf16 v[28:31], v[164:167], v[224:227], v[28:31]
	v_mfma_f32_16x16x32_bf16 v[28:31], v[168:171], v[230:233], v[28:31]
	v_mfma_f32_16x16x32_bf16 v[20:23], v[176:179], v[230:233], v[20:23]
	v_mfma_f32_16x16x32_bf16 v[20:23], v[172:175], v[224:227], v[20:23]
	v_mfma_f32_16x16x32_bf16 v[24:27], v[186:189], v[224:227], v[24:27]
	v_mfma_f32_16x16x32_bf16 v[24:27], v[190:193], v[230:233], v[24:27]
	v_mfma_f32_16x16x32_bf16 v[16:19], v[198:201], v[230:233], v[16:19]
	v_mfma_f32_16x16x32_bf16 v[16:19], v[194:197], v[224:227], v[16:19]
	v_mfma_f32_16x16x32_bf16 v[0:3], v[194:197], v[234:237], v[0:3]
	v_mfma_f32_16x16x32_bf16 v[0:3], v[198:201], v[238:241], v[0:3]
	v_mfma_f32_16x16x32_bf16 v[8:11], v[190:193], v[238:241], v[8:11]
	v_mfma_f32_16x16x32_bf16 v[8:11], v[186:189], v[234:237], v[8:11]
	v_mfma_f32_16x16x32_bf16 v[4:7], v[172:175], v[234:237], v[4:7]
	v_mfma_f32_16x16x32_bf16 v[4:7], v[176:179], v[238:241], v[4:7]
	v_mfma_f32_16x16x32_bf16 v[12:15], v[168:171], v[238:241], v[12:15]
	v_mfma_f32_16x16x32_bf16 v[12:15], v[164:167], v[234:237], v[12:15]
	s_setprio 0
	s_barrier
	s_add_u32 s10, s10, 0x100
	s_addc_u32 s11, s11, 0
	s_add_u32 s20, s20, 0x100
	s_addc_u32 s21, s21, 0
	s_cmp_ge_i32 s22, s55
	s_mov_b32 s12, s22
	s_cbranch_scc0 .LBB0_1131

; #define PG8_STAGE(bufoff, gbase, voff) do { _Pragma("unroll") for (int _i = 0; _i < 2; ++_i) \
;         __builtin_amdgcn_global_load_lds((const unsigned*)((const char*)(gbase) + (voff)[_i]), (LAS unsigned*)(lds + (bufoff) + ldsw + _i * 8192), 16, 0, 0); } while (0)
; #define PG8_LDA(dst, b, h) do { _Pragma("unroll") for (int m = 0; m < 4; ++m) _Pragma("unroll") for (int k = 0; k < 2; ++k) dst[m][k] = *(const LAS bf16x8*)(lds + PG8_SA(b, h) + aoff + m * 2048 + k * 1024); } while (0)
; #define PG8_LDB(dst, b, h) do { _Pragma("unroll") for (int n = 0; n < 2; ++n) _Pragma("unroll") for (int k = 0; k < 2; ++k) dst[n][k] = *(const LAS bf16x8*)(lds + PG8_SB(b, h) + boff + n * 2048 + k * 1024); } while (0)
; #define PG8_MMA(ai, bj, At, Bt) do { __builtin_amdgcn_s_setprio(1); _Pragma("unroll") for (int m = 0; m < 4; ++m) _Pragma("unroll") for (int n = 0; n < 2; ++n) _Pragma("unroll") for (int k = 0; k < 2; ++k) \
;         acc[ai][bj][m][n] = __builtin_amdgcn_mfma_f32_16x16x32_bf16(Bt[n][k], At[m][k], acc[ai][bj][m][n], 0, 0, 0); __builtin_amdgcn_s_setprio(0); } while (0)
; #define PG8_WAIT_V(n) asm volatile("s_waitcnt vmcnt(" #n ")" ::: "memory")
; #define PG8_WAIT_L(n) asm volatile("s_waitcnt lgkmcnt(" #n ")" ::: "memory")
; #define PG8_BAR __builtin_amdgcn_s_barrier()
; #define PG8_SCHED __builtin_amdgcn_sched_barrier(0)
; template <class Epi>
; __device__ __forceinline__ void gemm_phase(LAS unsigned char* lds, const Gemm g, const StaticOrder& S, const Epi& E) {
;     ...
;         for (int t = 0; t < nt; t += 2) {
;             const bool last = (t == nt - 2);
;             const char* a1 = cA + (size_t)(t + 1) * kstep;
;             const char* a2 = last ? nA : cA + (size_t)(t + 2) * kstep; const char* b2 = last ? nB : cB + (size_t)(t + 2) * kstep;
;             const char* a3 = a2 + kstep; const char* b3 = b2 + kstep;
;             PG8_LDB(B0, 0, 0); PG8_LDB(B1, 0, 1); PG8_SCHED; PG8_LDA(At, 0, 0); PG8_STAGE(PG8_SA(1, 1), a1 + hstepA, voffA);
;             PG8_WAIT_V(8); PG8_WAIT_L(0); PG8_BAR; PG8_MMA(0, 0, At, B0); PG8_MMA(0, 1, At, B1); PG8_BAR; PG8_SCHED;
;             PG8_LDA(At, 0, 1); PG8_STAGE(PG8_SB(0, 0), b2, voffB); PG8_STAGE(PG8_SB(0, 1), b2 + hstepB, voffB); PG8_STAGE(PG8_SA(0, 0), a2, voffA);
;             PG8_WAIT_V(8); PG8_WAIT_L(0); PG8_BAR; PG8_MMA(1, 0, At, B0); PG8_MMA(1, 1, At, B1); PG8_BAR; PG8_SCHED;
.LBB0_1161:
	ds_read_b128 v[152:155], v149
	ds_read_b128 v[156:159], v149 offset:1024
	ds_read_b128 v[160:163], v149 offset:2048
	ds_read_b128 v[164:167], v149 offset:3072
	ds_read_b128 v[168:171], v150
	ds_read_b128 v[172:175], v150 offset:1024
	ds_read_b128 v[176:179], v150 offset:2048
	ds_read_b128 v[180:183], v150 offset:3072
	s_add_i32 s83, s46, 2
	s_add_u32 s47, s44, 0xffff0080
	s_addc_u32 s48, s45, -1
	s_cmp_eq_u32 s65, s46
	s_cselect_b32 s46, s78, s79
	s_cselect_b32 s49, s35, s48
	s_cselect_b32 s48, s37, s47
	s_cselect_b32 s47, s39, s82
	v_lshl_add_u64 v[220:221], s[44:45], 0, v[140:141]
	s_add_i32 m0, s56, 0xc000
	ds_read_b128 v[184:187], v151
	ds_read_b128 v[188:191], v151 offset:1024
	ds_read_b128 v[192:195], v151 offset:2048
	ds_read_b128 v[196:199], v151 offset:3072
	ds_read_b128 v[200:203], v151 offset:4096
	ds_read_b128 v[208:211], v151 offset:5120
	ds_read_b128 v[212:215], v151 offset:6144
	ds_read_b128 v[216:219], v151 offset:7168
	global_load_lds_dwordx4 v[220:221], off
	v_lshl_add_u64 v[220:221], s[44:45], 0, v[142:143]
	s_add_i32 m0, s56, 0xe000
	s_nop 0
	global_load_lds_dwordx4 v[220:221], off
	s_waitcnt vmcnt(8)
	s_waitcnt lgkmcnt(0)
	s_barrier
	s_setprio 1
	s_waitcnt lgkmcnt(0)
	v_mfma_f32_16x16x32_bf16 v[120:123], v[152:155], v[184:187], v[120:123]
	v_mfma_f32_16x16x32_bf16 v[120:123], v[156:159], v[188:191], v[120:123]
	v_mfma_f32_16x16x32_bf16 v[124:127], v[164:167], v[188:191], v[124:127]
	v_mfma_f32_16x16x32_bf16 v[124:127], v[160:163], v[184:187], v[124:127]
	v_mfma_f32_16x16x32_bf16 v[116:119], v[168:171], v[184:187], v[116:119]
	v_mfma_f32_16x16x32_bf16 v[116:119], v[172:175], v[188:191], v[116:119]
	v_mfma_f32_16x16x32_bf16 v[112:115], v[180:183], v[188:191], v[112:115]
	v_mfma_f32_16x16x32_bf16 v[112:115], v[176:179], v[184:187], v[112:115]
	v_mfma_f32_16x16x32_bf16 v[96:99], v[176:179], v[192:195], v[96:99]
	v_mfma_f32_16x16x32_bf16 v[96:99], v[180:183], v[196:199], v[96:99]
	v_mfma_f32_16x16x32_bf16 v[100:103], v[172:175], v[196:199], v[100:103]
	v_mfma_f32_16x16x32_bf16 v[100:103], v[168:171], v[192:195], v[100:103]
	v_mfma_f32_16x16x32_bf16 v[104:107], v[160:163], v[192:195], v[104:107]
	v_mfma_f32_16x16x32_bf16 v[104:107], v[164:167], v[196:199], v[104:107]
	v_mfma_f32_16x16x32_bf16 v[108:111], v[156:159], v[196:199], v[108:111]
	v_mfma_f32_16x16x32_bf16 v[108:111], v[152:155], v[192:195], v[108:111]
	s_setprio 0
	s_setprio 1
	v_mfma_f32_16x16x32_bf16 v[92:95], v[152:155], v[200:203], v[92:95]
	v_mfma_f32_16x16x32_bf16 v[92:95], v[156:159], v[208:211], v[92:95]
	v_mfma_f32_16x16x32_bf16 v[88:91], v[164:167], v[208:211], v[88:91]
	v_mfma_f32_16x16x32_bf16 v[88:91], v[160:163], v[200:203], v[88:91]
	v_mfma_f32_16x16x32_bf16 v[84:87], v[168:171], v[200:203], v[84:87]
	v_mfma_f32_16x16x32_bf16 v[84:87], v[172:175], v[208:211], v[84:87]
	v_mfma_f32_16x16x32_bf16 v[80:83], v[180:183], v[208:211], v[80:83]
	v_mfma_f32_16x16x32_bf16 v[80:83], v[176:179], v[200:203], v[80:83]
	v_mfma_f32_16x16x32_bf16 v[64:67], v[176:179], v[212:215], v[64:67]
	v_mfma_f32_16x16x32_bf16 v[64:67], v[180:183], v[216:219], v[64:67]
	v_mfma_f32_16x16x32_bf16 v[68:71], v[172:175], v[216:219], v[68:71]
	v_mfma_f32_16x16x32_bf16 v[68:71], v[168:171], v[212:215], v[68:71]
	v_mfma_f32_16x16x32_bf16 v[72:75], v[160:163], v[212:215], v[72:75]
	v_mfma_f32_16x16x32_bf16 v[72:75], v[164:167], v[216:219], v[72:75]
	v_mfma_f32_16x16x32_bf16 v[76:79], v[156:159], v[216:219], v[76:79]
	v_mfma_f32_16x16x32_bf16 v[76:79], v[152:155], v[212:215], v[76:79]
	s_setprio 0
	s_barrier
	s_add_i32 s84, s67, s51
	v_lshl_add_u64 v[220:221], s[46:47], 0, v[130:131]
	s_mov_b32 m0, s84
	ds_read_b128 v[184:187], v151 offset:16384
	ds_read_b128 v[188:191], v151 offset:17408
	ds_read_b128 v[192:195], v151 offset:18432
	ds_read_b128 v[196:199], v151 offset:19456
	ds_read_b128 v[200:203], v151 offset:20480
	ds_read_b128 v[208:211], v151 offset:21504
	ds_read_b128 v[212:215], v151 offset:22528
	ds_read_b128 v[216:219], v151 offset:23552
	global_load_lds_dwordx4 v[220:221], off
	s_add_i32 m0, s84, 0x2000
	s_add_u32 s84, s46, 0x10000
	v_lshl_add_u64 v[222:223], s[46:47], 0, v[134:135]
	s_addc_u32 s85, s47, 0
	s_add_i32 s86, s68, s51
	global_load_lds_dwordx4 v[222:223], off
	v_lshl_add_u64 v[224:225], s[84:85], 0, v[130:131]
	s_mov_b32 m0, s86
	v_lshl_add_u64 v[226:227], s[48:49], 0, v[132:133]
	global_load_lds_dwordx4 v[224:225], off
	v_lshl_add_u64 v[224:225], s[84:85], 0, v[134:135]
	s_add_i32 m0, s86, 0x2000
	s_nop 0
	global_load_lds_dwordx4 v[224:225], off
	v_lshl_add_u64 v[224:225], s[48:49], 0, v[128:129]
	s_mov_b32 m0, s56
	s_nop 0
	global_load_lds_dwordx4 v[224:225], off
	s_mov_b32 m0, s57
	s_nop 0
	global_load_lds_dwordx4 v[226:227], off
	s_waitcnt vmcnt(8)
	s_waitcnt lgkmcnt(0)
	s_barrier
; #define PG8_STAGE(bufoff, gbase, voff) do { _Pragma("unroll") for (int _i = 0; _i < 2; ++_i) \
;         __builtin_amdgcn_global_load_lds((const unsigned*)((const char*)(gbase) + (voff)[_i]), (LAS unsigned*)(lds + (bufoff) + ldsw + _i * 8192), 16, 0, 0); } while (0)
; #define PG8_LDA(dst, b, h) do { _Pragma("unroll") for (int m = 0; m < 4; ++m) _Pragma("unroll") for (int k = 0; k < 2; ++k) dst[m][k] = *(const LAS bf16x8*)(lds + PG8_SA(b, h) + aoff + m * 2048 + k * 1024); } while (0)
; #define PG8_LDB(dst, b, h) do { _Pragma("unroll") for (int n = 0; n < 2; ++n) _Pragma("unroll") for (int k = 0; k < 2; ++k) dst[n][k] = *(const LAS bf16x8*)(lds + PG8_SB(b, h) + boff + n * 2048 + k * 1024); } while (0)
; #define PG8_MMA(ai, bj, At, Bt) do { __builtin_amdgcn_s_setprio(1); _Pragma("unroll") for (int m = 0; m < 4; ++m) _Pragma("unroll") for (int n = 0; n < 2; ++n) _Pragma("unroll") for (int k = 0; k < 2; ++k) \
;         acc[ai][bj][m][n] = __builtin_amdgcn_mfma_f32_16x16x32_bf16(Bt[n][k], At[m][k], acc[ai][bj][m][n], 0, 0, 0); __builtin_amdgcn_s_setprio(0); } while (0)
; #define PG8_WAIT_V(n) asm volatile("s_waitcnt vmcnt(" #n ")" ::: "memory")
; #define PG8_WAIT_L(n) asm volatile("s_waitcnt lgkmcnt(" #n ")" ::: "memory")
; #define PG8_BAR __builtin_amdgcn_s_barrier()
; #define PG8_SCHED __builtin_amdgcn_sched_barrier(0)
; template <class Epi>
; __device__ __forceinline__ void gemm_phase(LAS unsigned char* lds, const Gemm g, const StaticOrder& S, const Epi& E) {
;     ...
;             PG8_WAIT_V(8); PG8_WAIT_L(0); PG8_BAR; PG8_MMA(0, 0, At, B0); PG8_MMA(0, 1, At, B1); PG8_BAR; PG8_SCHED;
;             PG8_LDA(At, 0, 1); PG8_STAGE(PG8_SB(0, 0), b2, voffB); PG8_STAGE(PG8_SB(0, 1), b2 + hstepB, voffB); PG8_STAGE(PG8_SA(0, 0), a2, voffA);
;             PG8_WAIT_V(8); PG8_WAIT_L(0); PG8_BAR; PG8_MMA(1, 0, At, B0); PG8_MMA(1, 1, At, B1); PG8_BAR; PG8_SCHED;
;             PG8_LDB(B0, 1, 0); PG8_LDB(B1, 1, 1); PG8_SCHED; PG8_LDA(At, 1, 0); PG8_STAGE(PG8_SA(0, 1), a2 + hstepA, voffA);
;             PG8_WAIT_V(8); PG8_WAIT_L(0); PG8_BAR; PG8_MMA(0, 0, At, B0); PG8_MMA(0, 1, At, B1); PG8_BAR; PG8_SCHED;
	s_setprio 1
	s_waitcnt lgkmcnt(0)
	v_mfma_f32_16x16x32_bf16 v[60:63], v[152:155], v[184:187], v[60:63]
	v_mfma_f32_16x16x32_bf16 v[60:63], v[156:159], v[188:191], v[60:63]
	v_mfma_f32_16x16x32_bf16 v[56:59], v[164:167], v[188:191], v[56:59]
	v_mfma_f32_16x16x32_bf16 v[56:59], v[160:163], v[184:187], v[56:59]
	v_mfma_f32_16x16x32_bf16 v[52:55], v[168:171], v[184:187], v[52:55]
	v_mfma_f32_16x16x32_bf16 v[52:55], v[172:175], v[188:191], v[52:55]
	v_mfma_f32_16x16x32_bf16 v[48:51], v[180:183], v[188:191], v[48:51]
	v_mfma_f32_16x16x32_bf16 v[48:51], v[176:179], v[184:187], v[48:51]
	v_mfma_f32_16x16x32_bf16 v[32:35], v[176:179], v[192:195], v[32:35]
	v_mfma_f32_16x16x32_bf16 v[32:35], v[180:183], v[196:199], v[32:35]
	v_mfma_f32_16x16x32_bf16 v[36:39], v[172:175], v[196:199], v[36:39]
	v_mfma_f32_16x16x32_bf16 v[36:39], v[168:171], v[192:195], v[36:39]
	v_mfma_f32_16x16x32_bf16 v[40:43], v[160:163], v[192:195], v[40:43]
	v_mfma_f32_16x16x32_bf16 v[40:43], v[164:167], v[196:199], v[40:43]
	v_mfma_f32_16x16x32_bf16 v[44:47], v[156:159], v[196:199], v[44:47]
	v_mfma_f32_16x16x32_bf16 v[44:47], v[152:155], v[192:195], v[44:47]
	s_setprio 0
	s_setprio 1
	v_mfma_f32_16x16x32_bf16 v[28:31], v[152:155], v[200:203], v[28:31]
	v_mfma_f32_16x16x32_bf16 v[28:31], v[156:159], v[208:211], v[28:31]
	v_mfma_f32_16x16x32_bf16 v[24:27], v[164:167], v[208:211], v[24:27]
	v_mfma_f32_16x16x32_bf16 v[24:27], v[160:163], v[200:203], v[24:27]
	v_mfma_f32_16x16x32_bf16 v[20:23], v[168:171], v[200:203], v[20:23]
	v_mfma_f32_16x16x32_bf16 v[20:23], v[172:175], v[208:211], v[20:23]
	v_mfma_f32_16x16x32_bf16 v[16:19], v[180:183], v[208:211], v[16:19]
	v_mfma_f32_16x16x32_bf16 v[16:19], v[176:179], v[200:203], v[16:19]
	v_mfma_f32_16x16x32_bf16 v[0:3], v[176:179], v[212:215], v[0:3]
	v_mfma_f32_16x16x32_bf16 v[0:3], v[180:183], v[216:219], v[0:3]
	v_mfma_f32_16x16x32_bf16 v[4:7], v[172:175], v[216:219], v[4:7]
	v_mfma_f32_16x16x32_bf16 v[4:7], v[168:171], v[212:215], v[4:7]
	v_mfma_f32_16x16x32_bf16 v[8:11], v[160:163], v[212:215], v[8:11]
	v_mfma_f32_16x16x32_bf16 v[8:11], v[164:167], v[216:219], v[8:11]
	v_mfma_f32_16x16x32_bf16 v[12:15], v[156:159], v[216:219], v[12:15]
	v_mfma_f32_16x16x32_bf16 v[12:15], v[152:155], v[212:215], v[12:15]
	s_setprio 0
	s_barrier
	s_add_i32 s84, 0, 0x18000
	s_add_i32 s85, 0, 0x1c000
	v_add_u32_e32 v164, s84, v148
	v_add_u32_e32 v180, s85, v148
	ds_read_b128 v[152:155], v164
	ds_read_b128 v[156:159], v164 offset:1024
	ds_read_b128 v[160:163], v164 offset:2048
	ds_read_b128 v[164:167], v164 offset:3072
	ds_read_b128 v[168:171], v180
	ds_read_b128 v[172:175], v180 offset:1024
	ds_read_b128 v[176:179], v180 offset:2048
	ds_read_b128 v[180:183], v180 offset:3072
	s_add_u32 s48, s48, 0x10000
	s_addc_u32 s49, s49, 0
	s_mov_b32 m0, s58
	v_lshl_add_u64 v[230:231], s[48:49], 0, v[128:129]
	ds_read_b128 v[184:187], v151 offset:32768
	ds_read_b128 v[188:191], v151 offset:33792
	ds_read_b128 v[192:195], v151 offset:34816
	ds_read_b128 v[196:199], v151 offset:35840
	ds_read_b128 v[200:203], v151 offset:36864
	ds_read_b128 v[208:211], v151 offset:37888
	ds_read_b128 v[212:215], v151 offset:38912
	ds_read_b128 v[216:219], v151 offset:39936
	global_load_lds_dwordx4 v[230:231], off
	v_lshl_add_u64 v[230:231], s[48:49], 0, v[132:133]
	s_mov_b32 m0, s59
	s_nop 0
	global_load_lds_dwordx4 v[230:231], off
	s_waitcnt vmcnt(8)
	s_waitcnt lgkmcnt(0)
	s_barrier
	s_setprio 1
	s_waitcnt lgkmcnt(0)
	v_mfma_f32_16x16x32_bf16 v[120:123], v[152:155], v[184:187], v[120:123]
	v_mfma_f32_16x16x32_bf16 v[120:123], v[156:159], v[188:191], v[120:123]
	v_mfma_f32_16x16x32_bf16 v[124:127], v[164:167], v[188:191], v[124:127]
	v_mfma_f32_16x16x32_bf16 v[124:127], v[160:163], v[184:187], v[124:127]
	v_mfma_f32_16x16x32_bf16 v[116:119], v[168:171], v[184:187], v[116:119]
	v_mfma_f32_16x16x32_bf16 v[116:119], v[172:175], v[188:191], v[116:119]
	v_mfma_f32_16x16x32_bf16 v[112:115], v[180:183], v[188:191], v[112:115]
	v_mfma_f32_16x16x32_bf16 v[112:115], v[176:179], v[184:187], v[112:115]
	v_mfma_f32_16x16x32_bf16 v[96:99], v[176:179], v[192:195], v[96:99]
	v_mfma_f32_16x16x32_bf16 v[96:99], v[180:183], v[196:199], v[96:99]
	v_mfma_f32_16x16x32_bf16 v[100:103], v[172:175], v[196:199], v[100:103]
	v_mfma_f32_16x16x32_bf16 v[100:103], v[168:171], v[192:195], v[100:103]
	v_mfma_f32_16x16x32_bf16 v[104:107], v[160:163], v[192:195], v[104:107]
	v_mfma_f32_16x16x32_bf16 v[104:107], v[164:167], v[196:199], v[104:107]
	v_mfma_f32_16x16x32_bf16 v[108:111], v[156:159], v[196:199], v[108:111]
	v_mfma_f32_16x16x32_bf16 v[108:111], v[152:155], v[192:195], v[108:111]
	s_setprio 0
	s_setprio 1
	v_mfma_f32_16x16x32_bf16 v[92:95], v[152:155], v[200:203], v[92:95]
	v_mfma_f32_16x16x32_bf16 v[92:95], v[156:159], v[208:211], v[92:95]
	v_mfma_f32_16x16x32_bf16 v[88:91], v[164:167], v[208:211], v[88:91]
	v_mfma_f32_16x16x32_bf16 v[88:91], v[160:163], v[200:203], v[88:91]
	v_mfma_f32_16x16x32_bf16 v[84:87], v[168:171], v[200:203], v[84:87]
	v_mfma_f32_16x16x32_bf16 v[84:87], v[172:175], v[208:211], v[84:87]
	v_mfma_f32_16x16x32_bf16 v[80:83], v[180:183], v[208:211], v[80:83]
	v_mfma_f32_16x16x32_bf16 v[80:83], v[176:179], v[200:203], v[80:83]
	v_mfma_f32_16x16x32_bf16 v[64:67], v[176:179], v[212:215], v[64:67]
	v_mfma_f32_16x16x32_bf16 v[64:67], v[180:183], v[216:219], v[64:67]
	v_mfma_f32_16x16x32_bf16 v[68:71], v[172:175], v[216:219], v[68:71]
	v_mfma_f32_16x16x32_bf16 v[68:71], v[168:171], v[212:215], v[68:71]
	v_mfma_f32_16x16x32_bf16 v[72:75], v[160:163], v[212:215], v[72:75]
	v_mfma_f32_16x16x32_bf16 v[72:75], v[164:167], v[216:219], v[72:75]
	v_mfma_f32_16x16x32_bf16 v[76:79], v[156:159], v[216:219], v[76:79]
	v_mfma_f32_16x16x32_bf16 v[76:79], v[152:155], v[212:215], v[76:79]
	s_setprio 0
	s_barrier
; #define PG8_STAGE(bufoff, gbase, voff) do { _Pragma("unroll") for (int _i = 0; _i < 2; ++_i) \
;         __builtin_amdgcn_global_load_lds((const unsigned*)((const char*)(gbase) + (voff)[_i]), (LAS unsigned*)(lds + (bufoff) + ldsw + _i * 8192), 16, 0, 0); } while (0)
; #define PG8_LDA(dst, b, h) do { _Pragma("unroll") for (int m = 0; m < 4; ++m) _Pragma("unroll") for (int k = 0; k < 2; ++k) dst[m][k] = *(const LAS bf16x8*)(lds + PG8_SA(b, h) + aoff + m * 2048 + k * 1024); } while (0)
; #define PG8_MMA(ai, bj, At, Bt) do { __builtin_amdgcn_s_setprio(1); _Pragma("unroll") for (int m = 0; m < 4; ++m) _Pragma("unroll") for (int n = 0; n < 2; ++n) _Pragma("unroll") for (int k = 0; k < 2; ++k) \
;         acc[ai][bj][m][n] = __builtin_amdgcn_mfma_f32_16x16x32_bf16(Bt[n][k], At[m][k], acc[ai][bj][m][n], 0, 0, 0); __builtin_amdgcn_s_setprio(0); } while (0)
; #define PG8_WAIT_V(n) asm volatile("s_waitcnt vmcnt(" #n ")" ::: "memory")
; #define PG8_WAIT_L(n) asm volatile("s_waitcnt lgkmcnt(" #n ")" ::: "memory")
; #define PG8_BAR __builtin_amdgcn_s_barrier()
; #define PG8_SCHED __builtin_amdgcn_sched_barrier(0)
; template <class Epi>
; __device__ __forceinline__ void gemm_phase(LAS unsigned char* lds, const Gemm g, const StaticOrder& S, const Epi& E) {
;     ...
;             PG8_LDA(At, 1, 1); PG8_STAGE(PG8_SB(1, 0), b3, voffB); PG8_STAGE(PG8_SB(1, 1), b3 + hstepB, voffB); PG8_STAGE(PG8_SA(1, 0), a3, voffA);
;             PG8_WAIT_V(8); PG8_WAIT_L(0); PG8_BAR; PG8_MMA(1, 0, At, B0); PG8_MMA(1, 1, At, B1); PG8_BAR; PG8_SCHED;
;         }
	s_add_i32 s48, s84, s51
	v_lshl_add_u64 v[220:221], v[220:221], 0, s[12:13]
	s_mov_b32 m0, s48
	ds_read_b128 v[184:187], v151 offset:49152
	ds_read_b128 v[188:191], v151 offset:50176
	ds_read_b128 v[192:195], v151 offset:51200
	ds_read_b128 v[196:199], v151 offset:52224
	ds_read_b128 v[200:203], v151 offset:53248
	ds_read_b128 v[208:211], v151 offset:54272
	ds_read_b128 v[212:215], v151 offset:55296
	ds_read_b128 v[216:219], v151 offset:56320
	global_load_lds_dwordx4 v[220:221], off
	s_add_i32 m0, s48, 0x2000
	s_add_u32 s46, s46, 0x10080
	v_lshl_add_u64 v[220:221], v[222:223], 0, s[12:13]
	s_addc_u32 s47, s47, 0
	s_add_i32 s48, s85, s51
	global_load_lds_dwordx4 v[220:221], off
	v_lshl_add_u64 v[220:221], s[46:47], 0, v[130:131]
	s_mov_b32 m0, s48
	s_nop 0
	global_load_lds_dwordx4 v[220:221], off
	v_lshl_add_u64 v[220:221], s[46:47], 0, v[134:135]
	s_add_i32 m0, s48, 0x2000
	s_nop 0
	global_load_lds_dwordx4 v[220:221], off
	v_lshl_add_u64 v[220:221], v[224:225], 0, s[12:13]
	s_mov_b32 m0, s63
	s_nop 0
	global_load_lds_dwordx4 v[220:221], off
	v_lshl_add_u64 v[220:221], v[226:227], 0, s[12:13]
	s_mov_b32 m0, s64
	s_nop 0
	global_load_lds_dwordx4 v[220:221], off
	s_waitcnt vmcnt(8)
	s_waitcnt lgkmcnt(0)
	s_barrier
	s_setprio 1
	s_waitcnt lgkmcnt(0)
	v_mfma_f32_16x16x32_bf16 v[60:63], v[152:155], v[184:187], v[60:63]
	v_mfma_f32_16x16x32_bf16 v[60:63], v[156:159], v[188:191], v[60:63]
	v_mfma_f32_16x16x32_bf16 v[56:59], v[164:167], v[188:191], v[56:59]
	v_mfma_f32_16x16x32_bf16 v[56:59], v[160:163], v[184:187], v[56:59]
	v_mfma_f32_16x16x32_bf16 v[52:55], v[168:171], v[184:187], v[52:55]
	v_mfma_f32_16x16x32_bf16 v[52:55], v[172:175], v[188:191], v[52:55]
	v_mfma_f32_16x16x32_bf16 v[48:51], v[180:183], v[188:191], v[48:51]
	v_mfma_f32_16x16x32_bf16 v[48:51], v[176:179], v[184:187], v[48:51]
	v_mfma_f32_16x16x32_bf16 v[32:35], v[176:179], v[192:195], v[32:35]
	v_mfma_f32_16x16x32_bf16 v[32:35], v[180:183], v[196:199], v[32:35]
	v_mfma_f32_16x16x32_bf16 v[36:39], v[172:175], v[196:199], v[36:39]
	v_mfma_f32_16x16x32_bf16 v[36:39], v[168:171], v[192:195], v[36:39]
	v_mfma_f32_16x16x32_bf16 v[40:43], v[160:163], v[192:195], v[40:43]
	v_mfma_f32_16x16x32_bf16 v[40:43], v[164:167], v[196:199], v[40:43]
	v_mfma_f32_16x16x32_bf16 v[44:47], v[156:159], v[196:199], v[44:47]
	v_mfma_f32_16x16x32_bf16 v[44:47], v[152:155], v[192:195], v[44:47]
	s_setprio 0
	s_setprio 1
	v_mfma_f32_16x16x32_bf16 v[28:31], v[152:155], v[200:203], v[28:31]
	v_mfma_f32_16x16x32_bf16 v[28:31], v[156:159], v[208:211], v[28:31]
	v_mfma_f32_16x16x32_bf16 v[24:27], v[164:167], v[208:211], v[24:27]
	v_mfma_f32_16x16x32_bf16 v[24:27], v[160:163], v[200:203], v[24:27]
	v_mfma_f32_16x16x32_bf16 v[20:23], v[168:171], v[200:203], v[20:23]
	v_mfma_f32_16x16x32_bf16 v[20:23], v[172:175], v[208:211], v[20:23]
	v_mfma_f32_16x16x32_bf16 v[16:19], v[180:183], v[208:211], v[16:19]
	v_mfma_f32_16x16x32_bf16 v[16:19], v[176:179], v[200:203], v[16:19]
	v_mfma_f32_16x16x32_bf16 v[0:3], v[176:179], v[212:215], v[0:3]
	v_mfma_f32_16x16x32_bf16 v[0:3], v[180:183], v[216:219], v[0:3]
	v_mfma_f32_16x16x32_bf16 v[4:7], v[172:175], v[216:219], v[4:7]
	v_mfma_f32_16x16x32_bf16 v[4:7], v[168:171], v[212:215], v[4:7]
	v_mfma_f32_16x16x32_bf16 v[8:11], v[160:163], v[212:215], v[8:11]
	v_mfma_f32_16x16x32_bf16 v[8:11], v[164:167], v[216:219], v[8:11]
	v_mfma_f32_16x16x32_bf16 v[12:15], v[156:159], v[216:219], v[12:15]
	v_mfma_f32_16x16x32_bf16 v[12:15], v[152:155], v[212:215], v[12:15]
	s_setprio 0
	s_barrier
	s_add_u32 s44, s44, 0x100
	s_addc_u32 s45, s45, 0
	s_add_u32 s79, s79, 0x100
	s_addc_u32 s82, s82, 0
	s_cmp_ge_i32 s83, s61
	s_mov_b32 s46, s83
	s_cbranch_scc0 .LBB0_1161

; #define PG8_STAGE(bufoff, gbase, voff) do { _Pragma("unroll") for (int _i = 0; _i < 2; ++_i) \
;         __builtin_amdgcn_global_load_lds((const unsigned*)((const char*)(gbase) + (voff)[_i]), (LAS unsigned*)(lds + (bufoff) + ldsw + _i * 8192), 16, 0, 0); } while (0)
; #define PG8_LDA(dst, b, h) do { _Pragma("unroll") for (int m = 0; m < 4; ++m) _Pragma("unroll") for (int k = 0; k < 2; ++k) dst[m][k] = *(const LAS bf16x8*)(lds + PG8_SA(b, h) + aoff + m * 2048 + k * 1024); } while (0)
; #define PG8_LDB(dst, b, h) do { _Pragma("unroll") for (int n = 0; n < 2; ++n) _Pragma("unroll") for (int k = 0; k < 2; ++k) dst[n][k] = *(const LAS bf16x8*)(lds + PG8_SB(b, h) + boff + n * 2048 + k * 1024); } while (0)
; #define PG8_MMA(ai, bj, At, Bt) do { __builtin_amdgcn_s_setprio(1); _Pragma("unroll") for (int m = 0; m < 4; ++m) _Pragma("unroll") for (int n = 0; n < 2; ++n) _Pragma("unroll") for (int k = 0; k < 2; ++k) \
;         acc[ai][bj][m][n] = __builtin_amdgcn_mfma_f32_16x16x32_bf16(Bt[n][k], At[m][k], acc[ai][bj][m][n], 0, 0, 0); __builtin_amdgcn_s_setprio(0); } while (0)
; #define PG8_WAIT_V(n) asm volatile("s_waitcnt vmcnt(" #n ")" ::: "memory")
; #define PG8_WAIT_L(n) asm volatile("s_waitcnt lgkmcnt(" #n ")" ::: "memory")
; #define PG8_BAR __builtin_amdgcn_s_barrier()
; template <class Epi>
; __device__ __forceinline__ void gemm_phase(LAS unsigned char* lds, const Gemm g, const StaticOrder& S, const Epi& E) {
;     ...
;         const bool has_next = S.next(ui + 1, nxt);
;         const char* nA = has_next ? (const char*)g.A + (size_t)nxt.pm * tstepA : cA; const char* nB = has_next ? (const char*)g.Bt + (size_t)nxt.pb * tstepB : cB;
;         for (int t = 0; t < nt; t += 2) {
;             const bool last = (t == nt - 2);
;             const char* a1 = cA + (size_t)(t + 1) * kstep;
;             const char* a2 = last ? nA : cA + (size_t)(t + 2) * kstep; const char* b2 = last ? nB : cB + (size_t)(t + 2) * kstep;
;             const char* a3 = a2 + kstep; const char* b3 = b2 + kstep;
;             PG8_LDB(B0, 0, 0); PG8_LDB(B1, 0, 1); PG8_SCHED; PG8_LDA(At, 0, 0); PG8_STAGE(PG8_SA(1, 1), a1 + hstepA, voffA);
;             PG8_WAIT_V(8); PG8_WAIT_L(0); PG8_BAR; PG8_MMA(0, 0, At, B0); PG8_MMA(0, 1, At, B1); PG8_BAR; PG8_SCHED;
;             PG8_LDA(At, 0, 1); PG8_STAGE(PG8_SB(0, 0), b2, voffB); PG8_STAGE(PG8_SB(0, 1), b2 + hstepB, voffB); PG8_STAGE(PG8_SA(0, 0), a2, voffA);
.LBB0_1244:
	ds_read_b128 v[150:153], v187
	ds_read_b128 v[154:157], v187 offset:1024
	ds_read_b128 v[158:161], v187 offset:2048
	ds_read_b128 v[162:165], v187 offset:3072
	ds_read_b128 v[166:169], v188
	ds_read_b128 v[170:173], v188 offset:1024
	ds_read_b128 v[174:177], v188 offset:2048
	ds_read_b128 v[178:181], v188 offset:3072
	s_add_i32 s84, s52, 2
	s_add_u32 s12, s4, 0x100
	s_addc_u32 s13, s5, 0
	s_cmp_eq_u32 s67, s52
	s_cselect_b32 s52, s50, s1
	s_cselect_b32 s55, s49, s13
	s_cselect_b32 s54, s48, s12
	s_cselect_b32 s53, s51, s77
	v_lshl_add_u64 v[224:225], s[4:5], 0, v[142:143]
	s_add_i32 m0, s59, 0xc000
	ds_read_b128 v[182:185], v189
	ds_read_b128 v[192:195], v189 offset:1024
	ds_read_b128 v[196:199], v189 offset:2048
	ds_read_b128 v[200:203], v189 offset:3072
	ds_read_b128 v[208:211], v189 offset:4096
	ds_read_b128 v[212:215], v189 offset:5120
	ds_read_b128 v[216:219], v189 offset:6144
	ds_read_b128 v[220:223], v189 offset:7168
	global_load_lds_dwordx4 v[224:225], off
	v_lshl_add_u64 v[224:225], s[4:5], 0, v[144:145]
	s_add_i32 m0, s59, 0xe000
	s_nop 0
	global_load_lds_dwordx4 v[224:225], off
	s_waitcnt vmcnt(8)
	s_waitcnt lgkmcnt(0)
	s_barrier
	s_setprio 1
	s_waitcnt lgkmcnt(0)
	v_mfma_f32_16x16x32_bf16 v[124:127], v[150:153], v[182:185], v[124:127]
	v_mfma_f32_16x16x32_bf16 v[124:127], v[154:157], v[192:195], v[124:127]
	v_mfma_f32_16x16x32_bf16 v[120:123], v[162:165], v[192:195], v[120:123]
	v_mfma_f32_16x16x32_bf16 v[120:123], v[158:161], v[182:185], v[120:123]
	v_mfma_f32_16x16x32_bf16 v[108:111], v[166:169], v[182:185], v[108:111]
	v_mfma_f32_16x16x32_bf16 v[108:111], v[170:173], v[192:195], v[108:111]
	v_mfma_f32_16x16x32_bf16 v[100:103], v[178:181], v[192:195], v[100:103]
	v_mfma_f32_16x16x32_bf16 v[100:103], v[174:177], v[182:185], v[100:103]
	v_mfma_f32_16x16x32_bf16 v[84:87], v[174:177], v[196:199], v[84:87]
	v_mfma_f32_16x16x32_bf16 v[84:87], v[178:181], v[200:203], v[84:87]
	v_mfma_f32_16x16x32_bf16 v[92:95], v[170:173], v[200:203], v[92:95]
	v_mfma_f32_16x16x32_bf16 v[92:95], v[166:169], v[196:199], v[92:95]
	v_mfma_f32_16x16x32_bf16 v[112:115], v[158:161], v[196:199], v[112:115]
	v_mfma_f32_16x16x32_bf16 v[112:115], v[162:165], v[200:203], v[112:115]
	v_mfma_f32_16x16x32_bf16 v[116:119], v[154:157], v[200:203], v[116:119]
	v_mfma_f32_16x16x32_bf16 v[116:119], v[150:153], v[196:199], v[116:119]
	s_setprio 0
	s_setprio 1
	v_mfma_f32_16x16x32_bf16 v[104:107], v[150:153], v[208:211], v[104:107]
	v_mfma_f32_16x16x32_bf16 v[104:107], v[154:157], v[212:215], v[104:107]
	v_mfma_f32_16x16x32_bf16 v[96:99], v[162:165], v[212:215], v[96:99]
	v_mfma_f32_16x16x32_bf16 v[96:99], v[158:161], v[208:211], v[96:99]
	v_mfma_f32_16x16x32_bf16 v[76:79], v[166:169], v[208:211], v[76:79]
	v_mfma_f32_16x16x32_bf16 v[76:79], v[170:173], v[212:215], v[76:79]
	v_mfma_f32_16x16x32_bf16 v[72:75], v[178:181], v[212:215], v[72:75]
	v_mfma_f32_16x16x32_bf16 v[72:75], v[174:177], v[208:211], v[72:75]
	v_mfma_f32_16x16x32_bf16 v[64:67], v[174:177], v[216:219], v[64:67]
	v_mfma_f32_16x16x32_bf16 v[64:67], v[178:181], v[220:223], v[64:67]
	v_mfma_f32_16x16x32_bf16 v[68:71], v[170:173], v[220:223], v[68:71]
	v_mfma_f32_16x16x32_bf16 v[68:71], v[166:169], v[216:219], v[68:71]
	v_mfma_f32_16x16x32_bf16 v[80:83], v[158:161], v[216:219], v[80:83]
	v_mfma_f32_16x16x32_bf16 v[80:83], v[162:165], v[220:223], v[80:83]
	v_mfma_f32_16x16x32_bf16 v[88:91], v[154:157], v[220:223], v[88:91]
	v_mfma_f32_16x16x32_bf16 v[88:91], v[150:153], v[216:219], v[88:91]
	s_setprio 0
	s_barrier
	s_add_i32 s4, s70, s58
	v_lshl_add_u64 v[224:225], s[52:53], 0, v[130:131]
	s_mov_b32 m0, s4
	ds_read_b128 v[182:185], v189 offset:16384
	ds_read_b128 v[192:195], v189 offset:17408
	ds_read_b128 v[196:199], v189 offset:18432
	ds_read_b128 v[200:203], v189 offset:19456
	ds_read_b128 v[208:211], v189 offset:20480
	ds_read_b128 v[212:215], v189 offset:21504
	ds_read_b128 v[216:219], v189 offset:22528
	ds_read_b128 v[220:223], v189 offset:23552
	global_load_lds_dwordx4 v[224:225], off
	s_add_i32 m0, s4, 0x2000
	s_add_u32 s4, s52, 0x158000
	v_lshl_add_u64 v[226:227], s[52:53], 0, v[134:135]
	s_addc_u32 s5, s53, 0
	s_add_i32 s85, s71, s58
	global_load_lds_dwordx4 v[226:227], off
	v_lshl_add_u64 v[230:231], s[4:5], 0, v[130:131]
	s_mov_b32 m0, s85
	v_lshl_add_u64 v[232:233], s[54:55], 0, v[132:133]
	global_load_lds_dwordx4 v[230:231], off
	v_lshl_add_u64 v[230:231], s[4:5], 0, v[134:135]
	s_add_i32 m0, s85, 0x2000
	s_nop 0
	global_load_lds_dwordx4 v[230:231], off
	v_lshl_add_u64 v[230:231], s[54:55], 0, v[128:129]
	s_mov_b32 m0, s59
	s_nop 0
	global_load_lds_dwordx4 v[230:231], off
	s_mov_b32 m0, s60
	s_nop 0
	global_load_lds_dwordx4 v[232:233], off
	s_waitcnt vmcnt(8)
	s_waitcnt lgkmcnt(0)
	s_barrier
; #define PG8_STAGE(bufoff, gbase, voff) do { _Pragma("unroll") for (int _i = 0; _i < 2; ++_i) \
;         __builtin_amdgcn_global_load_lds((const unsigned*)((const char*)(gbase) + (voff)[_i]), (LAS unsigned*)(lds + (bufoff) + ldsw + _i * 8192), 16, 0, 0); } while (0)
; #define PG8_LDA(dst, b, h) do { _Pragma("unroll") for (int m = 0; m < 4; ++m) _Pragma("unroll") for (int k = 0; k < 2; ++k) dst[m][k] = *(const LAS bf16x8*)(lds + PG8_SA(b, h) + aoff + m * 2048 + k * 1024); } while (0)
; #define PG8_LDB(dst, b, h) do { _Pragma("unroll") for (int n = 0; n < 2; ++n) _Pragma("unroll") for (int k = 0; k < 2; ++k) dst[n][k] = *(const LAS bf16x8*)(lds + PG8_SB(b, h) + boff + n * 2048 + k * 1024); } while (0)
; #define PG8_MMA(ai, bj, At, Bt) do { __builtin_amdgcn_s_setprio(1); _Pragma("unroll") for (int m = 0; m < 4; ++m) _Pragma("unroll") for (int n = 0; n < 2; ++n) _Pragma("unroll") for (int k = 0; k < 2; ++k) \
;         acc[ai][bj][m][n] = __builtin_amdgcn_mfma_f32_16x16x32_bf16(Bt[n][k], At[m][k], acc[ai][bj][m][n], 0, 0, 0); __builtin_amdgcn_s_setprio(0); } while (0)
; #define PG8_WAIT_V(n) asm volatile("s_waitcnt vmcnt(" #n ")" ::: "memory")
; #define PG8_WAIT_L(n) asm volatile("s_waitcnt lgkmcnt(" #n ")" ::: "memory")
; #define PG8_BAR __builtin_amdgcn_s_barrier()
; #define PG8_SCHED __builtin_amdgcn_sched_barrier(0)
; template <class Epi>
; __device__ __forceinline__ void gemm_phase(LAS unsigned char* lds, const Gemm g, const StaticOrder& S, const Epi& E) {
;     ...
;             PG8_WAIT_V(8); PG8_WAIT_L(0); PG8_BAR; PG8_MMA(1, 0, At, B0); PG8_MMA(1, 1, At, B1); PG8_BAR; PG8_SCHED;
;             PG8_LDB(B0, 1, 0); PG8_LDB(B1, 1, 1); PG8_SCHED; PG8_LDA(At, 1, 0); PG8_STAGE(PG8_SA(0, 1), a2 + hstepA, voffA);
;             PG8_WAIT_V(8); PG8_WAIT_L(0); PG8_BAR; PG8_MMA(0, 0, At, B0); PG8_MMA(0, 1, At, B1); PG8_BAR; PG8_SCHED;
;             PG8_LDA(At, 1, 1); PG8_STAGE(PG8_SB(1, 0), b3, voffB); PG8_STAGE(PG8_SB(1, 1), b3 + hstepB, voffB); PG8_STAGE(PG8_SA(1, 0), a3, voffA);
	s_setprio 1
	s_waitcnt lgkmcnt(0)
	v_mfma_f32_16x16x32_bf16 v[60:63], v[150:153], v[182:185], v[60:63]
	v_mfma_f32_16x16x32_bf16 v[60:63], v[154:157], v[192:195], v[60:63]
	v_mfma_f32_16x16x32_bf16 v[56:59], v[162:165], v[192:195], v[56:59]
	v_mfma_f32_16x16x32_bf16 v[56:59], v[158:161], v[182:185], v[56:59]
	v_mfma_f32_16x16x32_bf16 v[44:47], v[166:169], v[182:185], v[44:47]
	v_mfma_f32_16x16x32_bf16 v[44:47], v[170:173], v[192:195], v[44:47]
	v_mfma_f32_16x16x32_bf16 v[36:39], v[178:181], v[192:195], v[36:39]
	v_mfma_f32_16x16x32_bf16 v[36:39], v[174:177], v[182:185], v[36:39]
	v_mfma_f32_16x16x32_bf16 v[20:23], v[174:177], v[196:199], v[20:23]
	v_mfma_f32_16x16x32_bf16 v[20:23], v[178:181], v[200:203], v[20:23]
	v_mfma_f32_16x16x32_bf16 v[28:31], v[170:173], v[200:203], v[28:31]
	v_mfma_f32_16x16x32_bf16 v[28:31], v[166:169], v[196:199], v[28:31]
	v_mfma_f32_16x16x32_bf16 v[48:51], v[158:161], v[196:199], v[48:51]
	v_mfma_f32_16x16x32_bf16 v[48:51], v[162:165], v[200:203], v[48:51]
	v_mfma_f32_16x16x32_bf16 v[52:55], v[154:157], v[200:203], v[52:55]
	v_mfma_f32_16x16x32_bf16 v[52:55], v[150:153], v[196:199], v[52:55]
	s_setprio 0
	s_setprio 1
	v_mfma_f32_16x16x32_bf16 v[40:43], v[150:153], v[208:211], v[40:43]
	v_mfma_f32_16x16x32_bf16 v[40:43], v[154:157], v[212:215], v[40:43]
	v_mfma_f32_16x16x32_bf16 v[32:35], v[162:165], v[212:215], v[32:35]
	v_mfma_f32_16x16x32_bf16 v[32:35], v[158:161], v[208:211], v[32:35]
	v_mfma_f32_16x16x32_bf16 v[12:15], v[166:169], v[208:211], v[12:15]
	v_mfma_f32_16x16x32_bf16 v[12:15], v[170:173], v[212:215], v[12:15]
	v_mfma_f32_16x16x32_bf16 v[8:11], v[178:181], v[212:215], v[8:11]
	v_mfma_f32_16x16x32_bf16 v[8:11], v[174:177], v[208:211], v[8:11]
	v_mfma_f32_16x16x32_bf16 v[0:3], v[174:177], v[216:219], v[0:3]
	v_mfma_f32_16x16x32_bf16 v[0:3], v[178:181], v[220:223], v[0:3]
	v_mfma_f32_16x16x32_bf16 v[4:7], v[170:173], v[220:223], v[4:7]
	v_mfma_f32_16x16x32_bf16 v[4:7], v[166:169], v[216:219], v[4:7]
	v_mfma_f32_16x16x32_bf16 v[16:19], v[158:161], v[216:219], v[16:19]
	v_mfma_f32_16x16x32_bf16 v[16:19], v[162:165], v[220:223], v[16:19]
	v_mfma_f32_16x16x32_bf16 v[24:27], v[154:157], v[220:223], v[24:27]
	v_mfma_f32_16x16x32_bf16 v[24:27], v[150:153], v[216:219], v[24:27]
	s_setprio 0
	s_barrier
	s_add_i32 s85, 0, 0x18000
	s_add_i32 s86, 0, 0x1c000
	v_add_u32_e32 v162, s85, v186
	v_add_u32_e32 v178, s86, v186
	ds_read_b128 v[150:153], v162
	ds_read_b128 v[154:157], v162 offset:1024
	ds_read_b128 v[158:161], v162 offset:2048
	ds_read_b128 v[162:165], v162 offset:3072
	ds_read_b128 v[166:169], v178
	ds_read_b128 v[170:173], v178 offset:1024
	ds_read_b128 v[174:177], v178 offset:2048
	ds_read_b128 v[178:181], v178 offset:3072
	s_add_u32 s4, s54, 0x158000
	s_addc_u32 s5, s55, 0
	s_mov_b32 m0, s61
	v_lshl_add_u64 v[234:235], s[4:5], 0, v[128:129]
	ds_read_b128 v[182:185], v189 offset:32768
	ds_read_b128 v[192:195], v189 offset:33792
	ds_read_b128 v[196:199], v189 offset:34816
	ds_read_b128 v[200:203], v189 offset:35840
	ds_read_b128 v[208:211], v189 offset:36864
	ds_read_b128 v[212:215], v189 offset:37888
	ds_read_b128 v[216:219], v189 offset:38912
	ds_read_b128 v[220:223], v189 offset:39936
	global_load_lds_dwordx4 v[234:235], off
	v_lshl_add_u64 v[234:235], s[4:5], 0, v[132:133]
	s_mov_b32 m0, s62
	s_nop 0
	global_load_lds_dwordx4 v[234:235], off
	s_waitcnt vmcnt(8)
	s_waitcnt lgkmcnt(0)
	s_barrier
	s_setprio 1
	s_waitcnt lgkmcnt(0)
	v_mfma_f32_16x16x32_bf16 v[124:127], v[150:153], v[182:185], v[124:127]
	v_mfma_f32_16x16x32_bf16 v[124:127], v[154:157], v[192:195], v[124:127]
	v_mfma_f32_16x16x32_bf16 v[120:123], v[162:165], v[192:195], v[120:123]
	v_mfma_f32_16x16x32_bf16 v[120:123], v[158:161], v[182:185], v[120:123]
	v_mfma_f32_16x16x32_bf16 v[108:111], v[166:169], v[182:185], v[108:111]
	v_mfma_f32_16x16x32_bf16 v[108:111], v[170:173], v[192:195], v[108:111]
	v_mfma_f32_16x16x32_bf16 v[100:103], v[178:181], v[192:195], v[100:103]
	v_mfma_f32_16x16x32_bf16 v[100:103], v[174:177], v[182:185], v[100:103]
	v_mfma_f32_16x16x32_bf16 v[84:87], v[174:177], v[196:199], v[84:87]
	v_mfma_f32_16x16x32_bf16 v[84:87], v[178:181], v[200:203], v[84:87]
	v_mfma_f32_16x16x32_bf16 v[92:95], v[170:173], v[200:203], v[92:95]
	v_mfma_f32_16x16x32_bf16 v[92:95], v[166:169], v[196:199], v[92:95]
	v_mfma_f32_16x16x32_bf16 v[112:115], v[158:161], v[196:199], v[112:115]
	v_mfma_f32_16x16x32_bf16 v[112:115], v[162:165], v[200:203], v[112:115]
	v_mfma_f32_16x16x32_bf16 v[116:119], v[154:157], v[200:203], v[116:119]
	v_mfma_f32_16x16x32_bf16 v[116:119], v[150:153], v[196:199], v[116:119]
	s_setprio 0
	s_setprio 1
	v_mfma_f32_16x16x32_bf16 v[104:107], v[150:153], v[208:211], v[104:107]
	v_mfma_f32_16x16x32_bf16 v[104:107], v[154:157], v[212:215], v[104:107]
	v_mfma_f32_16x16x32_bf16 v[96:99], v[162:165], v[212:215], v[96:99]
	v_mfma_f32_16x16x32_bf16 v[96:99], v[158:161], v[208:211], v[96:99]
	v_mfma_f32_16x16x32_bf16 v[76:79], v[166:169], v[208:211], v[76:79]
	v_mfma_f32_16x16x32_bf16 v[76:79], v[170:173], v[212:215], v[76:79]
	v_mfma_f32_16x16x32_bf16 v[72:75], v[178:181], v[212:215], v[72:75]
	v_mfma_f32_16x16x32_bf16 v[72:75], v[174:177], v[208:211], v[72:75]
	v_mfma_f32_16x16x32_bf16 v[64:67], v[174:177], v[216:219], v[64:67]
	v_mfma_f32_16x16x32_bf16 v[64:67], v[178:181], v[220:223], v[64:67]
	v_mfma_f32_16x16x32_bf16 v[68:71], v[170:173], v[220:223], v[68:71]
	v_mfma_f32_16x16x32_bf16 v[68:71], v[166:169], v[216:219], v[68:71]
	v_mfma_f32_16x16x32_bf16 v[80:83], v[158:161], v[216:219], v[80:83]
	v_mfma_f32_16x16x32_bf16 v[80:83], v[162:165], v[220:223], v[80:83]
	v_mfma_f32_16x16x32_bf16 v[88:91], v[154:157], v[220:223], v[88:91]
	v_mfma_f32_16x16x32_bf16 v[88:91], v[150:153], v[216:219], v[88:91]
	s_setprio 0
	s_barrier
; #define PG8_STAGE(bufoff, gbase, voff) do { _Pragma("unroll") for (int _i = 0; _i < 2; ++_i) \
;         __builtin_amdgcn_global_load_lds((const unsigned*)((const char*)(gbase) + (voff)[_i]), (LAS unsigned*)(lds + (bufoff) + ldsw + _i * 8192), 16, 0, 0); } while (0)
; #define PG8_LDA(dst, b, h) do { _Pragma("unroll") for (int m = 0; m < 4; ++m) _Pragma("unroll") for (int k = 0; k < 2; ++k) dst[m][k] = *(const LAS bf16x8*)(lds + PG8_SA(b, h) + aoff + m * 2048 + k * 1024); } while (0)
; #define PG8_MMA(ai, bj, At, Bt) do { __builtin_amdgcn_s_setprio(1); _Pragma("unroll") for (int m = 0; m < 4; ++m) _Pragma("unroll") for (int n = 0; n < 2; ++n) _Pragma("unroll") for (int k = 0; k < 2; ++k) \
;         acc[ai][bj][m][n] = __builtin_amdgcn_mfma_f32_16x16x32_bf16(Bt[n][k], At[m][k], acc[ai][bj][m][n], 0, 0, 0); __builtin_amdgcn_s_setprio(0); } while (0)
; #define PG8_WAIT_V(n) asm volatile("s_waitcnt vmcnt(" #n ")" ::: "memory")
; #define PG8_WAIT_L(n) asm volatile("s_waitcnt lgkmcnt(" #n ")" ::: "memory")
; #define PG8_BAR __builtin_amdgcn_s_barrier()
; #define PG8_SCHED __builtin_amdgcn_sched_barrier(0)
; template <class Epi>
; __device__ __forceinline__ void gemm_phase(LAS unsigned char* lds, const Gemm g, const StaticOrder& S, const Epi& E) {
;     ...
;             PG8_LDA(At, 1, 1); PG8_STAGE(PG8_SB(1, 0), b3, voffB); PG8_STAGE(PG8_SB(1, 1), b3 + hstepB, voffB); PG8_STAGE(PG8_SA(1, 0), a3, voffA);
;             PG8_WAIT_V(8); PG8_WAIT_L(0); PG8_BAR; PG8_MMA(1, 0, At, B0); PG8_MMA(1, 1, At, B1); PG8_BAR; PG8_SCHED;
;         }
	s_add_i32 s4, s85, s58
	v_lshl_add_u64 v[224:225], v[224:225], 0, s[16:17]
	s_mov_b32 m0, s4
	ds_read_b128 v[182:185], v189 offset:49152
	ds_read_b128 v[192:195], v189 offset:50176
	ds_read_b128 v[196:199], v189 offset:51200
	ds_read_b128 v[200:203], v189 offset:52224
	ds_read_b128 v[208:211], v189 offset:53248
	ds_read_b128 v[212:215], v189 offset:54272
	ds_read_b128 v[216:219], v189 offset:55296
	ds_read_b128 v[220:223], v189 offset:56320
	global_load_lds_dwordx4 v[224:225], off
	s_add_i32 m0, s4, 0x2000
	s_add_u32 s4, s52, 0x158080
	v_lshl_add_u64 v[224:225], v[226:227], 0, s[16:17]
	s_addc_u32 s5, s53, 0
	s_add_i32 s52, s86, s58
	global_load_lds_dwordx4 v[224:225], off
	v_lshl_add_u64 v[224:225], s[4:5], 0, v[130:131]
	s_mov_b32 m0, s52
	s_nop 0
	global_load_lds_dwordx4 v[224:225], off
	v_lshl_add_u64 v[224:225], s[4:5], 0, v[134:135]
	s_add_i32 m0, s52, 0x2000
	s_nop 0
	global_load_lds_dwordx4 v[224:225], off
	v_lshl_add_u64 v[224:225], v[230:231], 0, s[16:17]
	s_mov_b32 m0, s65
	s_nop 0
	global_load_lds_dwordx4 v[224:225], off
	v_lshl_add_u64 v[224:225], v[232:233], 0, s[16:17]
	s_mov_b32 m0, s66
	s_nop 0
	global_load_lds_dwordx4 v[224:225], off
	s_waitcnt vmcnt(8)
	s_waitcnt lgkmcnt(0)
	s_barrier
	s_setprio 1
	s_waitcnt lgkmcnt(0)
	v_mfma_f32_16x16x32_bf16 v[60:63], v[150:153], v[182:185], v[60:63]
	v_mfma_f32_16x16x32_bf16 v[60:63], v[154:157], v[192:195], v[60:63]
	v_mfma_f32_16x16x32_bf16 v[56:59], v[162:165], v[192:195], v[56:59]
	v_mfma_f32_16x16x32_bf16 v[56:59], v[158:161], v[182:185], v[56:59]
	v_mfma_f32_16x16x32_bf16 v[44:47], v[166:169], v[182:185], v[44:47]
	v_mfma_f32_16x16x32_bf16 v[44:47], v[170:173], v[192:195], v[44:47]
	v_mfma_f32_16x16x32_bf16 v[36:39], v[178:181], v[192:195], v[36:39]
	v_mfma_f32_16x16x32_bf16 v[36:39], v[174:177], v[182:185], v[36:39]
	v_mfma_f32_16x16x32_bf16 v[20:23], v[174:177], v[196:199], v[20:23]
	v_mfma_f32_16x16x32_bf16 v[20:23], v[178:181], v[200:203], v[20:23]
	v_mfma_f32_16x16x32_bf16 v[28:31], v[170:173], v[200:203], v[28:31]
	v_mfma_f32_16x16x32_bf16 v[28:31], v[166:169], v[196:199], v[28:31]
	v_mfma_f32_16x16x32_bf16 v[48:51], v[158:161], v[196:199], v[48:51]
	v_mfma_f32_16x16x32_bf16 v[48:51], v[162:165], v[200:203], v[48:51]
	v_mfma_f32_16x16x32_bf16 v[52:55], v[154:157], v[200:203], v[52:55]
	v_mfma_f32_16x16x32_bf16 v[52:55], v[150:153], v[196:199], v[52:55]
	s_setprio 0
	s_setprio 1
	v_mfma_f32_16x16x32_bf16 v[40:43], v[150:153], v[208:211], v[40:43]
	v_mfma_f32_16x16x32_bf16 v[40:43], v[154:157], v[212:215], v[40:43]
	v_mfma_f32_16x16x32_bf16 v[32:35], v[162:165], v[212:215], v[32:35]
	v_mfma_f32_16x16x32_bf16 v[32:35], v[158:161], v[208:211], v[32:35]
	v_mfma_f32_16x16x32_bf16 v[12:15], v[166:169], v[208:211], v[12:15]
	v_mfma_f32_16x16x32_bf16 v[12:15], v[170:173], v[212:215], v[12:15]
	v_mfma_f32_16x16x32_bf16 v[8:11], v[178:181], v[212:215], v[8:11]
	v_mfma_f32_16x16x32_bf16 v[8:11], v[174:177], v[208:211], v[8:11]
	v_mfma_f32_16x16x32_bf16 v[0:3], v[174:177], v[216:219], v[0:3]
	v_mfma_f32_16x16x32_bf16 v[0:3], v[178:181], v[220:223], v[0:3]
	v_mfma_f32_16x16x32_bf16 v[4:7], v[170:173], v[220:223], v[4:7]
	v_mfma_f32_16x16x32_bf16 v[4:7], v[166:169], v[216:219], v[4:7]
	v_mfma_f32_16x16x32_bf16 v[16:19], v[158:161], v[216:219], v[16:19]
	v_mfma_f32_16x16x32_bf16 v[16:19], v[162:165], v[220:223], v[16:19]
	v_mfma_f32_16x16x32_bf16 v[24:27], v[154:157], v[220:223], v[24:27]
	v_mfma_f32_16x16x32_bf16 v[24:27], v[150:153], v[216:219], v[24:27]
	s_setprio 0
	s_barrier
	s_add_u32 s1, s1, 0x100
	s_addc_u32 s77, s77, 0
	s_cmp_ge_i32 s84, s64
	s_mov_b64 s[4:5], s[12:13]
	s_mov_b32 s52, s84
	s_cbranch_scc0 .LBB0_1244
	v_pk_mul_f32 v[170:171], v[126:127], 0.5 op_sel_hi:[1,0]
	v_pk_mul_f32 v[172:173], v[124:125], 0.5 op_sel_hi:[1,0]
	v_pk_mul_f32 v[174:175], v[122:123], 0.5 op_sel_hi:[1,0]
	v_pk_mul_f32 v[176:177], v[120:121], 0.5 op_sel_hi:[1,0]
	v_pk_mul_f32 v[178:179], v[110:111], 0.5 op_sel_hi:[1,0]
	v_pk_mul_f32 v[180:181], v[108:109], 0.5 op_sel_hi:[1,0]
	v_pk_mul_f32 v[182:183], v[102:103], 0.5 op_sel_hi:[1,0]
	v_pk_mul_f32 v[184:185], v[100:101], 0.5 op_sel_hi:[1,0]
	v_pk_mul_f32 v[160:161], v[118:119], 0.5 op_sel_hi:[1,0]
	v_pk_mul_f32 v[158:159], v[116:117], 0.5 op_sel_hi:[1,0]
	v_pk_mul_f32 v[156:157], v[114:115], 0.5 op_sel_hi:[1,0]
	v_pk_mul_f32 v[154:155], v[112:113], 0.5 op_sel_hi:[1,0]
	v_pk_mul_f32 v[168:169], v[94:95], 0.5 op_sel_hi:[1,0]
	v_pk_mul_f32 v[166:167], v[92:93], 0.5 op_sel_hi:[1,0]
	v_pk_mul_f32 v[164:165], v[86:87], 0.5 op_sel_hi:[1,0]
	v_pk_mul_f32 v[162:163], v[84:85], 0.5 op_sel_hi:[1,0]
	v_pk_mul_f32 v[116:117], v[106:107], 0.5 op_sel_hi:[1,0]
	v_pk_mul_f32 v[118:119], v[104:105], 0.5 op_sel_hi:[1,0]
	v_pk_mul_f32 v[120:121], v[98:99], 0.5 op_sel_hi:[1,0]
	v_pk_mul_f32 v[122:123], v[96:97], 0.5 op_sel_hi:[1,0]
	v_pk_mul_f32 v[124:125], v[78:79], 0.5 op_sel_hi:[1,0]
	v_pk_mul_f32 v[126:127], v[76:77], 0.5 op_sel_hi:[1,0]
	v_pk_mul_f32 v[150:151], v[74:75], 0.5 op_sel_hi:[1,0]
	v_pk_mul_f32 v[152:153], v[72:73], 0.5 op_sel_hi:[1,0]
	v_pk_mul_f32 v[104:105], v[90:91], 0.5 op_sel_hi:[1,0]
	v_pk_mul_f32 v[102:103], v[88:89], 0.5 op_sel_hi:[1,0]
	v_pk_mul_f32 v[100:101], v[82:83], 0.5 op_sel_hi:[1,0]
	v_pk_mul_f32 v[98:99], v[80:81], 0.5 op_sel_hi:[1,0]
	v_pk_mul_f32 v[112:113], v[70:71], 0.5 op_sel_hi:[1,0]
	v_pk_mul_f32 v[110:111], v[68:69], 0.5 op_sel_hi:[1,0]
	v_pk_mul_f32 v[108:109], v[66:67], 0.5 op_sel_hi:[1,0]
	v_pk_mul_f32 v[106:107], v[64:65], 0.5 op_sel_hi:[1,0]
	v_pk_mul_f32 v[80:81], v[62:63], 0.5 op_sel_hi:[1,0]
	v_pk_mul_f32 v[82:83], v[60:61], 0.5 op_sel_hi:[1,0]
	v_pk_mul_f32 v[84:85], v[58:59], 0.5 op_sel_hi:[1,0]
	v_pk_mul_f32 v[86:87], v[56:57], 0.5 op_sel_hi:[1,0]
	v_pk_mul_f32 v[88:89], v[46:47], 0.5 op_sel_hi:[1,0]
	v_pk_mul_f32 v[90:91], v[44:45], 0.5 op_sel_hi:[1,0]
	v_pk_mul_f32 v[92:93], v[38:39], 0.5 op_sel_hi:[1,0]
	v_pk_mul_f32 v[94:95], v[36:37], 0.5 op_sel_hi:[1,0]
	v_pk_mul_f32 v[70:71], v[54:55], 0.5 op_sel_hi:[1,0]
	v_pk_mul_f32 v[68:69], v[52:53], 0.5 op_sel_hi:[1,0]
	v_pk_mul_f32 v[66:67], v[50:51], 0.5 op_sel_hi:[1,0]
	v_pk_mul_f32 v[64:65], v[48:49], 0.5 op_sel_hi:[1,0]
	v_pk_mul_f32 v[78:79], v[30:31], 0.5 op_sel_hi:[1,0]
	v_pk_mul_f32 v[76:77], v[28:29], 0.5 op_sel_hi:[1,0]
	v_pk_mul_f32 v[74:75], v[22:23], 0.5 op_sel_hi:[1,0]
	v_pk_mul_f32 v[72:73], v[20:21], 0.5 op_sel_hi:[1,0]
	v_pk_mul_f32 v[54:55], v[42:43], 0.5 op_sel_hi:[1,0]
	v_pk_mul_f32 v[52:53], v[40:41], 0.5 op_sel_hi:[1,0]
	v_pk_mul_f32 v[50:51], v[34:35], 0.5 op_sel_hi:[1,0]
	v_pk_mul_f32 v[48:49], v[32:33], 0.5 op_sel_hi:[1,0]
	v_pk_mul_f32 v[62:63], v[14:15], 0.5 op_sel_hi:[1,0]
	v_pk_mul_f32 v[60:61], v[12:13], 0.5 op_sel_hi:[1,0]
	v_pk_mul_f32 v[58:59], v[10:11], 0.5 op_sel_hi:[1,0]
	v_pk_mul_f32 v[56:57], v[8:9], 0.5 op_sel_hi:[1,0]
	v_pk_mul_f32 v[38:39], v[26:27], 0.5 op_sel_hi:[1,0]
	v_pk_mul_f32 v[36:37], v[24:25], 0.5 op_sel_hi:[1,0]
	v_pk_mul_f32 v[34:35], v[18:19], 0.5 op_sel_hi:[1,0]
	v_pk_mul_f32 v[32:33], v[16:17], 0.5 op_sel_hi:[1,0]
	v_pk_mul_f32 v[46:47], v[6:7], 0.5 op_sel_hi:[1,0]
	v_pk_mul_f32 v[44:45], v[4:5], 0.5 op_sel_hi:[1,0]
	v_pk_mul_f32 v[42:43], v[2:3], 0.5 op_sel_hi:[1,0]
	v_pk_mul_f32 v[40:41], v[0:1], 0.5 op_sel_hi:[1,0]

; #define PG8_STAGE(bufoff, gbase, voff) do { _Pragma("unroll") for (int _i = 0; _i < 2; ++_i) \
;         __builtin_amdgcn_global_load_lds((const unsigned*)((const char*)(gbase) + (voff)[_i]), (LAS unsigned*)(lds + (bufoff) + ldsw + _i * 8192), 16, 0, 0); } while (0)
; #define PG8_LDA(dst, b, h) do { _Pragma("unroll") for (int m = 0; m < 4; ++m) _Pragma("unroll") for (int k = 0; k < 2; ++k) dst[m][k] = *(const LAS bf16x8*)(lds + PG8_SA(b, h) + aoff + m * 2048 + k * 1024); } while (0)
; #define PG8_LDB(dst, b, h) do { _Pragma("unroll") for (int n = 0; n < 2; ++n) _Pragma("unroll") for (int k = 0; k < 2; ++k) dst[n][k] = *(const LAS bf16x8*)(lds + PG8_SB(b, h) + boff + n * 2048 + k * 1024); } while (0)
; #define PG8_MMA(ai, bj, At, Bt) do { __builtin_amdgcn_s_setprio(1); _Pragma("unroll") for (int m = 0; m < 4; ++m) _Pragma("unroll") for (int n = 0; n < 2; ++n) _Pragma("unroll") for (int k = 0; k < 2; ++k) \
;         acc[ai][bj][m][n] = __builtin_amdgcn_mfma_f32_16x16x32_bf16(Bt[n][k], At[m][k], acc[ai][bj][m][n], 0, 0, 0); __builtin_amdgcn_s_setprio(0); } while (0)
; #define PG8_WAIT_V(n) asm volatile("s_waitcnt vmcnt(" #n ")" ::: "memory")
; #define PG8_WAIT_L(n) asm volatile("s_waitcnt lgkmcnt(" #n ")" ::: "memory")
; #define PG8_BAR __builtin_amdgcn_s_barrier()
; #define PG8_SCHED __builtin_amdgcn_sched_barrier(0)
; template <class Epi>
; __device__ __forceinline__ void gemm_phase(LAS unsigned char* lds, const Gemm g, const StaticOrder& S, const Epi& E) {
;     ...
;             const char* a2 = last ? nA : cA + (size_t)(t + 2) * kstep; const char* b2 = last ? nB : cB + (size_t)(t + 2) * kstep;
;             const char* a3 = a2 + kstep; const char* b3 = b2 + kstep;
;             PG8_LDB(B0, 0, 0); PG8_LDB(B1, 0, 1); PG8_SCHED; PG8_LDA(At, 0, 0); PG8_STAGE(PG8_SA(1, 1), a1 + hstepA, voffA);
;             PG8_WAIT_V(8); PG8_WAIT_L(0); PG8_BAR; PG8_MMA(0, 0, At, B0); PG8_MMA(0, 1, At, B1); PG8_BAR; PG8_SCHED;
;             PG8_LDA(At, 0, 1); PG8_STAGE(PG8_SB(0, 0), b2, voffB); PG8_STAGE(PG8_SB(0, 1), b2 + hstepB, voffB); PG8_STAGE(PG8_SA(0, 0), a2, voffA);
.LBB0_1338:
	ds_read_b128 v[128:131], v173
	ds_read_b128 v[132:135], v173 offset:1024
	ds_read_b128 v[136:139], v173 offset:2048
	ds_read_b128 v[140:143], v173 offset:3072
	ds_read_b128 v[144:147], v175
	ds_read_b128 v[148:151], v175 offset:1024
	ds_read_b128 v[176:179], v175 offset:2048
	ds_read_b128 v[184:187], v175 offset:3072
	s_add_i32 s20, s10, 2
	s_add_u32 s11, s8, 0xfff80080
	s_addc_u32 s12, s9, -1
	s_cmp_eq_u32 s56, s10
	s_cselect_b32 s10, s17, s18
	s_cselect_b32 s13, s1, s12
	s_cselect_b32 s12, s15, s11
	s_cselect_b32 s11, s16, s19
	v_lshl_add_u64 v[224:225], s[8:9], 0, v[164:165]
	s_add_i32 m0, s47, 0xc000
	ds_read_b128 v[188:191], v181
	ds_read_b128 v[192:195], v181 offset:1024
	ds_read_b128 v[196:199], v181 offset:2048
	ds_read_b128 v[200:203], v181 offset:3072
	ds_read_b128 v[208:211], v181 offset:4096
	ds_read_b128 v[212:215], v181 offset:5120
	ds_read_b128 v[216:219], v181 offset:6144
	ds_read_b128 v[220:223], v181 offset:7168
	global_load_lds_dwordx4 v[224:225], off
	v_lshl_add_u64 v[224:225], s[8:9], 0, v[166:167]
	s_add_i32 m0, s47, 0xe000
	s_nop 0
	global_load_lds_dwordx4 v[224:225], off
	s_waitcnt vmcnt(8)
	s_waitcnt lgkmcnt(0)
	s_barrier
	s_setprio 1
	s_waitcnt lgkmcnt(0)
	v_mfma_f32_16x16x32_bf16 v[124:127], v[128:131], v[188:191], v[124:127]
	v_mfma_f32_16x16x32_bf16 v[124:127], v[132:135], v[192:195], v[124:127]
	v_mfma_f32_16x16x32_bf16 v[120:123], v[140:143], v[192:195], v[120:123]
	v_mfma_f32_16x16x32_bf16 v[120:123], v[136:139], v[188:191], v[120:123]
	v_mfma_f32_16x16x32_bf16 v[116:119], v[144:147], v[188:191], v[116:119]
	v_mfma_f32_16x16x32_bf16 v[116:119], v[148:151], v[192:195], v[116:119]
	v_mfma_f32_16x16x32_bf16 v[112:115], v[184:187], v[192:195], v[112:115]
	v_mfma_f32_16x16x32_bf16 v[112:115], v[176:179], v[188:191], v[112:115]
	v_mfma_f32_16x16x32_bf16 v[96:99], v[176:179], v[196:199], v[96:99]
	v_mfma_f32_16x16x32_bf16 v[96:99], v[184:187], v[200:203], v[96:99]
	v_mfma_f32_16x16x32_bf16 v[100:103], v[148:151], v[200:203], v[100:103]
	v_mfma_f32_16x16x32_bf16 v[100:103], v[144:147], v[196:199], v[100:103]
	v_mfma_f32_16x16x32_bf16 v[104:107], v[136:139], v[196:199], v[104:107]
	v_mfma_f32_16x16x32_bf16 v[104:107], v[140:143], v[200:203], v[104:107]
	v_mfma_f32_16x16x32_bf16 v[108:111], v[132:135], v[200:203], v[108:111]
	v_mfma_f32_16x16x32_bf16 v[108:111], v[128:131], v[196:199], v[108:111]
	s_setprio 0
	s_setprio 1
	v_mfma_f32_16x16x32_bf16 v[92:95], v[128:131], v[208:211], v[92:95]
	v_mfma_f32_16x16x32_bf16 v[92:95], v[132:135], v[212:215], v[92:95]
	v_mfma_f32_16x16x32_bf16 v[88:91], v[140:143], v[212:215], v[88:91]
	v_mfma_f32_16x16x32_bf16 v[88:91], v[136:139], v[208:211], v[88:91]
	v_mfma_f32_16x16x32_bf16 v[84:87], v[144:147], v[208:211], v[84:87]
	v_mfma_f32_16x16x32_bf16 v[84:87], v[148:151], v[212:215], v[84:87]
	v_mfma_f32_16x16x32_bf16 v[80:83], v[184:187], v[212:215], v[80:83]
	v_mfma_f32_16x16x32_bf16 v[80:83], v[176:179], v[208:211], v[80:83]
	v_mfma_f32_16x16x32_bf16 v[64:67], v[176:179], v[216:219], v[64:67]
	v_mfma_f32_16x16x32_bf16 v[64:67], v[184:187], v[220:223], v[64:67]
	v_mfma_f32_16x16x32_bf16 v[68:71], v[148:151], v[220:223], v[68:71]
	v_mfma_f32_16x16x32_bf16 v[68:71], v[144:147], v[216:219], v[68:71]
	v_mfma_f32_16x16x32_bf16 v[72:75], v[136:139], v[216:219], v[72:75]
	v_mfma_f32_16x16x32_bf16 v[72:75], v[140:143], v[220:223], v[72:75]
	v_mfma_f32_16x16x32_bf16 v[76:79], v[132:135], v[220:223], v[76:79]
	v_mfma_f32_16x16x32_bf16 v[76:79], v[128:131], v[216:219], v[76:79]
	s_setprio 0
	s_barrier
	s_add_i32 s21, s59, s46
	v_lshl_add_u64 v[224:225], s[10:11], 0, v[154:155]
	s_mov_b32 m0, s21
	ds_read_b128 v[188:191], v181 offset:16384
	ds_read_b128 v[192:195], v181 offset:17408
	ds_read_b128 v[196:199], v181 offset:18432
	ds_read_b128 v[200:203], v181 offset:19456
	ds_read_b128 v[208:211], v181 offset:20480
	ds_read_b128 v[212:215], v181 offset:21504
	ds_read_b128 v[216:219], v181 offset:22528
	ds_read_b128 v[220:223], v181 offset:23552
	global_load_lds_dwordx4 v[224:225], off
	s_add_i32 m0, s21, 0x2000
	s_add_u32 s68, s10, 0x80000
	v_lshl_add_u64 v[226:227], s[10:11], 0, v[158:159]
	s_addc_u32 s69, s11, 0
	s_add_i32 s21, s60, s46
	global_load_lds_dwordx4 v[226:227], off
	v_lshl_add_u64 v[230:231], s[68:69], 0, v[154:155]
	s_mov_b32 m0, s21
	v_lshl_add_u64 v[232:233], s[12:13], 0, v[156:157]
	global_load_lds_dwordx4 v[230:231], off
	v_lshl_add_u64 v[230:231], s[68:69], 0, v[158:159]
	s_add_i32 m0, s21, 0x2000
	s_nop 0
	global_load_lds_dwordx4 v[230:231], off
	v_lshl_add_u64 v[230:231], s[12:13], 0, v[152:153]
	s_mov_b32 m0, s47
	s_nop 0
	global_load_lds_dwordx4 v[230:231], off
	s_mov_b32 m0, s48
	s_nop 0
	global_load_lds_dwordx4 v[232:233], off
	s_waitcnt vmcnt(8)
	s_waitcnt lgkmcnt(0)
	s_barrier
; #define PG8_STAGE(bufoff, gbase, voff) do { _Pragma("unroll") for (int _i = 0; _i < 2; ++_i) \
;         __builtin_amdgcn_global_load_lds((const unsigned*)((const char*)(gbase) + (voff)[_i]), (LAS unsigned*)(lds + (bufoff) + ldsw + _i * 8192), 16, 0, 0); } while (0)
; #define PG8_LDA(dst, b, h) do { _Pragma("unroll") for (int m = 0; m < 4; ++m) _Pragma("unroll") for (int k = 0; k < 2; ++k) dst[m][k] = *(const LAS bf16x8*)(lds + PG8_SA(b, h) + aoff + m * 2048 + k * 1024); } while (0)
; #define PG8_LDB(dst, b, h) do { _Pragma("unroll") for (int n = 0; n < 2; ++n) _Pragma("unroll") for (int k = 0; k < 2; ++k) dst[n][k] = *(const LAS bf16x8*)(lds + PG8_SB(b, h) + boff + n * 2048 + k * 1024); } while (0)
; #define PG8_MMA(ai, bj, At, Bt) do { __builtin_amdgcn_s_setprio(1); _Pragma("unroll") for (int m = 0; m < 4; ++m) _Pragma("unroll") for (int n = 0; n < 2; ++n) _Pragma("unroll") for (int k = 0; k < 2; ++k) \
;         acc[ai][bj][m][n] = __builtin_amdgcn_mfma_f32_16x16x32_bf16(Bt[n][k], At[m][k], acc[ai][bj][m][n], 0, 0, 0); __builtin_amdgcn_s_setprio(0); } while (0)
; #define PG8_WAIT_V(n) asm volatile("s_waitcnt vmcnt(" #n ")" ::: "memory")
; #define PG8_WAIT_L(n) asm volatile("s_waitcnt lgkmcnt(" #n ")" ::: "memory")
; #define PG8_BAR __builtin_amdgcn_s_barrier()
; #define PG8_SCHED __builtin_amdgcn_sched_barrier(0)
; template <class Epi>
; __device__ __forceinline__ void gemm_phase(LAS unsigned char* lds, const Gemm g, const StaticOrder& S, const Epi& E) {
;     ...
;             PG8_WAIT_V(8); PG8_WAIT_L(0); PG8_BAR; PG8_MMA(1, 0, At, B0); PG8_MMA(1, 1, At, B1); PG8_BAR; PG8_SCHED;
;             PG8_LDB(B0, 1, 0); PG8_LDB(B1, 1, 1); PG8_SCHED; PG8_LDA(At, 1, 0); PG8_STAGE(PG8_SA(0, 1), a2 + hstepA, voffA);
;             PG8_WAIT_V(8); PG8_WAIT_L(0); PG8_BAR; PG8_MMA(0, 0, At, B0); PG8_MMA(0, 1, At, B1); PG8_BAR; PG8_SCHED;
;             PG8_LDA(At, 1, 1); PG8_STAGE(PG8_SB(1, 0), b3, voffB); PG8_STAGE(PG8_SB(1, 1), b3 + hstepB, voffB); PG8_STAGE(PG8_SA(1, 0), a3, voffA);
	s_setprio 1
	s_waitcnt lgkmcnt(0)
	v_mfma_f32_16x16x32_bf16 v[60:63], v[128:131], v[188:191], v[60:63]
	v_mfma_f32_16x16x32_bf16 v[60:63], v[132:135], v[192:195], v[60:63]
	v_mfma_f32_16x16x32_bf16 v[56:59], v[140:143], v[192:195], v[56:59]
	v_mfma_f32_16x16x32_bf16 v[56:59], v[136:139], v[188:191], v[56:59]
	v_mfma_f32_16x16x32_bf16 v[52:55], v[144:147], v[188:191], v[52:55]
	v_mfma_f32_16x16x32_bf16 v[52:55], v[148:151], v[192:195], v[52:55]
	v_mfma_f32_16x16x32_bf16 v[48:51], v[184:187], v[192:195], v[48:51]
	v_mfma_f32_16x16x32_bf16 v[48:51], v[176:179], v[188:191], v[48:51]
	v_mfma_f32_16x16x32_bf16 v[32:35], v[176:179], v[196:199], v[32:35]
	v_mfma_f32_16x16x32_bf16 v[32:35], v[184:187], v[200:203], v[32:35]
	v_mfma_f32_16x16x32_bf16 v[36:39], v[148:151], v[200:203], v[36:39]
	v_mfma_f32_16x16x32_bf16 v[36:39], v[144:147], v[196:199], v[36:39]
	v_mfma_f32_16x16x32_bf16 v[40:43], v[136:139], v[196:199], v[40:43]
	v_mfma_f32_16x16x32_bf16 v[40:43], v[140:143], v[200:203], v[40:43]
	v_mfma_f32_16x16x32_bf16 v[44:47], v[132:135], v[200:203], v[44:47]
	v_mfma_f32_16x16x32_bf16 v[44:47], v[128:131], v[196:199], v[44:47]
	s_setprio 0
	s_setprio 1
	v_mfma_f32_16x16x32_bf16 v[28:31], v[128:131], v[208:211], v[28:31]
	v_mfma_f32_16x16x32_bf16 v[28:31], v[132:135], v[212:215], v[28:31]
	v_mfma_f32_16x16x32_bf16 v[24:27], v[140:143], v[212:215], v[24:27]
	v_mfma_f32_16x16x32_bf16 v[24:27], v[136:139], v[208:211], v[24:27]
	v_mfma_f32_16x16x32_bf16 v[20:23], v[144:147], v[208:211], v[20:23]
	v_mfma_f32_16x16x32_bf16 v[20:23], v[148:151], v[212:215], v[20:23]
	v_mfma_f32_16x16x32_bf16 v[16:19], v[184:187], v[212:215], v[16:19]
	v_mfma_f32_16x16x32_bf16 v[16:19], v[176:179], v[208:211], v[16:19]
	v_mfma_f32_16x16x32_bf16 v[0:3], v[176:179], v[216:219], v[0:3]
	v_mfma_f32_16x16x32_bf16 v[0:3], v[184:187], v[220:223], v[0:3]
	v_mfma_f32_16x16x32_bf16 v[4:7], v[148:151], v[220:223], v[4:7]
	v_mfma_f32_16x16x32_bf16 v[4:7], v[144:147], v[216:219], v[4:7]
	v_mfma_f32_16x16x32_bf16 v[8:11], v[136:139], v[216:219], v[8:11]
	v_mfma_f32_16x16x32_bf16 v[8:11], v[140:143], v[220:223], v[8:11]
	v_mfma_f32_16x16x32_bf16 v[12:15], v[132:135], v[220:223], v[12:15]
	v_mfma_f32_16x16x32_bf16 v[12:15], v[128:131], v[216:219], v[12:15]
	s_setprio 0
	s_barrier
	s_add_i32 s21, 0, 0x18000
	s_add_i32 s33, 0, 0x1c000
	v_add_u32_e32 v140, s21, v163
	v_add_u32_e32 v172, s33, v163
	ds_read_b128 v[128:131], v140
	ds_read_b128 v[132:135], v140 offset:1024
	ds_read_b128 v[136:139], v140 offset:2048
	ds_read_b128 v[140:143], v140 offset:3072
	ds_read_b128 v[144:147], v172
	ds_read_b128 v[148:151], v172 offset:1024
	ds_read_b128 v[176:179], v172 offset:2048
	ds_read_b128 v[184:187], v172 offset:3072
	s_add_u32 s12, s12, 0x80000
	s_addc_u32 s13, s13, 0
	s_mov_b32 m0, s49
	v_lshl_add_u64 v[234:235], s[12:13], 0, v[152:153]
	ds_read_b128 v[188:191], v181 offset:32768
	ds_read_b128 v[192:195], v181 offset:33792
	ds_read_b128 v[196:199], v181 offset:34816
	ds_read_b128 v[200:203], v181 offset:35840
	ds_read_b128 v[208:211], v181 offset:36864
	ds_read_b128 v[212:215], v181 offset:37888
	ds_read_b128 v[216:219], v181 offset:38912
	ds_read_b128 v[220:223], v181 offset:39936
	global_load_lds_dwordx4 v[234:235], off
	v_lshl_add_u64 v[234:235], s[12:13], 0, v[156:157]
	s_mov_b32 m0, s50
	s_nop 0
	global_load_lds_dwordx4 v[234:235], off
	s_waitcnt vmcnt(8)
	s_waitcnt lgkmcnt(0)
	s_barrier
	s_setprio 1
	s_waitcnt lgkmcnt(0)
	v_mfma_f32_16x16x32_bf16 v[124:127], v[128:131], v[188:191], v[124:127]
	v_mfma_f32_16x16x32_bf16 v[124:127], v[132:135], v[192:195], v[124:127]
	v_mfma_f32_16x16x32_bf16 v[120:123], v[140:143], v[192:195], v[120:123]
	v_mfma_f32_16x16x32_bf16 v[120:123], v[136:139], v[188:191], v[120:123]
	v_mfma_f32_16x16x32_bf16 v[116:119], v[144:147], v[188:191], v[116:119]
	v_mfma_f32_16x16x32_bf16 v[116:119], v[148:151], v[192:195], v[116:119]
	v_mfma_f32_16x16x32_bf16 v[112:115], v[184:187], v[192:195], v[112:115]
	v_mfma_f32_16x16x32_bf16 v[112:115], v[176:179], v[188:191], v[112:115]
	v_mfma_f32_16x16x32_bf16 v[96:99], v[176:179], v[196:199], v[96:99]
	v_mfma_f32_16x16x32_bf16 v[96:99], v[184:187], v[200:203], v[96:99]
	v_mfma_f32_16x16x32_bf16 v[100:103], v[148:151], v[200:203], v[100:103]
	v_mfma_f32_16x16x32_bf16 v[100:103], v[144:147], v[196:199], v[100:103]
	v_mfma_f32_16x16x32_bf16 v[104:107], v[136:139], v[196:199], v[104:107]
	v_mfma_f32_16x16x32_bf16 v[104:107], v[140:143], v[200:203], v[104:107]
	v_mfma_f32_16x16x32_bf16 v[108:111], v[132:135], v[200:203], v[108:111]
	v_mfma_f32_16x16x32_bf16 v[108:111], v[128:131], v[196:199], v[108:111]
	s_setprio 0
	s_setprio 1
	v_mfma_f32_16x16x32_bf16 v[92:95], v[128:131], v[208:211], v[92:95]
	v_mfma_f32_16x16x32_bf16 v[92:95], v[132:135], v[212:215], v[92:95]
	v_mfma_f32_16x16x32_bf16 v[88:91], v[140:143], v[212:215], v[88:91]
	v_mfma_f32_16x16x32_bf16 v[88:91], v[136:139], v[208:211], v[88:91]
	v_mfma_f32_16x16x32_bf16 v[84:87], v[144:147], v[208:211], v[84:87]
	v_mfma_f32_16x16x32_bf16 v[84:87], v[148:151], v[212:215], v[84:87]
	v_mfma_f32_16x16x32_bf16 v[80:83], v[184:187], v[212:215], v[80:83]
	v_mfma_f32_16x16x32_bf16 v[80:83], v[176:179], v[208:211], v[80:83]
	v_mfma_f32_16x16x32_bf16 v[64:67], v[176:179], v[216:219], v[64:67]
	v_mfma_f32_16x16x32_bf16 v[64:67], v[184:187], v[220:223], v[64:67]
	v_mfma_f32_16x16x32_bf16 v[68:71], v[148:151], v[220:223], v[68:71]
	v_mfma_f32_16x16x32_bf16 v[68:71], v[144:147], v[216:219], v[68:71]
	v_mfma_f32_16x16x32_bf16 v[72:75], v[136:139], v[216:219], v[72:75]
	v_mfma_f32_16x16x32_bf16 v[72:75], v[140:143], v[220:223], v[72:75]
	v_mfma_f32_16x16x32_bf16 v[76:79], v[132:135], v[220:223], v[76:79]
	v_mfma_f32_16x16x32_bf16 v[76:79], v[128:131], v[216:219], v[76:79]
	s_setprio 0
	s_barrier
; #define PG8_STAGE(bufoff, gbase, voff) do { _Pragma("unroll") for (int _i = 0; _i < 2; ++_i) \
;         __builtin_amdgcn_global_load_lds((const unsigned*)((const char*)(gbase) + (voff)[_i]), (LAS unsigned*)(lds + (bufoff) + ldsw + _i * 8192), 16, 0, 0); } while (0)
; #define PG8_LDA(dst, b, h) do { _Pragma("unroll") for (int m = 0; m < 4; ++m) _Pragma("unroll") for (int k = 0; k < 2; ++k) dst[m][k] = *(const LAS bf16x8*)(lds + PG8_SA(b, h) + aoff + m * 2048 + k * 1024); } while (0)
; #define PG8_MMA(ai, bj, At, Bt) do { __builtin_amdgcn_s_setprio(1); _Pragma("unroll") for (int m = 0; m < 4; ++m) _Pragma("unroll") for (int n = 0; n < 2; ++n) _Pragma("unroll") for (int k = 0; k < 2; ++k) \
;         acc[ai][bj][m][n] = __builtin_amdgcn_mfma_f32_16x16x32_bf16(Bt[n][k], At[m][k], acc[ai][bj][m][n], 0, 0, 0); __builtin_amdgcn_s_setprio(0); } while (0)
; #define PG8_WAIT_V(n) asm volatile("s_waitcnt vmcnt(" #n ")" ::: "memory")
; #define PG8_WAIT_L(n) asm volatile("s_waitcnt lgkmcnt(" #n ")" ::: "memory")
; #define PG8_BAR __builtin_amdgcn_s_barrier()
; #define PG8_SCHED __builtin_amdgcn_sched_barrier(0)
; template <class Epi>
; __device__ __forceinline__ void gemm_phase(LAS unsigned char* lds, const Gemm g, const StaticOrder& S, const Epi& E) {
;     ...
;             PG8_LDA(At, 1, 1); PG8_STAGE(PG8_SB(1, 0), b3, voffB); PG8_STAGE(PG8_SB(1, 1), b3 + hstepB, voffB); PG8_STAGE(PG8_SA(1, 0), a3, voffA);
;             PG8_WAIT_V(8); PG8_WAIT_L(0); PG8_BAR; PG8_MMA(1, 0, At, B0); PG8_MMA(1, 1, At, B1); PG8_BAR; PG8_SCHED;
;         }
	s_add_i32 s12, s21, s46
	v_lshl_add_u64 v[224:225], v[224:225], 0, s[28:29]
	s_mov_b32 m0, s12
	ds_read_b128 v[188:191], v181 offset:49152
	ds_read_b128 v[192:195], v181 offset:50176
	ds_read_b128 v[196:199], v181 offset:51200
	ds_read_b128 v[200:203], v181 offset:52224
	ds_read_b128 v[208:211], v181 offset:53248
	ds_read_b128 v[212:215], v181 offset:54272
	ds_read_b128 v[216:219], v181 offset:55296
	ds_read_b128 v[220:223], v181 offset:56320
	global_load_lds_dwordx4 v[224:225], off
	s_add_i32 m0, s12, 0x2000
	s_add_u32 s10, s10, 0x80080
	v_lshl_add_u64 v[224:225], v[226:227], 0, s[28:29]
	s_addc_u32 s11, s11, 0
	s_add_i32 s12, s33, s46
	global_load_lds_dwordx4 v[224:225], off
	v_lshl_add_u64 v[224:225], s[10:11], 0, v[154:155]
	s_mov_b32 m0, s12
	s_nop 0
	global_load_lds_dwordx4 v[224:225], off
	v_lshl_add_u64 v[224:225], s[10:11], 0, v[158:159]
	s_add_i32 m0, s12, 0x2000
	s_nop 0
	global_load_lds_dwordx4 v[224:225], off
	v_lshl_add_u64 v[224:225], v[230:231], 0, s[28:29]
	s_mov_b32 m0, s54
	s_nop 0
	global_load_lds_dwordx4 v[224:225], off
	v_lshl_add_u64 v[224:225], v[232:233], 0, s[28:29]
	s_mov_b32 m0, s55
	s_nop 0
	global_load_lds_dwordx4 v[224:225], off
	s_waitcnt vmcnt(8)
	s_waitcnt lgkmcnt(0)
	s_barrier
	s_setprio 1
	s_waitcnt lgkmcnt(0)
	v_mfma_f32_16x16x32_bf16 v[60:63], v[128:131], v[188:191], v[60:63]
	v_mfma_f32_16x16x32_bf16 v[60:63], v[132:135], v[192:195], v[60:63]
	v_mfma_f32_16x16x32_bf16 v[56:59], v[140:143], v[192:195], v[56:59]
	v_mfma_f32_16x16x32_bf16 v[56:59], v[136:139], v[188:191], v[56:59]
	v_mfma_f32_16x16x32_bf16 v[52:55], v[144:147], v[188:191], v[52:55]
	v_mfma_f32_16x16x32_bf16 v[52:55], v[148:151], v[192:195], v[52:55]
	v_mfma_f32_16x16x32_bf16 v[48:51], v[184:187], v[192:195], v[48:51]
	v_mfma_f32_16x16x32_bf16 v[48:51], v[176:179], v[188:191], v[48:51]
	v_mfma_f32_16x16x32_bf16 v[32:35], v[176:179], v[196:199], v[32:35]
	v_mfma_f32_16x16x32_bf16 v[32:35], v[184:187], v[200:203], v[32:35]
	v_mfma_f32_16x16x32_bf16 v[36:39], v[148:151], v[200:203], v[36:39]
	v_mfma_f32_16x16x32_bf16 v[36:39], v[144:147], v[196:199], v[36:39]
	v_mfma_f32_16x16x32_bf16 v[40:43], v[136:139], v[196:199], v[40:43]
	v_mfma_f32_16x16x32_bf16 v[40:43], v[140:143], v[200:203], v[40:43]
	v_mfma_f32_16x16x32_bf16 v[44:47], v[132:135], v[200:203], v[44:47]
	v_mfma_f32_16x16x32_bf16 v[44:47], v[128:131], v[196:199], v[44:47]
	s_setprio 0
	s_setprio 1
	v_mfma_f32_16x16x32_bf16 v[28:31], v[128:131], v[208:211], v[28:31]
	v_mfma_f32_16x16x32_bf16 v[28:31], v[132:135], v[212:215], v[28:31]
	v_mfma_f32_16x16x32_bf16 v[24:27], v[140:143], v[212:215], v[24:27]
	v_mfma_f32_16x16x32_bf16 v[24:27], v[136:139], v[208:211], v[24:27]
	v_mfma_f32_16x16x32_bf16 v[20:23], v[144:147], v[208:211], v[20:23]
	v_mfma_f32_16x16x32_bf16 v[20:23], v[148:151], v[212:215], v[20:23]
	v_mfma_f32_16x16x32_bf16 v[16:19], v[184:187], v[212:215], v[16:19]
	v_mfma_f32_16x16x32_bf16 v[16:19], v[176:179], v[208:211], v[16:19]
	v_mfma_f32_16x16x32_bf16 v[0:3], v[176:179], v[216:219], v[0:3]
	v_mfma_f32_16x16x32_bf16 v[0:3], v[184:187], v[220:223], v[0:3]
	v_mfma_f32_16x16x32_bf16 v[4:7], v[148:151], v[220:223], v[4:7]
	v_mfma_f32_16x16x32_bf16 v[4:7], v[144:147], v[216:219], v[4:7]
	v_mfma_f32_16x16x32_bf16 v[8:11], v[136:139], v[216:219], v[8:11]
	v_mfma_f32_16x16x32_bf16 v[8:11], v[140:143], v[220:223], v[8:11]
	v_mfma_f32_16x16x32_bf16 v[12:15], v[132:135], v[220:223], v[12:15]
	v_mfma_f32_16x16x32_bf16 v[12:15], v[128:131], v[216:219], v[12:15]
	s_setprio 0
	s_barrier
	s_add_u32 s8, s8, 0x100
	s_addc_u32 s9, s9, 0
	s_add_u32 s18, s18, 0x100
	s_addc_u32 s19, s19, 0
	s_cmp_ge_i32 s20, s53
	s_mov_b32 s10, s20
	s_cbranch_scc0 .LBB0_1338
